# kdma with per=1: one ds_read after each LDS-DMA in the load segments (DMAs issue earlier than per=2)
# baseline (speedup 1.0000x reference)
; #define PG8_STAGE(bufoff, gbase, voff) do { _Pragma("unroll") for (int _i = 0; _i < 2; ++_i) \
;         __builtin_amdgcn_global_load_lds((const unsigned*)((const char*)(gbase) + (voff)[_i]), (LAS unsigned*)(lds + (bufoff) + ldsw + _i * 8192), 16, 0, 0); } while (0)
; #define PG8_LDA(dst, b, h) do { _Pragma("unroll") for (int m = 0; m < 4; ++m) _Pragma("unroll") for (int k = 0; k < 2; ++k) dst[m][k] = *(const LAS bf16x8*)(lds + PG8_SA(b, h) + aoff + m * 2048 + k * 1024); } while (0)
; #define PG8_LDB(dst, b, h) do { _Pragma("unroll") for (int n = 0; n < 2; ++n) _Pragma("unroll") for (int k = 0; k < 2; ++k) dst[n][k] = *(const LAS bf16x8*)(lds + PG8_SB(b, h) + boff + n * 2048 + k * 1024); } while (0)
; #define PG8_WAIT_V(n) asm volatile("s_waitcnt vmcnt(" #n ")" ::: "memory")
; #define PG8_WAIT_L(n) asm volatile("s_waitcnt lgkmcnt(" #n ")" ::: "memory")
; #define PG8_BAR __builtin_amdgcn_s_barrier()
; #define PG8_SCHED __builtin_amdgcn_sched_barrier(0)
; template <class Epi>
; __device__ __forceinline__ void gemm_phase(LAS unsigned char* lds, const Gemm g, const StaticOrder& S, const Epi& E, const int tid) {
;     ...
;             const bool last = (t == ntt - 2);
;             const bool s1 = Epi::TWO && (t >= nt), s2 = Epi::TWO && (t + 2 >= nt);
;             const char* a1 = (s1 ? cA2 + (size_t)(t - nt + 1) * kstep : cA + (size_t)(t + 1) * kstep);
;             const char* a2 = last ? nA : (s2 ? cA2 + (size_t)(t + 2 - nt) * kstep : cA + (size_t)(t + 2) * kstep);
;             const char* b2 = last ? nB : (s2 ? cB2 + (size_t)(t + 2 - nt) * kstep : cB + (size_t)(t + 2) * kstep);
;             const char* a3 = a2 + kstep; const char* b3 = b2 + kstep;
;             if constexpr (Epi::TWO) { if (t == nt) E.mid(acc, cur, wr, wc, fr, fq); }
;             if constexpr (SP2) {
;             PG8_LDB(B0, 0, 0); PG8_LDB(B1, 0, 1); PG8_SCHED; PG8_LDA(At, 0, 0); PG8_STAGE(PG8_SA(1, 1), a1 + hstep, voffA);
;             PG8_WAIT_V(8); PG8_WAIT_L(0); PG8_BAR; PG8_MMA(0, 0, At, B0); PG8_MMA(0, 1, At, B1); PG8_BAR; PG8_SCHED;
;             PG8_LDA(At, 0, 1); PG8_STAGE(PG8_SB(0, 0), b2, voffB); PG8_STAGE(PG8_SB(0, 1), b2 + bhs, voffB); PG8_STAGE(PG8_SA(0, 0), a2, voffA);
;             PG8_WAIT_V(8); PG8_WAIT_L(0); PG8_BAR; PG8_MMA(1, 0, At, B0); PG8_MMA(1, 1, At, B1); PG8_BAR; PG8_SCHED;
.LBB0_126:
	s_add_u32 s30, s28, 0xffe00080
	s_addc_u32 s31, s29, -1
	s_add_i32 s52, 0, 0x10000
	s_cmpk_eq_i32 s51, 0x7c
	s_cselect_b32 s35, s17, s31
	s_cselect_b32 s34, s27, s30
	s_cselect_b32 s31, s15, s50
	s_cselect_b32 s30, s33, s49
	s_add_i32 s54, 0, 0x14000
	v_add_u32_e32 v30, s52, v193
	v_add_u32_e32 v54, s54, v193
	ds_read_b128 v[18:21], v30
	ds_read_b128 v[22:25], v30 offset:1024
	ds_read_b128 v[26:29], v30 offset:2048
	ds_read_b128 v[30:33], v30 offset:3072
	ds_read_b128 v[42:45], v54
	ds_read_b128 v[46:49], v54 offset:1024
	ds_read_b128 v[50:53], v54 offset:2048
	ds_read_b128 v[54:57], v54 offset:3072
	v_lshl_add_u64 v[172:173], s[28:29], 0, v[180:181]
	s_add_i32 m0, s37, 0xc000
	ds_read_b128 v[182:185], v199
	global_load_lds_dwordx4 v[172:173], off
	ds_read_b128 v[186:189], v199 offset:1024
	v_lshl_add_u64 v[172:173], s[28:29], 0, v[178:179]
	s_add_i32 m0, s37, 0xe000
	s_nop 0
	global_load_lds_dwordx4 v[172:173], off
	ds_read_b128 v[212:215], v199 offset:2048
	ds_read_b128 v[216:219], v199 offset:3072
	ds_read_b128 v[220:223], v199 offset:4096
	ds_read_b128 v[224:227], v199 offset:5120
	ds_read_b128 v[228:231], v199 offset:6144
	ds_read_b128 v[232:235], v199 offset:7168
	s_waitcnt vmcnt(8)
	s_waitcnt lgkmcnt(0)
	s_barrier
	s_setprio 1
	s_waitcnt lgkmcnt(0)
	v_mfma_f32_16x16x32_bf16 v[158:161], v[18:21], v[182:185], v[158:161]
	v_mfma_f32_16x16x32_bf16 v[154:157], v[26:29], v[182:185], v[154:157]
	v_mfma_f32_16x16x32_bf16 v[142:145], v[18:21], v[212:215], v[142:145]
	v_mfma_f32_16x16x32_bf16 v[138:141], v[26:29], v[212:215], v[138:141]
	v_mfma_f32_16x16x32_bf16 v[126:129], v[18:21], v[220:223], v[126:129]
	v_mfma_f32_16x16x32_bf16 v[122:125], v[26:29], v[220:223], v[122:125]
	v_mfma_f32_16x16x32_bf16 v[110:113], v[18:21], v[228:231], v[110:113]
	v_mfma_f32_16x16x32_bf16 v[106:109], v[26:29], v[228:231], v[106:109]
	v_mfma_f32_16x16x32_bf16 v[158:161], v[22:25], v[186:189], v[158:161]
	v_mfma_f32_16x16x32_bf16 v[154:157], v[30:33], v[186:189], v[154:157]
	v_mfma_f32_16x16x32_bf16 v[142:145], v[22:25], v[216:219], v[142:145]
	v_mfma_f32_16x16x32_bf16 v[138:141], v[30:33], v[216:219], v[138:141]
	v_mfma_f32_16x16x32_bf16 v[126:129], v[22:25], v[224:227], v[126:129]
	v_mfma_f32_16x16x32_bf16 v[122:125], v[30:33], v[224:227], v[122:125]
	v_mfma_f32_16x16x32_bf16 v[110:113], v[22:25], v[232:235], v[110:113]
	v_mfma_f32_16x16x32_bf16 v[106:109], v[30:33], v[232:235], v[106:109]
	s_setprio 0
	s_setprio 1
	v_mfma_f32_16x16x32_bf16 v[150:153], v[42:45], v[182:185], v[150:153]
	v_mfma_f32_16x16x32_bf16 v[146:149], v[50:53], v[182:185], v[146:149]
	v_mfma_f32_16x16x32_bf16 v[134:137], v[42:45], v[212:215], v[134:137]
	v_mfma_f32_16x16x32_bf16 v[130:133], v[50:53], v[212:215], v[130:133]
	v_mfma_f32_16x16x32_bf16 v[118:121], v[42:45], v[220:223], v[118:121]
	v_mfma_f32_16x16x32_bf16 v[114:117], v[50:53], v[220:223], v[114:117]
	v_mfma_f32_16x16x32_bf16 v[102:105], v[42:45], v[228:231], v[102:105]
	v_mfma_f32_16x16x32_bf16 v[98:101], v[50:53], v[228:231], v[98:101]
	v_mfma_f32_16x16x32_bf16 v[150:153], v[46:49], v[186:189], v[150:153]
	v_mfma_f32_16x16x32_bf16 v[146:149], v[54:57], v[186:189], v[146:149]
	v_mfma_f32_16x16x32_bf16 v[134:137], v[46:49], v[216:219], v[134:137]
	v_mfma_f32_16x16x32_bf16 v[130:133], v[54:57], v[216:219], v[130:133]
	v_mfma_f32_16x16x32_bf16 v[118:121], v[46:49], v[224:227], v[118:121]
	v_mfma_f32_16x16x32_bf16 v[114:117], v[54:57], v[224:227], v[114:117]
	v_mfma_f32_16x16x32_bf16 v[102:105], v[46:49], v[232:235], v[102:105]
	v_mfma_f32_16x16x32_bf16 v[98:101], v[54:57], v[232:235], v[98:101]
	s_setprio 0
	s_barrier
	s_add_i32 s52, s52, s36
	v_lshl_add_u64 v[172:173], s[30:31], 0, v[0:1]
	s_mov_b32 m0, s52
	ds_read_b128 v[182:185], v199 offset:16384
	global_load_lds_dwordx4 v[172:173], off
	ds_read_b128 v[186:189], v199 offset:17408
	s_add_i32 m0, s52, 0x2000
	s_add_u32 s52, s30, 0x20000
	v_lshl_add_u64 v[174:175], s[30:31], 0, v[166:167]
	s_addc_u32 s53, s31, 0
	s_add_i32 s54, s54, s36
	global_load_lds_dwordx4 v[174:175], off
	ds_read_b128 v[212:215], v199 offset:18432
	v_lshl_add_u64 v[176:177], s[52:53], 0, v[0:1]
	s_mov_b32 m0, s54
	v_lshl_add_u64 v[200:201], s[34:35], 0, v[164:165]
	global_load_lds_dwordx4 v[176:177], off
	ds_read_b128 v[216:219], v199 offset:19456
	v_lshl_add_u64 v[176:177], s[52:53], 0, v[166:167]
	s_add_i32 m0, s54, 0x2000
	s_nop 0
	global_load_lds_dwordx4 v[176:177], off
	ds_read_b128 v[220:223], v199 offset:20480
	v_lshl_add_u64 v[176:177], s[34:35], 0, v[162:163]
	s_mov_b32 m0, s37
	s_nop 0
	global_load_lds_dwordx4 v[176:177], off
	ds_read_b128 v[224:227], v199 offset:21504
	s_mov_b32 m0, s38
	s_nop 0
	global_load_lds_dwordx4 v[200:201], off
	ds_read_b128 v[228:231], v199 offset:22528
	ds_read_b128 v[232:235], v199 offset:23552
	s_waitcnt vmcnt(8)
	s_waitcnt lgkmcnt(0)
	s_barrier
; #define PG8_STAGE(bufoff, gbase, voff) do { _Pragma("unroll") for (int _i = 0; _i < 2; ++_i) \
;         __builtin_amdgcn_global_load_lds((const unsigned*)((const char*)(gbase) + (voff)[_i]), (LAS unsigned*)(lds + (bufoff) + ldsw + _i * 8192), 16, 0, 0); } while (0)
; #define PG8_LDA(dst, b, h) do { _Pragma("unroll") for (int m = 0; m < 4; ++m) _Pragma("unroll") for (int k = 0; k < 2; ++k) dst[m][k] = *(const LAS bf16x8*)(lds + PG8_SA(b, h) + aoff + m * 2048 + k * 1024); } while (0)
; #define PG8_LDB(dst, b, h) do { _Pragma("unroll") for (int n = 0; n < 2; ++n) _Pragma("unroll") for (int k = 0; k < 2; ++k) dst[n][k] = *(const LAS bf16x8*)(lds + PG8_SB(b, h) + boff + n * 2048 + k * 1024); } while (0)
; #define PG8_MMA(ai, bj, At, Bt) do { __builtin_amdgcn_s_setprio(1); _Pragma("unroll") for (int m = 0; m < 4; ++m) _Pragma("unroll") for (int n = 0; n < 2; ++n) _Pragma("unroll") for (int k = 0; k < 2; ++k) \
;         acc[ai][bj][m][n] = __builtin_amdgcn_mfma_f32_16x16x32_bf16(Bt[n][k], At[m][k], acc[ai][bj][m][n], 0, 0, 0); __builtin_amdgcn_s_setprio(0); } while (0)
; #define PG8_WAIT_V(n) asm volatile("s_waitcnt vmcnt(" #n ")" ::: "memory")
; #define PG8_WAIT_L(n) asm volatile("s_waitcnt lgkmcnt(" #n ")" ::: "memory")
; #define PG8_BAR __builtin_amdgcn_s_barrier()
; #define PG8_SCHED __builtin_amdgcn_sched_barrier(0)
; template <class Epi>
; __device__ __forceinline__ void gemm_phase(LAS unsigned char* lds, const Gemm g, const StaticOrder& S, const Epi& E, const int tid) {
;     ...
;             PG8_WAIT_V(8); PG8_WAIT_L(0); PG8_BAR; PG8_MMA(1, 0, At, B0); PG8_MMA(1, 1, At, B1); PG8_BAR; PG8_SCHED;
;             PG8_LDB(B0, 1, 0); PG8_LDB(B1, 1, 1); PG8_SCHED; PG8_LDA(At, 1, 0); PG8_STAGE(PG8_SA(0, 1), a2 + hstep, voffA);
;             PG8_WAIT_V(8); PG8_WAIT_L(0); PG8_BAR; PG8_MMA(0, 0, At, B0); PG8_MMA(0, 1, At, B1); PG8_BAR; PG8_SCHED;
	s_setprio 1
	s_waitcnt lgkmcnt(0)
	v_mfma_f32_16x16x32_bf16 v[94:97], v[18:21], v[182:185], v[94:97]
	v_mfma_f32_16x16x32_bf16 v[90:93], v[26:29], v[182:185], v[90:93]
	v_mfma_f32_16x16x32_bf16 v[78:81], v[18:21], v[212:215], v[78:81]
	v_mfma_f32_16x16x32_bf16 v[74:77], v[26:29], v[212:215], v[74:77]
	v_mfma_f32_16x16x32_bf16 v[62:65], v[18:21], v[220:223], v[62:65]
	v_mfma_f32_16x16x32_bf16 v[58:61], v[26:29], v[220:223], v[58:61]
	v_mfma_f32_16x16x32_bf16 v[14:17], v[18:21], v[228:231], v[14:17]
	v_mfma_f32_16x16x32_bf16 v[10:13], v[26:29], v[228:231], v[10:13]
	v_mfma_f32_16x16x32_bf16 v[94:97], v[22:25], v[186:189], v[94:97]
	v_mfma_f32_16x16x32_bf16 v[90:93], v[30:33], v[186:189], v[90:93]
	v_mfma_f32_16x16x32_bf16 v[78:81], v[22:25], v[216:219], v[78:81]
	v_mfma_f32_16x16x32_bf16 v[74:77], v[30:33], v[216:219], v[74:77]
	v_mfma_f32_16x16x32_bf16 v[62:65], v[22:25], v[224:227], v[62:65]
	v_mfma_f32_16x16x32_bf16 v[58:61], v[30:33], v[224:227], v[58:61]
	v_mfma_f32_16x16x32_bf16 v[14:17], v[22:25], v[232:235], v[14:17]
	v_mfma_f32_16x16x32_bf16 v[10:13], v[30:33], v[232:235], v[10:13]
	s_setprio 0
	s_setprio 1
	v_mfma_f32_16x16x32_bf16 v[38:41], v[42:45], v[220:223], v[38:41]
	v_mfma_f32_16x16x32_bf16 v[34:37], v[50:53], v[220:223], v[34:37]
	v_mfma_f32_16x16x32_bf16 v[6:9], v[42:45], v[228:231], v[6:9]
	v_mfma_f32_16x16x32_bf16 v[2:5], v[50:53], v[228:231], v[2:5]
	v_mfma_f32_16x16x32_bf16 v[18:21], v[42:45], v[182:185], v[86:89]
	v_mfma_f32_16x16x32_bf16 v[22:25], v[50:53], v[182:185], v[82:85]
	v_mfma_f32_16x16x32_bf16 v[26:29], v[42:45], v[212:215], v[70:73]
	v_mfma_f32_16x16x32_bf16 v[30:33], v[50:53], v[212:215], v[66:69]
	v_mfma_f32_16x16x32_bf16 v[38:41], v[46:49], v[224:227], v[38:41]
	v_mfma_f32_16x16x32_bf16 v[34:37], v[54:57], v[224:227], v[34:37]
	v_mfma_f32_16x16x32_bf16 v[6:9], v[46:49], v[232:235], v[6:9]
	v_mfma_f32_16x16x32_bf16 v[2:5], v[54:57], v[232:235], v[2:5]
	v_mfma_f32_16x16x32_bf16 v[18:21], v[46:49], v[186:189], v[18:21]
	v_mfma_f32_16x16x32_bf16 v[22:25], v[54:57], v[186:189], v[22:25]
	v_mfma_f32_16x16x32_bf16 v[26:29], v[46:49], v[216:219], v[26:29]
	v_mfma_f32_16x16x32_bf16 v[30:33], v[54:57], v[216:219], v[30:33]
	s_setprio 0
	s_barrier
	s_add_i32 s52, 0, 0x18000
	s_add_i32 s53, 0, 0x1c000
	v_add_u32_e32 v54, s52, v193
	v_add_u32_e32 v66, s53, v193
	ds_read_b128 v[42:45], v54
	ds_read_b128 v[46:49], v54 offset:1024
	ds_read_b128 v[50:53], v54 offset:2048
	ds_read_b128 v[54:57], v54 offset:3072
	ds_read_b128 v[182:185], v66
	ds_read_b128 v[186:189], v66 offset:1024
	ds_read_b128 v[212:215], v66 offset:2048
	ds_read_b128 v[216:219], v66 offset:3072
	s_add_u32 s34, s34, 0x200000
	s_addc_u32 s35, s35, 0
	s_mov_b32 m0, s39
	v_lshl_add_u64 v[236:237], s[34:35], 0, v[162:163]
	ds_read_b128 v[66:69], v199 offset:32768
	global_load_lds_dwordx4 v[236:237], off
	ds_read_b128 v[70:73], v199 offset:33792
	v_lshl_add_u64 v[236:237], s[34:35], 0, v[164:165]
	s_mov_b32 m0, s44
	s_nop 0
	global_load_lds_dwordx4 v[236:237], off
	ds_read_b128 v[82:85], v199 offset:34816
	ds_read_b128 v[86:89], v199 offset:35840
	ds_read_b128 v[220:223], v199 offset:36864
	ds_read_b128 v[224:227], v199 offset:37888
	ds_read_b128 v[228:231], v199 offset:38912
	ds_read_b128 v[232:235], v199 offset:39936
	s_waitcnt vmcnt(8)
	s_waitcnt lgkmcnt(0)
	s_barrier
	s_setprio 1
	s_waitcnt lgkmcnt(0)
	v_mfma_f32_16x16x32_bf16 v[158:161], v[42:45], v[66:69], v[158:161]
	v_mfma_f32_16x16x32_bf16 v[154:157], v[50:53], v[66:69], v[154:157]
	v_mfma_f32_16x16x32_bf16 v[142:145], v[42:45], v[82:85], v[142:145]
	v_mfma_f32_16x16x32_bf16 v[138:141], v[50:53], v[82:85], v[138:141]
	v_mfma_f32_16x16x32_bf16 v[126:129], v[42:45], v[220:223], v[126:129]
	v_mfma_f32_16x16x32_bf16 v[122:125], v[50:53], v[220:223], v[122:125]
	v_mfma_f32_16x16x32_bf16 v[110:113], v[42:45], v[228:231], v[110:113]
	v_mfma_f32_16x16x32_bf16 v[106:109], v[50:53], v[228:231], v[106:109]
	v_mfma_f32_16x16x32_bf16 v[158:161], v[46:49], v[70:73], v[158:161]
	v_mfma_f32_16x16x32_bf16 v[154:157], v[54:57], v[70:73], v[154:157]
	v_mfma_f32_16x16x32_bf16 v[142:145], v[46:49], v[86:89], v[142:145]
	v_mfma_f32_16x16x32_bf16 v[138:141], v[54:57], v[86:89], v[138:141]
	v_mfma_f32_16x16x32_bf16 v[126:129], v[46:49], v[224:227], v[126:129]
	v_mfma_f32_16x16x32_bf16 v[122:125], v[54:57], v[224:227], v[122:125]
	v_mfma_f32_16x16x32_bf16 v[110:113], v[46:49], v[232:235], v[110:113]
	v_mfma_f32_16x16x32_bf16 v[106:109], v[54:57], v[232:235], v[106:109]
	s_setprio 0
	s_setprio 1
	v_mfma_f32_16x16x32_bf16 v[150:153], v[182:185], v[66:69], v[150:153]
	v_mfma_f32_16x16x32_bf16 v[66:69], v[212:215], v[66:69], v[146:149]
	v_mfma_f32_16x16x32_bf16 v[146:149], v[216:219], v[70:73], v[66:69]
	v_mfma_f32_16x16x32_bf16 v[66:69], v[182:185], v[82:85], v[134:137]
	v_mfma_f32_16x16x32_bf16 v[134:137], v[186:189], v[86:89], v[66:69]
	v_mfma_f32_16x16x32_bf16 v[66:69], v[212:215], v[82:85], v[130:133]
	v_mfma_f32_16x16x32_bf16 v[130:133], v[216:219], v[86:89], v[66:69]
	v_mfma_f32_16x16x32_bf16 v[66:69], v[182:185], v[220:223], v[118:121]
	v_mfma_f32_16x16x32_bf16 v[118:121], v[186:189], v[224:227], v[66:69]
	v_mfma_f32_16x16x32_bf16 v[66:69], v[212:215], v[220:223], v[114:117]
	v_mfma_f32_16x16x32_bf16 v[114:117], v[216:219], v[224:227], v[66:69]
	v_mfma_f32_16x16x32_bf16 v[66:69], v[182:185], v[228:231], v[102:105]
	v_mfma_f32_16x16x32_bf16 v[102:105], v[186:189], v[232:235], v[66:69]
	v_mfma_f32_16x16x32_bf16 v[66:69], v[212:215], v[228:231], v[98:101]
	v_mfma_f32_16x16x32_bf16 v[150:153], v[186:189], v[70:73], v[150:153]
	v_mfma_f32_16x16x32_bf16 v[98:101], v[216:219], v[232:235], v[66:69]
	s_setprio 0
	s_barrier
; #define PG8_STAGE(bufoff, gbase, voff) do { _Pragma("unroll") for (int _i = 0; _i < 2; ++_i) \
;         __builtin_amdgcn_global_load_lds((const unsigned*)((const char*)(gbase) + (voff)[_i]), (LAS unsigned*)(lds + (bufoff) + ldsw + _i * 8192), 16, 0, 0); } while (0)
; #define PG8_LDA(dst, b, h) do { _Pragma("unroll") for (int m = 0; m < 4; ++m) _Pragma("unroll") for (int k = 0; k < 2; ++k) dst[m][k] = *(const LAS bf16x8*)(lds + PG8_SA(b, h) + aoff + m * 2048 + k * 1024); } while (0)
; #define PG8_MMA(ai, bj, At, Bt) do { __builtin_amdgcn_s_setprio(1); _Pragma("unroll") for (int m = 0; m < 4; ++m) _Pragma("unroll") for (int n = 0; n < 2; ++n) _Pragma("unroll") for (int k = 0; k < 2; ++k) \
;         acc[ai][bj][m][n] = __builtin_amdgcn_mfma_f32_16x16x32_bf16(Bt[n][k], At[m][k], acc[ai][bj][m][n], 0, 0, 0); __builtin_amdgcn_s_setprio(0); } while (0)
; #define PG8_WAIT_V(n) asm volatile("s_waitcnt vmcnt(" #n ")" ::: "memory")
; #define PG8_WAIT_L(n) asm volatile("s_waitcnt lgkmcnt(" #n ")" ::: "memory")
; #define PG8_BAR __builtin_amdgcn_s_barrier()
; #define PG8_SCHED __builtin_amdgcn_sched_barrier(0)
; template <class Epi>
; __device__ __forceinline__ void gemm_phase(LAS unsigned char* lds, const Gemm g, const StaticOrder& S, const Epi& E, const int tid) {
;     ...
;         for (int t = 0; t < ntt; t += 2) {
;     ...
;             PG8_LDA(At, 1, 1); PG8_STAGE(PG8_SB(1, 0), b3, voffB); PG8_STAGE(PG8_SB(1, 1), b3 + bhs, voffB); PG8_STAGE(PG8_SA(1, 0), a3, voffA);
;             PG8_WAIT_V(8); PG8_WAIT_L(0); PG8_BAR; PG8_MMA(1, 0, At, B0); PG8_MMA(1, 1, At, B1); PG8_BAR; PG8_SCHED;
	s_add_i32 s34, s52, s36
	v_lshl_add_u64 v[82:83], v[172:173], 0, s[70:71]
	s_mov_b32 m0, s34
	s_nop 0
	ds_read_b128 v[66:69], v199 offset:49152
	global_load_lds_dwordx4 v[82:83], off
	ds_read_b128 v[70:73], v199 offset:50176
	s_add_i32 m0, s34, 0x2000
	s_add_u32 s30, s30, 0x20080
	v_lshl_add_u64 v[82:83], v[174:175], 0, s[70:71]
	s_addc_u32 s31, s31, 0
	s_add_i32 s34, s53, s36
	global_load_lds_dwordx4 v[82:83], off
	ds_read_b128 v[220:223], v199 offset:51200
	v_lshl_add_u64 v[82:83], s[30:31], 0, v[0:1]
	s_mov_b32 m0, s34
	s_nop 0
	global_load_lds_dwordx4 v[82:83], off
	ds_read_b128 v[224:227], v199 offset:52224
	v_lshl_add_u64 v[82:83], s[30:31], 0, v[166:167]
	s_add_i32 m0, s34, 0x2000
	s_nop 0
	global_load_lds_dwordx4 v[82:83], off
	ds_read_b128 v[228:231], v199 offset:53248
	v_lshl_add_u64 v[82:83], v[176:177], 0, s[70:71]
	s_mov_b32 m0, s45
	s_nop 0
	global_load_lds_dwordx4 v[82:83], off
	ds_read_b128 v[232:235], v199 offset:54272
	v_lshl_add_u64 v[82:83], v[200:201], 0, s[70:71]
	s_mov_b32 m0, s46
	s_nop 0
	global_load_lds_dwordx4 v[82:83], off
	ds_read_b128 v[236:239], v199 offset:55296
	ds_read_b128 v[240:243], v199 offset:56320
	s_waitcnt vmcnt(8)
	s_waitcnt lgkmcnt(0)
	s_barrier
	s_setprio 1
	s_waitcnt lgkmcnt(0)
	v_mfma_f32_16x16x32_bf16 v[82:85], v[42:45], v[66:69], v[94:97]
	v_mfma_f32_16x16x32_bf16 v[94:97], v[46:49], v[70:73], v[82:85]
	v_mfma_f32_16x16x32_bf16 v[82:85], v[50:53], v[66:69], v[90:93]
	v_mfma_f32_16x16x32_bf16 v[78:81], v[42:45], v[220:223], v[78:81]
	v_mfma_f32_16x16x32_bf16 v[74:77], v[50:53], v[220:223], v[74:77]
	v_mfma_f32_16x16x32_bf16 v[62:65], v[42:45], v[228:231], v[62:65]
	v_mfma_f32_16x16x32_bf16 v[58:61], v[50:53], v[228:231], v[58:61]
	v_mfma_f32_16x16x32_bf16 v[14:17], v[42:45], v[236:239], v[14:17]
	v_mfma_f32_16x16x32_bf16 v[10:13], v[50:53], v[236:239], v[10:13]
	v_mfma_f32_16x16x32_bf16 v[90:93], v[54:57], v[70:73], v[82:85]
	v_mfma_f32_16x16x32_bf16 v[78:81], v[46:49], v[224:227], v[78:81]
	v_mfma_f32_16x16x32_bf16 v[74:77], v[54:57], v[224:227], v[74:77]
	v_mfma_f32_16x16x32_bf16 v[62:65], v[46:49], v[232:235], v[62:65]
	v_mfma_f32_16x16x32_bf16 v[58:61], v[54:57], v[232:235], v[58:61]
	v_mfma_f32_16x16x32_bf16 v[14:17], v[46:49], v[240:243], v[14:17]
	v_mfma_f32_16x16x32_bf16 v[10:13], v[54:57], v[240:243], v[10:13]
	s_setprio 0
	s_setprio 1
	v_mfma_f32_16x16x32_bf16 v[18:21], v[182:185], v[66:69], v[18:21]
	v_mfma_f32_16x16x32_bf16 v[86:89], v[186:189], v[70:73], v[18:21]
	v_mfma_f32_16x16x32_bf16 v[18:21], v[212:215], v[66:69], v[22:25]
	v_mfma_f32_16x16x32_bf16 v[82:85], v[216:219], v[70:73], v[18:21]
	v_mfma_f32_16x16x32_bf16 v[18:21], v[182:185], v[220:223], v[26:29]
	v_mfma_f32_16x16x32_bf16 v[70:73], v[186:189], v[224:227], v[18:21]
	v_mfma_f32_16x16x32_bf16 v[18:21], v[212:215], v[220:223], v[30:33]
	v_mfma_f32_16x16x32_bf16 v[66:69], v[216:219], v[224:227], v[18:21]
	v_mfma_f32_16x16x32_bf16 v[18:21], v[182:185], v[228:231], v[38:41]
	v_mfma_f32_16x16x32_bf16 v[38:41], v[186:189], v[232:235], v[18:21]
	v_mfma_f32_16x16x32_bf16 v[18:21], v[212:215], v[228:231], v[34:37]
	v_mfma_f32_16x16x32_bf16 v[6:9], v[182:185], v[236:239], v[6:9]
	v_mfma_f32_16x16x32_bf16 v[2:5], v[212:215], v[236:239], v[2:5]
	v_mfma_f32_16x16x32_bf16 v[34:37], v[216:219], v[232:235], v[18:21]
	v_mfma_f32_16x16x32_bf16 v[6:9], v[186:189], v[240:243], v[6:9]
	v_mfma_f32_16x16x32_bf16 v[2:5], v[216:219], v[240:243], v[2:5]
	s_setprio 0
	s_barrier
	s_add_i32 s51, s51, 2
	s_add_u32 s49, s49, 0x100
	s_addc_u32 s50, s50, 0
	s_add_u32 s28, s28, 0x100
	s_addc_u32 s29, s29, 0
	s_cmpk_gt_u32 s51, 0x7d
	s_cbranch_scc0 .LBB0_126
	s_and_b64 vcc, exec, s[12:13]
	s_cbranch_vccz .LBB0_129
	s_barrier

; #define PG8_STAGE(bufoff, gbase, voff) do { _Pragma("unroll") for (int _i = 0; _i < 2; ++_i) \
;         __builtin_amdgcn_global_load_lds((const unsigned*)((const char*)(gbase) + (voff)[_i]), (LAS unsigned*)(lds + (bufoff) + ldsw + _i * 8192), 16, 0, 0); } while (0)
; #define PG8_LDA(dst, b, h) do { _Pragma("unroll") for (int m = 0; m < 4; ++m) _Pragma("unroll") for (int k = 0; k < 2; ++k) dst[m][k] = *(const LAS bf16x8*)(lds + PG8_SA(b, h) + aoff + m * 2048 + k * 1024); } while (0)
; #define PG8_LDB(dst, b, h) do { _Pragma("unroll") for (int n = 0; n < 2; ++n) _Pragma("unroll") for (int k = 0; k < 2; ++k) dst[n][k] = *(const LAS bf16x8*)(lds + PG8_SB(b, h) + boff + n * 2048 + k * 1024); } while (0)
; #define PG8_WAIT_V(n) asm volatile("s_waitcnt vmcnt(" #n ")" ::: "memory")
; #define PG8_WAIT_L(n) asm volatile("s_waitcnt lgkmcnt(" #n ")" ::: "memory")
; #define PG8_BAR __builtin_amdgcn_s_barrier()
; #define PG8_SCHED __builtin_amdgcn_sched_barrier(0)
; template <class Epi>
; __device__ __forceinline__ void gemm_phase(LAS unsigned char* lds, const Gemm g, const StaticOrder& S, const Epi& E, const int tid) {
;     ...
;             const bool last = (t == ntt - 2);
;             const bool s1 = Epi::TWO && (t >= nt), s2 = Epi::TWO && (t + 2 >= nt);
;             const char* a1 = (s1 ? cA2 + (size_t)(t - nt + 1) * kstep : cA + (size_t)(t + 1) * kstep);
;             const char* a2 = last ? nA : (s2 ? cA2 + (size_t)(t + 2 - nt) * kstep : cA + (size_t)(t + 2) * kstep);
;             const char* b2 = last ? nB : (s2 ? cB2 + (size_t)(t + 2 - nt) * kstep : cB + (size_t)(t + 2) * kstep);
;             const char* a3 = a2 + kstep; const char* b3 = b2 + kstep;
;             if constexpr (Epi::TWO) { if (t == nt) E.mid(acc, cur, wr, wc, fr, fq); }
;             if constexpr (SP2) {
;             PG8_LDB(B0, 0, 0); PG8_LDB(B1, 0, 1); PG8_SCHED; PG8_LDA(At, 0, 0); PG8_STAGE(PG8_SA(1, 1), a1 + hstep, voffA);
;             PG8_WAIT_V(8); PG8_WAIT_L(0); PG8_BAR; PG8_MMA(0, 0, At, B0); PG8_MMA(0, 1, At, B1); PG8_BAR; PG8_SCHED;
;             PG8_LDA(At, 0, 1); PG8_STAGE(PG8_SB(0, 0), b2, voffB); PG8_STAGE(PG8_SB(0, 1), b2 + bhs, voffB); PG8_STAGE(PG8_SA(0, 0), a2, voffA);
;             PG8_WAIT_V(8); PG8_WAIT_L(0); PG8_BAR; PG8_MMA(1, 0, At, B0); PG8_MMA(1, 1, At, B1); PG8_BAR; PG8_SCHED;
.LBB0_173:
	s_add_u32 s28, s26, 0xfff80080
	s_addc_u32 s29, s27, -1
	s_add_i32 s47, 0, 0x10000
	s_cmp_eq_u32 s46, 28
	s_cselect_b32 s31, s17, s29
	s_cselect_b32 s30, s42, s28
	v_add_u32_e32 v142, s47, v149
	s_cselect_b32 s29, s15, s45
	s_cselect_b32 s28, s43, s44
	s_add_i32 s50, 0, 0x14000
	ds_read_b128 v[156:159], v142
	ds_read_b128 v[160:163], v142 offset:1024
	ds_read_b128 v[164:167], v142 offset:2048
	ds_read_b128 v[178:181], v142 offset:3072
	v_add_u32_e32 v142, s50, v149
	ds_read_b128 v[182:185], v142
	ds_read_b128 v[186:189], v142 offset:1024
	ds_read_b128 v[190:193], v142 offset:2048
	ds_read_b128 v[194:197], v142 offset:3072
	v_lshl_add_u64 v[142:143], s[26:27], 0, v[140:141]
	s_add_i32 m0, s2, 0xc000
	ds_read_b128 v[198:201], v154
	global_load_lds_dwordx4 v[142:143], off
	ds_read_b128 v[212:215], v154 offset:1024
	v_lshl_add_u64 v[142:143], s[26:27], 0, v[138:139]
	s_add_i32 m0, s2, 0xe000
	s_nop 0
	global_load_lds_dwordx4 v[142:143], off
	ds_read_b128 v[216:219], v154 offset:2048
	ds_read_b128 v[220:223], v154 offset:3072
	ds_read_b128 v[224:227], v154 offset:4096
	ds_read_b128 v[228:231], v154 offset:5120
	ds_read_b128 v[232:235], v154 offset:6144
	ds_read_b128 v[236:239], v154 offset:7168
	s_waitcnt vmcnt(8)
	s_waitcnt lgkmcnt(0)
	s_barrier
	s_setprio 1
	s_waitcnt lgkmcnt(0)
	v_mfma_f32_16x16x32_bf16 v[126:129], v[156:159], v[198:201], v[126:129]
	v_mfma_f32_16x16x32_bf16 v[122:125], v[164:167], v[198:201], v[122:125]
	v_mfma_f32_16x16x32_bf16 v[110:113], v[156:159], v[216:219], v[110:113]
	v_mfma_f32_16x16x32_bf16 v[106:109], v[164:167], v[216:219], v[106:109]
	v_mfma_f32_16x16x32_bf16 v[94:97], v[156:159], v[224:227], v[94:97]
	v_mfma_f32_16x16x32_bf16 v[90:93], v[164:167], v[224:227], v[90:93]
	v_mfma_f32_16x16x32_bf16 v[78:81], v[156:159], v[232:235], v[78:81]
	v_mfma_f32_16x16x32_bf16 v[74:77], v[164:167], v[232:235], v[74:77]
	v_mfma_f32_16x16x32_bf16 v[126:129], v[160:163], v[212:215], v[126:129]
	v_mfma_f32_16x16x32_bf16 v[122:125], v[178:181], v[212:215], v[122:125]
	v_mfma_f32_16x16x32_bf16 v[110:113], v[160:163], v[220:223], v[110:113]
	v_mfma_f32_16x16x32_bf16 v[106:109], v[178:181], v[220:223], v[106:109]
	v_mfma_f32_16x16x32_bf16 v[94:97], v[160:163], v[228:231], v[94:97]
	v_mfma_f32_16x16x32_bf16 v[90:93], v[178:181], v[228:231], v[90:93]
	v_mfma_f32_16x16x32_bf16 v[78:81], v[160:163], v[236:239], v[78:81]
	v_mfma_f32_16x16x32_bf16 v[74:77], v[178:181], v[236:239], v[74:77]
	s_setprio 0
	s_setprio 1
	v_mfma_f32_16x16x32_bf16 v[118:121], v[182:185], v[198:201], v[118:121]
	v_mfma_f32_16x16x32_bf16 v[114:117], v[190:193], v[198:201], v[114:117]
	v_mfma_f32_16x16x32_bf16 v[102:105], v[182:185], v[216:219], v[102:105]
	v_mfma_f32_16x16x32_bf16 v[98:101], v[190:193], v[216:219], v[98:101]
	v_mfma_f32_16x16x32_bf16 v[86:89], v[182:185], v[224:227], v[86:89]
	v_mfma_f32_16x16x32_bf16 v[82:85], v[190:193], v[224:227], v[82:85]
	v_mfma_f32_16x16x32_bf16 v[70:73], v[182:185], v[232:235], v[70:73]
	v_mfma_f32_16x16x32_bf16 v[66:69], v[190:193], v[232:235], v[66:69]
	v_mfma_f32_16x16x32_bf16 v[118:121], v[186:189], v[212:215], v[118:121]
	v_mfma_f32_16x16x32_bf16 v[114:117], v[194:197], v[212:215], v[114:117]
	v_mfma_f32_16x16x32_bf16 v[102:105], v[186:189], v[220:223], v[102:105]
	v_mfma_f32_16x16x32_bf16 v[98:101], v[194:197], v[220:223], v[98:101]
	v_mfma_f32_16x16x32_bf16 v[86:89], v[186:189], v[228:231], v[86:89]
	v_mfma_f32_16x16x32_bf16 v[82:85], v[194:197], v[228:231], v[82:85]
	v_mfma_f32_16x16x32_bf16 v[70:73], v[186:189], v[236:239], v[70:73]
	v_mfma_f32_16x16x32_bf16 v[66:69], v[194:197], v[236:239], v[66:69]
	s_setprio 0
	s_barrier
	s_add_i32 s47, s47, s34
	v_lshl_add_u64 v[142:143], s[28:29], 0, v[0:1]
	s_mov_b32 m0, s47
	ds_read_b128 v[198:201], v154 offset:16384
	global_load_lds_dwordx4 v[142:143], off
	ds_read_b128 v[212:215], v154 offset:17408
	s_add_i32 m0, s47, 0x2000
	s_add_u32 s48, s28, 0x8000
	v_lshl_add_u64 v[168:169], s[28:29], 0, v[134:135]
	s_addc_u32 s49, s29, 0
	s_add_i32 s47, s50, s34
	global_load_lds_dwordx4 v[168:169], off
	ds_read_b128 v[216:219], v154 offset:18432
	v_lshl_add_u64 v[172:173], s[48:49], 0, v[0:1]
	s_mov_b32 m0, s47
	v_lshl_add_u64 v[174:175], s[30:31], 0, v[132:133]
	global_load_lds_dwordx4 v[172:173], off
	ds_read_b128 v[220:223], v154 offset:19456
	v_lshl_add_u64 v[172:173], s[48:49], 0, v[134:135]
	s_add_i32 m0, s47, 0x2000
	s_nop 0
	global_load_lds_dwordx4 v[172:173], off
	ds_read_b128 v[224:227], v154 offset:20480
	v_lshl_add_u64 v[172:173], s[30:31], 0, v[130:131]
	s_mov_b32 m0, s2
	s_nop 0
	global_load_lds_dwordx4 v[172:173], off
	ds_read_b128 v[228:231], v154 offset:21504
	s_mov_b32 m0, s25
	s_nop 0
	global_load_lds_dwordx4 v[174:175], off
	ds_read_b128 v[232:235], v154 offset:22528
	ds_read_b128 v[236:239], v154 offset:23552
	s_waitcnt vmcnt(8)
	s_waitcnt lgkmcnt(0)
	s_barrier
; #define PG8_STAGE(bufoff, gbase, voff) do { _Pragma("unroll") for (int _i = 0; _i < 2; ++_i) \
;         __builtin_amdgcn_global_load_lds((const unsigned*)((const char*)(gbase) + (voff)[_i]), (LAS unsigned*)(lds + (bufoff) + ldsw + _i * 8192), 16, 0, 0); } while (0)
; #define PG8_LDA(dst, b, h) do { _Pragma("unroll") for (int m = 0; m < 4; ++m) _Pragma("unroll") for (int k = 0; k < 2; ++k) dst[m][k] = *(const LAS bf16x8*)(lds + PG8_SA(b, h) + aoff + m * 2048 + k * 1024); } while (0)
; #define PG8_LDB(dst, b, h) do { _Pragma("unroll") for (int n = 0; n < 2; ++n) _Pragma("unroll") for (int k = 0; k < 2; ++k) dst[n][k] = *(const LAS bf16x8*)(lds + PG8_SB(b, h) + boff + n * 2048 + k * 1024); } while (0)
; #define PG8_MMA(ai, bj, At, Bt) do { __builtin_amdgcn_s_setprio(1); _Pragma("unroll") for (int m = 0; m < 4; ++m) _Pragma("unroll") for (int n = 0; n < 2; ++n) _Pragma("unroll") for (int k = 0; k < 2; ++k) \
;         acc[ai][bj][m][n] = __builtin_amdgcn_mfma_f32_16x16x32_bf16(Bt[n][k], At[m][k], acc[ai][bj][m][n], 0, 0, 0); __builtin_amdgcn_s_setprio(0); } while (0)
; #define PG8_WAIT_V(n) asm volatile("s_waitcnt vmcnt(" #n ")" ::: "memory")
; #define PG8_WAIT_L(n) asm volatile("s_waitcnt lgkmcnt(" #n ")" ::: "memory")
; #define PG8_BAR __builtin_amdgcn_s_barrier()
; #define PG8_SCHED __builtin_amdgcn_sched_barrier(0)
; template <class Epi>
; __device__ __forceinline__ void gemm_phase(LAS unsigned char* lds, const Gemm g, const StaticOrder& S, const Epi& E, const int tid) {
;     ...
;             PG8_WAIT_V(8); PG8_WAIT_L(0); PG8_BAR; PG8_MMA(1, 0, At, B0); PG8_MMA(1, 1, At, B1); PG8_BAR; PG8_SCHED;
;             PG8_LDB(B0, 1, 0); PG8_LDB(B1, 1, 1); PG8_SCHED; PG8_LDA(At, 1, 0); PG8_STAGE(PG8_SA(0, 1), a2 + hstep, voffA);
;             PG8_WAIT_V(8); PG8_WAIT_L(0); PG8_BAR; PG8_MMA(0, 0, At, B0); PG8_MMA(0, 1, At, B1); PG8_BAR; PG8_SCHED;
	s_setprio 1
	s_waitcnt lgkmcnt(0)
	v_mfma_f32_16x16x32_bf16 v[62:65], v[156:159], v[198:201], v[62:65]
	v_mfma_f32_16x16x32_bf16 v[58:61], v[164:167], v[198:201], v[58:61]
	v_mfma_f32_16x16x32_bf16 v[46:49], v[156:159], v[216:219], v[46:49]
	v_mfma_f32_16x16x32_bf16 v[42:45], v[164:167], v[216:219], v[42:45]
	v_mfma_f32_16x16x32_bf16 v[30:33], v[156:159], v[224:227], v[30:33]
	v_mfma_f32_16x16x32_bf16 v[26:29], v[164:167], v[224:227], v[26:29]
	v_mfma_f32_16x16x32_bf16 v[14:17], v[156:159], v[232:235], v[14:17]
	v_mfma_f32_16x16x32_bf16 v[10:13], v[164:167], v[232:235], v[10:13]
	v_mfma_f32_16x16x32_bf16 v[62:65], v[160:163], v[212:215], v[62:65]
	v_mfma_f32_16x16x32_bf16 v[58:61], v[178:181], v[212:215], v[58:61]
	v_mfma_f32_16x16x32_bf16 v[46:49], v[160:163], v[220:223], v[46:49]
	v_mfma_f32_16x16x32_bf16 v[42:45], v[178:181], v[220:223], v[42:45]
	v_mfma_f32_16x16x32_bf16 v[30:33], v[160:163], v[228:231], v[30:33]
	v_mfma_f32_16x16x32_bf16 v[26:29], v[178:181], v[228:231], v[26:29]
	v_mfma_f32_16x16x32_bf16 v[14:17], v[160:163], v[236:239], v[14:17]
	v_mfma_f32_16x16x32_bf16 v[10:13], v[178:181], v[236:239], v[10:13]
	s_setprio 0
	s_setprio 1
	v_mfma_f32_16x16x32_bf16 v[54:57], v[182:185], v[198:201], v[54:57]
	v_mfma_f32_16x16x32_bf16 v[50:53], v[190:193], v[198:201], v[50:53]
	v_mfma_f32_16x16x32_bf16 v[38:41], v[182:185], v[216:219], v[38:41]
	v_mfma_f32_16x16x32_bf16 v[34:37], v[190:193], v[216:219], v[34:37]
	v_mfma_f32_16x16x32_bf16 v[22:25], v[182:185], v[224:227], v[22:25]
	v_mfma_f32_16x16x32_bf16 v[18:21], v[190:193], v[224:227], v[18:21]
	v_mfma_f32_16x16x32_bf16 v[6:9], v[182:185], v[232:235], v[6:9]
	v_mfma_f32_16x16x32_bf16 v[2:5], v[190:193], v[232:235], v[2:5]
	v_mfma_f32_16x16x32_bf16 v[54:57], v[186:189], v[212:215], v[54:57]
	v_mfma_f32_16x16x32_bf16 v[50:53], v[194:197], v[212:215], v[50:53]
	v_mfma_f32_16x16x32_bf16 v[38:41], v[186:189], v[220:223], v[38:41]
	v_mfma_f32_16x16x32_bf16 v[34:37], v[194:197], v[220:223], v[34:37]
	v_mfma_f32_16x16x32_bf16 v[22:25], v[186:189], v[228:231], v[22:25]
	v_mfma_f32_16x16x32_bf16 v[18:21], v[194:197], v[228:231], v[18:21]
	v_mfma_f32_16x16x32_bf16 v[6:9], v[186:189], v[236:239], v[6:9]
	v_mfma_f32_16x16x32_bf16 v[2:5], v[194:197], v[236:239], v[2:5]
	s_setprio 0
	s_barrier
	s_add_i32 s47, 0, 0x18000
	v_add_u32_e32 v155, s47, v149
	s_add_i32 s48, 0, 0x1c000
	ds_read_b128 v[156:159], v155
	ds_read_b128 v[160:163], v155 offset:1024
	ds_read_b128 v[164:167], v155 offset:2048
	ds_read_b128 v[178:181], v155 offset:3072
	v_add_u32_e32 v155, s48, v149
	ds_read_b128 v[182:185], v155
	ds_read_b128 v[186:189], v155 offset:1024
	ds_read_b128 v[190:193], v155 offset:2048
	ds_read_b128 v[194:197], v155 offset:3072
	s_add_u32 s30, s30, 0x80000
	s_addc_u32 s31, s31, 0
	s_mov_b32 m0, s35
	v_lshl_add_u64 v[176:177], s[30:31], 0, v[130:131]
	ds_read_b128 v[198:201], v154 offset:32768
	global_load_lds_dwordx4 v[176:177], off
	ds_read_b128 v[212:215], v154 offset:33792
	v_lshl_add_u64 v[176:177], s[30:31], 0, v[132:133]
	s_mov_b32 m0, s36
	s_nop 0
	global_load_lds_dwordx4 v[176:177], off
	ds_read_b128 v[216:219], v154 offset:34816
	ds_read_b128 v[220:223], v154 offset:35840
	ds_read_b128 v[224:227], v154 offset:36864
	ds_read_b128 v[228:231], v154 offset:37888
	ds_read_b128 v[232:235], v154 offset:38912
	ds_read_b128 v[236:239], v154 offset:39936
	s_waitcnt vmcnt(8)
	s_waitcnt lgkmcnt(0)
	s_barrier
	s_setprio 1
	s_waitcnt lgkmcnt(0)
	v_mfma_f32_16x16x32_bf16 v[126:129], v[156:159], v[198:201], v[126:129]
	v_mfma_f32_16x16x32_bf16 v[122:125], v[164:167], v[198:201], v[122:125]
	v_mfma_f32_16x16x32_bf16 v[110:113], v[156:159], v[216:219], v[110:113]
	v_mfma_f32_16x16x32_bf16 v[106:109], v[164:167], v[216:219], v[106:109]
	v_mfma_f32_16x16x32_bf16 v[94:97], v[156:159], v[224:227], v[94:97]
	v_mfma_f32_16x16x32_bf16 v[90:93], v[164:167], v[224:227], v[90:93]
	v_mfma_f32_16x16x32_bf16 v[78:81], v[156:159], v[232:235], v[78:81]
	v_mfma_f32_16x16x32_bf16 v[74:77], v[164:167], v[232:235], v[74:77]
	v_mfma_f32_16x16x32_bf16 v[126:129], v[160:163], v[212:215], v[126:129]
	v_mfma_f32_16x16x32_bf16 v[122:125], v[178:181], v[212:215], v[122:125]
	v_mfma_f32_16x16x32_bf16 v[110:113], v[160:163], v[220:223], v[110:113]
	v_mfma_f32_16x16x32_bf16 v[106:109], v[178:181], v[220:223], v[106:109]
	v_mfma_f32_16x16x32_bf16 v[94:97], v[160:163], v[228:231], v[94:97]
	v_mfma_f32_16x16x32_bf16 v[90:93], v[178:181], v[228:231], v[90:93]
	v_mfma_f32_16x16x32_bf16 v[78:81], v[160:163], v[236:239], v[78:81]
	v_mfma_f32_16x16x32_bf16 v[74:77], v[178:181], v[236:239], v[74:77]
	s_setprio 0
	s_setprio 1
	v_mfma_f32_16x16x32_bf16 v[118:121], v[182:185], v[198:201], v[118:121]
	v_mfma_f32_16x16x32_bf16 v[114:117], v[190:193], v[198:201], v[114:117]
	v_mfma_f32_16x16x32_bf16 v[102:105], v[182:185], v[216:219], v[102:105]
	v_mfma_f32_16x16x32_bf16 v[98:101], v[190:193], v[216:219], v[98:101]
	v_mfma_f32_16x16x32_bf16 v[86:89], v[182:185], v[224:227], v[86:89]
	v_mfma_f32_16x16x32_bf16 v[82:85], v[190:193], v[224:227], v[82:85]
	v_mfma_f32_16x16x32_bf16 v[70:73], v[182:185], v[232:235], v[70:73]
	v_mfma_f32_16x16x32_bf16 v[66:69], v[190:193], v[232:235], v[66:69]
	v_mfma_f32_16x16x32_bf16 v[118:121], v[186:189], v[212:215], v[118:121]
	v_mfma_f32_16x16x32_bf16 v[114:117], v[194:197], v[212:215], v[114:117]
	v_mfma_f32_16x16x32_bf16 v[102:105], v[186:189], v[220:223], v[102:105]
	v_mfma_f32_16x16x32_bf16 v[98:101], v[194:197], v[220:223], v[98:101]
	v_mfma_f32_16x16x32_bf16 v[86:89], v[186:189], v[228:231], v[86:89]
	v_mfma_f32_16x16x32_bf16 v[82:85], v[194:197], v[228:231], v[82:85]
	v_mfma_f32_16x16x32_bf16 v[70:73], v[186:189], v[236:239], v[70:73]
	v_mfma_f32_16x16x32_bf16 v[66:69], v[194:197], v[236:239], v[66:69]
	s_setprio 0
	s_barrier
; #define PG8_STAGE(bufoff, gbase, voff) do { _Pragma("unroll") for (int _i = 0; _i < 2; ++_i) \
;         __builtin_amdgcn_global_load_lds((const unsigned*)((const char*)(gbase) + (voff)[_i]), (LAS unsigned*)(lds + (bufoff) + ldsw + _i * 8192), 16, 0, 0); } while (0)
; #define PG8_LDA(dst, b, h) do { _Pragma("unroll") for (int m = 0; m < 4; ++m) _Pragma("unroll") for (int k = 0; k < 2; ++k) dst[m][k] = *(const LAS bf16x8*)(lds + PG8_SA(b, h) + aoff + m * 2048 + k * 1024); } while (0)
; #define PG8_MMA(ai, bj, At, Bt) do { __builtin_amdgcn_s_setprio(1); _Pragma("unroll") for (int m = 0; m < 4; ++m) _Pragma("unroll") for (int n = 0; n < 2; ++n) _Pragma("unroll") for (int k = 0; k < 2; ++k) \
;         acc[ai][bj][m][n] = __builtin_amdgcn_mfma_f32_16x16x32_bf16(Bt[n][k], At[m][k], acc[ai][bj][m][n], 0, 0, 0); __builtin_amdgcn_s_setprio(0); } while (0)
; #define PG8_WAIT_V(n) asm volatile("s_waitcnt vmcnt(" #n ")" ::: "memory")
; #define PG8_WAIT_L(n) asm volatile("s_waitcnt lgkmcnt(" #n ")" ::: "memory")
; #define PG8_BAR __builtin_amdgcn_s_barrier()
; #define PG8_SCHED __builtin_amdgcn_sched_barrier(0)
; template <class Epi>
; __device__ __forceinline__ void gemm_phase(LAS unsigned char* lds, const Gemm g, const StaticOrder& S, const Epi& E, const int tid) {
;     ...
;         for (int t = 0; t < ntt; t += 2) {
;     ...
;             PG8_LDA(At, 1, 1); PG8_STAGE(PG8_SB(1, 0), b3, voffB); PG8_STAGE(PG8_SB(1, 1), b3 + bhs, voffB); PG8_STAGE(PG8_SA(1, 0), a3, voffA);
;             PG8_WAIT_V(8); PG8_WAIT_L(0); PG8_BAR; PG8_MMA(1, 0, At, B0); PG8_MMA(1, 1, At, B1); PG8_BAR; PG8_SCHED;
	s_add_i32 s30, s47, s34
	v_lshl_add_u64 v[142:143], v[142:143], 0, s[70:71]
	s_mov_b32 m0, s30
	ds_read_b128 v[198:201], v154 offset:49152
	global_load_lds_dwordx4 v[142:143], off
	ds_read_b128 v[212:215], v154 offset:50176
	s_add_i32 m0, s30, 0x2000
	s_add_u32 s28, s28, 0x8080
	v_lshl_add_u64 v[142:143], v[168:169], 0, s[70:71]
	s_addc_u32 s29, s29, 0
	s_add_i32 s30, s48, s34
	global_load_lds_dwordx4 v[142:143], off
	ds_read_b128 v[216:219], v154 offset:51200
	v_lshl_add_u64 v[142:143], s[28:29], 0, v[0:1]
	s_mov_b32 m0, s30
	s_nop 0
	global_load_lds_dwordx4 v[142:143], off
	ds_read_b128 v[220:223], v154 offset:52224
	v_lshl_add_u64 v[142:143], s[28:29], 0, v[134:135]
	s_add_i32 m0, s30, 0x2000
	s_nop 0
	global_load_lds_dwordx4 v[142:143], off
	ds_read_b128 v[224:227], v154 offset:53248
	v_lshl_add_u64 v[142:143], v[172:173], 0, s[70:71]
	s_mov_b32 m0, s37
	s_nop 0
	global_load_lds_dwordx4 v[142:143], off
	ds_read_b128 v[228:231], v154 offset:54272
	v_lshl_add_u64 v[142:143], v[174:175], 0, s[70:71]
	s_mov_b32 m0, s38
	s_nop 0
	global_load_lds_dwordx4 v[142:143], off
	ds_read_b128 v[232:235], v154 offset:55296
	ds_read_b128 v[236:239], v154 offset:56320
	s_waitcnt vmcnt(8)
	s_waitcnt lgkmcnt(0)
	s_barrier
	s_setprio 1
	s_waitcnt lgkmcnt(0)
	v_mfma_f32_16x16x32_bf16 v[62:65], v[156:159], v[198:201], v[62:65]
	v_mfma_f32_16x16x32_bf16 v[58:61], v[164:167], v[198:201], v[58:61]
	v_mfma_f32_16x16x32_bf16 v[46:49], v[156:159], v[216:219], v[46:49]
	v_mfma_f32_16x16x32_bf16 v[42:45], v[164:167], v[216:219], v[42:45]
	v_mfma_f32_16x16x32_bf16 v[30:33], v[156:159], v[224:227], v[30:33]
	v_mfma_f32_16x16x32_bf16 v[26:29], v[164:167], v[224:227], v[26:29]
	v_mfma_f32_16x16x32_bf16 v[14:17], v[156:159], v[232:235], v[14:17]
	v_mfma_f32_16x16x32_bf16 v[10:13], v[164:167], v[232:235], v[10:13]
	v_mfma_f32_16x16x32_bf16 v[62:65], v[160:163], v[212:215], v[62:65]
	v_mfma_f32_16x16x32_bf16 v[58:61], v[178:181], v[212:215], v[58:61]
	v_mfma_f32_16x16x32_bf16 v[46:49], v[160:163], v[220:223], v[46:49]
	v_mfma_f32_16x16x32_bf16 v[42:45], v[178:181], v[220:223], v[42:45]
	v_mfma_f32_16x16x32_bf16 v[30:33], v[160:163], v[228:231], v[30:33]
	v_mfma_f32_16x16x32_bf16 v[26:29], v[178:181], v[228:231], v[26:29]
	v_mfma_f32_16x16x32_bf16 v[14:17], v[160:163], v[236:239], v[14:17]
	v_mfma_f32_16x16x32_bf16 v[10:13], v[178:181], v[236:239], v[10:13]
	s_setprio 0
	s_setprio 1
	v_mfma_f32_16x16x32_bf16 v[54:57], v[182:185], v[198:201], v[54:57]
	v_mfma_f32_16x16x32_bf16 v[50:53], v[190:193], v[198:201], v[50:53]
	v_mfma_f32_16x16x32_bf16 v[38:41], v[182:185], v[216:219], v[38:41]
	v_mfma_f32_16x16x32_bf16 v[34:37], v[190:193], v[216:219], v[34:37]
	v_mfma_f32_16x16x32_bf16 v[22:25], v[182:185], v[224:227], v[22:25]
	v_mfma_f32_16x16x32_bf16 v[18:21], v[190:193], v[224:227], v[18:21]
	v_mfma_f32_16x16x32_bf16 v[6:9], v[182:185], v[232:235], v[6:9]
	v_mfma_f32_16x16x32_bf16 v[2:5], v[190:193], v[232:235], v[2:5]
	v_mfma_f32_16x16x32_bf16 v[54:57], v[186:189], v[212:215], v[54:57]
	v_mfma_f32_16x16x32_bf16 v[50:53], v[194:197], v[212:215], v[50:53]
	v_mfma_f32_16x16x32_bf16 v[38:41], v[186:189], v[220:223], v[38:41]
	v_mfma_f32_16x16x32_bf16 v[34:37], v[194:197], v[220:223], v[34:37]
	v_mfma_f32_16x16x32_bf16 v[22:25], v[186:189], v[228:231], v[22:25]
	v_mfma_f32_16x16x32_bf16 v[18:21], v[194:197], v[228:231], v[18:21]
	v_mfma_f32_16x16x32_bf16 v[6:9], v[186:189], v[236:239], v[6:9]
	v_mfma_f32_16x16x32_bf16 v[2:5], v[194:197], v[236:239], v[2:5]
	s_setprio 0
	s_barrier
	s_add_i32 s46, s46, 2
	s_add_u32 s44, s44, 0x100
	s_addc_u32 s45, s45, 0
	s_add_u32 s26, s26, 0x100
	s_addc_u32 s27, s27, 0
	s_cmp_gt_u32 s46, 29
	s_cbranch_scc0 .LBB0_173
	v_readlane_b32 s42, v251, 53
	s_and_b64 vcc, exec, s[12:13]
	v_readlane_b32 s43, v251, 54
	s_cbranch_vccz .LBB0_176
	s_barrier

; #define PG8_STAGE(bufoff, gbase, voff) do { _Pragma("unroll") for (int _i = 0; _i < 2; ++_i) \
;         __builtin_amdgcn_global_load_lds((const unsigned*)((const char*)(gbase) + (voff)[_i]), (LAS unsigned*)(lds + (bufoff) + ldsw + _i * 8192), 16, 0, 0); } while (0)
; #define PG8_LDA(dst, b, h) do { _Pragma("unroll") for (int m = 0; m < 4; ++m) _Pragma("unroll") for (int k = 0; k < 2; ++k) dst[m][k] = *(const LAS bf16x8*)(lds + PG8_SA(b, h) + aoff + m * 2048 + k * 1024); } while (0)
; #define PG8_LDB(dst, b, h) do { _Pragma("unroll") for (int n = 0; n < 2; ++n) _Pragma("unroll") for (int k = 0; k < 2; ++k) dst[n][k] = *(const LAS bf16x8*)(lds + PG8_SB(b, h) + boff + n * 2048 + k * 1024); } while (0)
; #define PG8_WAIT_V(n) asm volatile("s_waitcnt vmcnt(" #n ")" ::: "memory")
; #define PG8_WAIT_L(n) asm volatile("s_waitcnt lgkmcnt(" #n ")" ::: "memory")
; #define PG8_BAR __builtin_amdgcn_s_barrier()
; #define PG8_SCHED __builtin_amdgcn_sched_barrier(0)
; template <class Epi>
; __device__ __forceinline__ void gemm_phase(LAS unsigned char* lds, const Gemm g, const StaticOrder& S, const Epi& E, const int tid) {
;     ...
;             const bool last = (t == ntt - 2);
;             const bool s1 = Epi::TWO && (t >= nt), s2 = Epi::TWO && (t + 2 >= nt);
;             const char* a1 = (s1 ? cA2 + (size_t)(t - nt + 1) * kstep : cA + (size_t)(t + 1) * kstep);
;             const char* a2 = last ? nA : (s2 ? cA2 + (size_t)(t + 2 - nt) * kstep : cA + (size_t)(t + 2) * kstep);
;             const char* b2 = last ? nB : (s2 ? cB2 + (size_t)(t + 2 - nt) * kstep : cB + (size_t)(t + 2) * kstep);
;             const char* a3 = a2 + kstep; const char* b3 = b2 + kstep;
;             if constexpr (Epi::TWO) { if (t == nt) E.mid(acc, cur, wr, wc, fr, fq); }
;             if constexpr (SP2) {
;             PG8_LDB(B0, 0, 0); PG8_LDB(B1, 0, 1); PG8_SCHED; PG8_LDA(At, 0, 0); PG8_STAGE(PG8_SA(1, 1), a1 + hstep, voffA);
;             PG8_WAIT_V(8); PG8_WAIT_L(0); PG8_BAR; PG8_MMA(0, 0, At, B0); PG8_MMA(0, 1, At, B1); PG8_BAR; PG8_SCHED;
;             PG8_LDA(At, 0, 1); PG8_STAGE(PG8_SB(0, 0), b2, voffB); PG8_STAGE(PG8_SB(0, 1), b2 + bhs, voffB); PG8_STAGE(PG8_SA(0, 0), a2, voffA);
;             PG8_WAIT_V(8); PG8_WAIT_L(0); PG8_BAR; PG8_MMA(1, 0, At, B0); PG8_MMA(1, 1, At, B1); PG8_BAR; PG8_SCHED;
.LBB0_206:
	s_add_u32 s30, s28, 0xfffe0080
	s_addc_u32 s31, s29, -1
	s_add_i32 s52, 0, 0x10000
	s_cmp_eq_u32 s51, 4
	s_cselect_b32 s35, s17, s31
	s_cselect_b32 s34, s27, s30
	s_cselect_b32 s31, s15, s50
	s_cselect_b32 s30, s33, s49
	s_add_i32 s54, 0, 0x14000
	v_add_u32_e32 v30, s52, v193
	v_add_u32_e32 v54, s54, v193
	ds_read_b128 v[18:21], v30
	ds_read_b128 v[22:25], v30 offset:1024
	ds_read_b128 v[26:29], v30 offset:2048
	ds_read_b128 v[30:33], v30 offset:3072
	ds_read_b128 v[42:45], v54
	ds_read_b128 v[46:49], v54 offset:1024
	ds_read_b128 v[50:53], v54 offset:2048
	ds_read_b128 v[54:57], v54 offset:3072
	v_lshl_add_u64 v[172:173], s[28:29], 0, v[180:181]
	s_add_i32 m0, s37, 0xc000
	ds_read_b128 v[182:185], v199
	global_load_lds_dwordx4 v[172:173], off
	ds_read_b128 v[186:189], v199 offset:1024
	v_lshl_add_u64 v[172:173], s[28:29], 0, v[178:179]
	s_add_i32 m0, s37, 0xe000
	s_nop 0
	global_load_lds_dwordx4 v[172:173], off
	ds_read_b128 v[212:215], v199 offset:2048
	ds_read_b128 v[216:219], v199 offset:3072
	ds_read_b128 v[220:223], v199 offset:4096
	ds_read_b128 v[224:227], v199 offset:5120
	ds_read_b128 v[228:231], v199 offset:6144
	ds_read_b128 v[232:235], v199 offset:7168
	s_waitcnt vmcnt(8)
	s_waitcnt lgkmcnt(0)
	s_barrier
	s_setprio 1
	s_waitcnt lgkmcnt(0)
	v_mfma_f32_16x16x32_bf16 v[158:161], v[18:21], v[182:185], v[158:161]
	v_mfma_f32_16x16x32_bf16 v[154:157], v[26:29], v[182:185], v[154:157]
	v_mfma_f32_16x16x32_bf16 v[142:145], v[18:21], v[212:215], v[142:145]
	v_mfma_f32_16x16x32_bf16 v[138:141], v[26:29], v[212:215], v[138:141]
	v_mfma_f32_16x16x32_bf16 v[126:129], v[18:21], v[220:223], v[126:129]
	v_mfma_f32_16x16x32_bf16 v[122:125], v[26:29], v[220:223], v[122:125]
	v_mfma_f32_16x16x32_bf16 v[110:113], v[18:21], v[228:231], v[110:113]
	v_mfma_f32_16x16x32_bf16 v[106:109], v[26:29], v[228:231], v[106:109]
	v_mfma_f32_16x16x32_bf16 v[158:161], v[22:25], v[186:189], v[158:161]
	v_mfma_f32_16x16x32_bf16 v[154:157], v[30:33], v[186:189], v[154:157]
	v_mfma_f32_16x16x32_bf16 v[142:145], v[22:25], v[216:219], v[142:145]
	v_mfma_f32_16x16x32_bf16 v[138:141], v[30:33], v[216:219], v[138:141]
	v_mfma_f32_16x16x32_bf16 v[126:129], v[22:25], v[224:227], v[126:129]
	v_mfma_f32_16x16x32_bf16 v[122:125], v[30:33], v[224:227], v[122:125]
	v_mfma_f32_16x16x32_bf16 v[110:113], v[22:25], v[232:235], v[110:113]
	v_mfma_f32_16x16x32_bf16 v[106:109], v[30:33], v[232:235], v[106:109]
	s_setprio 0
	s_setprio 1
	v_mfma_f32_16x16x32_bf16 v[150:153], v[42:45], v[182:185], v[150:153]
	v_mfma_f32_16x16x32_bf16 v[146:149], v[50:53], v[182:185], v[146:149]
	v_mfma_f32_16x16x32_bf16 v[134:137], v[42:45], v[212:215], v[134:137]
	v_mfma_f32_16x16x32_bf16 v[130:133], v[50:53], v[212:215], v[130:133]
	v_mfma_f32_16x16x32_bf16 v[118:121], v[42:45], v[220:223], v[118:121]
	v_mfma_f32_16x16x32_bf16 v[114:117], v[50:53], v[220:223], v[114:117]
	v_mfma_f32_16x16x32_bf16 v[102:105], v[42:45], v[228:231], v[102:105]
	v_mfma_f32_16x16x32_bf16 v[98:101], v[50:53], v[228:231], v[98:101]
	v_mfma_f32_16x16x32_bf16 v[150:153], v[46:49], v[186:189], v[150:153]
	v_mfma_f32_16x16x32_bf16 v[146:149], v[54:57], v[186:189], v[146:149]
	v_mfma_f32_16x16x32_bf16 v[134:137], v[46:49], v[216:219], v[134:137]
	v_mfma_f32_16x16x32_bf16 v[130:133], v[54:57], v[216:219], v[130:133]
	v_mfma_f32_16x16x32_bf16 v[118:121], v[46:49], v[224:227], v[118:121]
	v_mfma_f32_16x16x32_bf16 v[114:117], v[54:57], v[224:227], v[114:117]
	v_mfma_f32_16x16x32_bf16 v[102:105], v[46:49], v[232:235], v[102:105]
	v_mfma_f32_16x16x32_bf16 v[98:101], v[54:57], v[232:235], v[98:101]
	s_setprio 0
	s_barrier
	s_add_i32 s52, s52, s36
	v_lshl_add_u64 v[172:173], s[30:31], 0, v[0:1]
	s_mov_b32 m0, s52
	ds_read_b128 v[182:185], v199 offset:16384
	global_load_lds_dwordx4 v[172:173], off
	ds_read_b128 v[186:189], v199 offset:17408
	s_add_i32 m0, s52, 0x2000
	s_add_u32 s52, s30, 0x2000
	v_lshl_add_u64 v[174:175], s[30:31], 0, v[166:167]
	s_addc_u32 s53, s31, 0
	s_add_i32 s54, s54, s36
	global_load_lds_dwordx4 v[174:175], off
	ds_read_b128 v[212:215], v199 offset:18432
	v_lshl_add_u64 v[176:177], s[52:53], 0, v[0:1]
	s_mov_b32 m0, s54
	v_lshl_add_u64 v[200:201], s[34:35], 0, v[164:165]
	global_load_lds_dwordx4 v[176:177], off
	ds_read_b128 v[216:219], v199 offset:19456
	v_lshl_add_u64 v[176:177], s[52:53], 0, v[166:167]
	s_add_i32 m0, s54, 0x2000
	s_nop 0
	global_load_lds_dwordx4 v[176:177], off
	ds_read_b128 v[220:223], v199 offset:20480
	v_lshl_add_u64 v[176:177], s[34:35], 0, v[162:163]
	s_mov_b32 m0, s37
	s_nop 0
	global_load_lds_dwordx4 v[176:177], off
	ds_read_b128 v[224:227], v199 offset:21504
	s_mov_b32 m0, s38
	s_nop 0
	global_load_lds_dwordx4 v[200:201], off
	ds_read_b128 v[228:231], v199 offset:22528
	ds_read_b128 v[232:235], v199 offset:23552
	s_waitcnt vmcnt(8)
	s_waitcnt lgkmcnt(0)
	s_barrier
; #define PG8_STAGE(bufoff, gbase, voff) do { _Pragma("unroll") for (int _i = 0; _i < 2; ++_i) \
;         __builtin_amdgcn_global_load_lds((const unsigned*)((const char*)(gbase) + (voff)[_i]), (LAS unsigned*)(lds + (bufoff) + ldsw + _i * 8192), 16, 0, 0); } while (0)
; #define PG8_LDA(dst, b, h) do { _Pragma("unroll") for (int m = 0; m < 4; ++m) _Pragma("unroll") for (int k = 0; k < 2; ++k) dst[m][k] = *(const LAS bf16x8*)(lds + PG8_SA(b, h) + aoff + m * 2048 + k * 1024); } while (0)
; #define PG8_LDB(dst, b, h) do { _Pragma("unroll") for (int n = 0; n < 2; ++n) _Pragma("unroll") for (int k = 0; k < 2; ++k) dst[n][k] = *(const LAS bf16x8*)(lds + PG8_SB(b, h) + boff + n * 2048 + k * 1024); } while (0)
; #define PG8_MMA(ai, bj, At, Bt) do { __builtin_amdgcn_s_setprio(1); _Pragma("unroll") for (int m = 0; m < 4; ++m) _Pragma("unroll") for (int n = 0; n < 2; ++n) _Pragma("unroll") for (int k = 0; k < 2; ++k) \
;         acc[ai][bj][m][n] = __builtin_amdgcn_mfma_f32_16x16x32_bf16(Bt[n][k], At[m][k], acc[ai][bj][m][n], 0, 0, 0); __builtin_amdgcn_s_setprio(0); } while (0)
; #define PG8_WAIT_V(n) asm volatile("s_waitcnt vmcnt(" #n ")" ::: "memory")
; #define PG8_WAIT_L(n) asm volatile("s_waitcnt lgkmcnt(" #n ")" ::: "memory")
; #define PG8_BAR __builtin_amdgcn_s_barrier()
; #define PG8_SCHED __builtin_amdgcn_sched_barrier(0)
; template <class Epi>
; __device__ __forceinline__ void gemm_phase(LAS unsigned char* lds, const Gemm g, const StaticOrder& S, const Epi& E, const int tid) {
;     ...
;             PG8_WAIT_V(8); PG8_WAIT_L(0); PG8_BAR; PG8_MMA(1, 0, At, B0); PG8_MMA(1, 1, At, B1); PG8_BAR; PG8_SCHED;
;             PG8_LDB(B0, 1, 0); PG8_LDB(B1, 1, 1); PG8_SCHED; PG8_LDA(At, 1, 0); PG8_STAGE(PG8_SA(0, 1), a2 + hstep, voffA);
;             PG8_WAIT_V(8); PG8_WAIT_L(0); PG8_BAR; PG8_MMA(0, 0, At, B0); PG8_MMA(0, 1, At, B1); PG8_BAR; PG8_SCHED;
	s_setprio 1
	s_waitcnt lgkmcnt(0)
	v_mfma_f32_16x16x32_bf16 v[94:97], v[18:21], v[182:185], v[94:97]
	v_mfma_f32_16x16x32_bf16 v[90:93], v[26:29], v[182:185], v[90:93]
	v_mfma_f32_16x16x32_bf16 v[78:81], v[18:21], v[212:215], v[78:81]
	v_mfma_f32_16x16x32_bf16 v[74:77], v[26:29], v[212:215], v[74:77]
	v_mfma_f32_16x16x32_bf16 v[62:65], v[18:21], v[220:223], v[62:65]
	v_mfma_f32_16x16x32_bf16 v[58:61], v[26:29], v[220:223], v[58:61]
	v_mfma_f32_16x16x32_bf16 v[14:17], v[18:21], v[228:231], v[14:17]
	v_mfma_f32_16x16x32_bf16 v[10:13], v[26:29], v[228:231], v[10:13]
	v_mfma_f32_16x16x32_bf16 v[94:97], v[22:25], v[186:189], v[94:97]
	v_mfma_f32_16x16x32_bf16 v[90:93], v[30:33], v[186:189], v[90:93]
	v_mfma_f32_16x16x32_bf16 v[78:81], v[22:25], v[216:219], v[78:81]
	v_mfma_f32_16x16x32_bf16 v[74:77], v[30:33], v[216:219], v[74:77]
	v_mfma_f32_16x16x32_bf16 v[62:65], v[22:25], v[224:227], v[62:65]
	v_mfma_f32_16x16x32_bf16 v[58:61], v[30:33], v[224:227], v[58:61]
	v_mfma_f32_16x16x32_bf16 v[14:17], v[22:25], v[232:235], v[14:17]
	v_mfma_f32_16x16x32_bf16 v[10:13], v[30:33], v[232:235], v[10:13]
	s_setprio 0
	s_setprio 1
	v_mfma_f32_16x16x32_bf16 v[38:41], v[42:45], v[220:223], v[38:41]
	v_mfma_f32_16x16x32_bf16 v[34:37], v[50:53], v[220:223], v[34:37]
	v_mfma_f32_16x16x32_bf16 v[6:9], v[42:45], v[228:231], v[6:9]
	v_mfma_f32_16x16x32_bf16 v[2:5], v[50:53], v[228:231], v[2:5]
	v_mfma_f32_16x16x32_bf16 v[18:21], v[42:45], v[182:185], v[86:89]
	v_mfma_f32_16x16x32_bf16 v[22:25], v[50:53], v[182:185], v[82:85]
	v_mfma_f32_16x16x32_bf16 v[26:29], v[42:45], v[212:215], v[70:73]
	v_mfma_f32_16x16x32_bf16 v[30:33], v[50:53], v[212:215], v[66:69]
	v_mfma_f32_16x16x32_bf16 v[38:41], v[46:49], v[224:227], v[38:41]
	v_mfma_f32_16x16x32_bf16 v[34:37], v[54:57], v[224:227], v[34:37]
	v_mfma_f32_16x16x32_bf16 v[6:9], v[46:49], v[232:235], v[6:9]
	v_mfma_f32_16x16x32_bf16 v[2:5], v[54:57], v[232:235], v[2:5]
	v_mfma_f32_16x16x32_bf16 v[18:21], v[46:49], v[186:189], v[18:21]
	v_mfma_f32_16x16x32_bf16 v[22:25], v[54:57], v[186:189], v[22:25]
	v_mfma_f32_16x16x32_bf16 v[26:29], v[46:49], v[216:219], v[26:29]
	v_mfma_f32_16x16x32_bf16 v[30:33], v[54:57], v[216:219], v[30:33]
	s_setprio 0
	s_barrier
	s_add_i32 s52, 0, 0x18000
	s_add_i32 s53, 0, 0x1c000
	v_add_u32_e32 v54, s52, v193
	v_add_u32_e32 v66, s53, v193
	ds_read_b128 v[42:45], v54
	ds_read_b128 v[46:49], v54 offset:1024
	ds_read_b128 v[50:53], v54 offset:2048
	ds_read_b128 v[54:57], v54 offset:3072
	ds_read_b128 v[182:185], v66
	ds_read_b128 v[186:189], v66 offset:1024
	ds_read_b128 v[212:215], v66 offset:2048
	ds_read_b128 v[216:219], v66 offset:3072
	s_add_u32 s34, s34, 0x20000
	s_addc_u32 s35, s35, 0
	s_mov_b32 m0, s39
	v_lshl_add_u64 v[236:237], s[34:35], 0, v[162:163]
	ds_read_b128 v[66:69], v199 offset:32768
	global_load_lds_dwordx4 v[236:237], off
	ds_read_b128 v[70:73], v199 offset:33792
	v_lshl_add_u64 v[236:237], s[34:35], 0, v[164:165]
	s_mov_b32 m0, s44
	s_nop 0
	global_load_lds_dwordx4 v[236:237], off
	ds_read_b128 v[82:85], v199 offset:34816
	ds_read_b128 v[86:89], v199 offset:35840
	ds_read_b128 v[220:223], v199 offset:36864
	ds_read_b128 v[224:227], v199 offset:37888
	ds_read_b128 v[228:231], v199 offset:38912
	ds_read_b128 v[232:235], v199 offset:39936
	s_waitcnt vmcnt(8)
	s_waitcnt lgkmcnt(0)
	s_barrier
	s_setprio 1
	s_waitcnt lgkmcnt(0)
	v_mfma_f32_16x16x32_bf16 v[158:161], v[42:45], v[66:69], v[158:161]
	v_mfma_f32_16x16x32_bf16 v[154:157], v[50:53], v[66:69], v[154:157]
	v_mfma_f32_16x16x32_bf16 v[142:145], v[42:45], v[82:85], v[142:145]
	v_mfma_f32_16x16x32_bf16 v[138:141], v[50:53], v[82:85], v[138:141]
	v_mfma_f32_16x16x32_bf16 v[126:129], v[42:45], v[220:223], v[126:129]
	v_mfma_f32_16x16x32_bf16 v[122:125], v[50:53], v[220:223], v[122:125]
	v_mfma_f32_16x16x32_bf16 v[110:113], v[42:45], v[228:231], v[110:113]
	v_mfma_f32_16x16x32_bf16 v[106:109], v[50:53], v[228:231], v[106:109]
	v_mfma_f32_16x16x32_bf16 v[158:161], v[46:49], v[70:73], v[158:161]
	v_mfma_f32_16x16x32_bf16 v[154:157], v[54:57], v[70:73], v[154:157]
	v_mfma_f32_16x16x32_bf16 v[142:145], v[46:49], v[86:89], v[142:145]
	v_mfma_f32_16x16x32_bf16 v[138:141], v[54:57], v[86:89], v[138:141]
	v_mfma_f32_16x16x32_bf16 v[126:129], v[46:49], v[224:227], v[126:129]
	v_mfma_f32_16x16x32_bf16 v[122:125], v[54:57], v[224:227], v[122:125]
	v_mfma_f32_16x16x32_bf16 v[110:113], v[46:49], v[232:235], v[110:113]
	v_mfma_f32_16x16x32_bf16 v[106:109], v[54:57], v[232:235], v[106:109]
	s_setprio 0
	s_setprio 1
	v_mfma_f32_16x16x32_bf16 v[150:153], v[182:185], v[66:69], v[150:153]
	v_mfma_f32_16x16x32_bf16 v[66:69], v[212:215], v[66:69], v[146:149]
	v_mfma_f32_16x16x32_bf16 v[146:149], v[216:219], v[70:73], v[66:69]
	v_mfma_f32_16x16x32_bf16 v[66:69], v[182:185], v[82:85], v[134:137]
	v_mfma_f32_16x16x32_bf16 v[134:137], v[186:189], v[86:89], v[66:69]
	v_mfma_f32_16x16x32_bf16 v[66:69], v[212:215], v[82:85], v[130:133]
	v_mfma_f32_16x16x32_bf16 v[130:133], v[216:219], v[86:89], v[66:69]
	v_mfma_f32_16x16x32_bf16 v[66:69], v[182:185], v[220:223], v[118:121]
	v_mfma_f32_16x16x32_bf16 v[118:121], v[186:189], v[224:227], v[66:69]
	v_mfma_f32_16x16x32_bf16 v[66:69], v[212:215], v[220:223], v[114:117]
	v_mfma_f32_16x16x32_bf16 v[114:117], v[216:219], v[224:227], v[66:69]
	v_mfma_f32_16x16x32_bf16 v[66:69], v[182:185], v[228:231], v[102:105]
	v_mfma_f32_16x16x32_bf16 v[102:105], v[186:189], v[232:235], v[66:69]
	v_mfma_f32_16x16x32_bf16 v[66:69], v[212:215], v[228:231], v[98:101]
	v_mfma_f32_16x16x32_bf16 v[150:153], v[186:189], v[70:73], v[150:153]
	v_mfma_f32_16x16x32_bf16 v[98:101], v[216:219], v[232:235], v[66:69]
	s_setprio 0
	s_barrier
; #define PG8_STAGE(bufoff, gbase, voff) do { _Pragma("unroll") for (int _i = 0; _i < 2; ++_i) \
;         __builtin_amdgcn_global_load_lds((const unsigned*)((const char*)(gbase) + (voff)[_i]), (LAS unsigned*)(lds + (bufoff) + ldsw + _i * 8192), 16, 0, 0); } while (0)
; #define PG8_LDA(dst, b, h) do { _Pragma("unroll") for (int m = 0; m < 4; ++m) _Pragma("unroll") for (int k = 0; k < 2; ++k) dst[m][k] = *(const LAS bf16x8*)(lds + PG8_SA(b, h) + aoff + m * 2048 + k * 1024); } while (0)
; #define PG8_MMA(ai, bj, At, Bt) do { __builtin_amdgcn_s_setprio(1); _Pragma("unroll") for (int m = 0; m < 4; ++m) _Pragma("unroll") for (int n = 0; n < 2; ++n) _Pragma("unroll") for (int k = 0; k < 2; ++k) \
;         acc[ai][bj][m][n] = __builtin_amdgcn_mfma_f32_16x16x32_bf16(Bt[n][k], At[m][k], acc[ai][bj][m][n], 0, 0, 0); __builtin_amdgcn_s_setprio(0); } while (0)
; #define PG8_WAIT_V(n) asm volatile("s_waitcnt vmcnt(" #n ")" ::: "memory")
; #define PG8_WAIT_L(n) asm volatile("s_waitcnt lgkmcnt(" #n ")" ::: "memory")
; #define PG8_BAR __builtin_amdgcn_s_barrier()
; #define PG8_SCHED __builtin_amdgcn_sched_barrier(0)
; template <class Epi>
; __device__ __forceinline__ void gemm_phase(LAS unsigned char* lds, const Gemm g, const StaticOrder& S, const Epi& E, const int tid) {
;     ...
;         for (int t = 0; t < ntt; t += 2) {
;     ...
;             PG8_LDA(At, 1, 1); PG8_STAGE(PG8_SB(1, 0), b3, voffB); PG8_STAGE(PG8_SB(1, 1), b3 + bhs, voffB); PG8_STAGE(PG8_SA(1, 0), a3, voffA);
;             PG8_WAIT_V(8); PG8_WAIT_L(0); PG8_BAR; PG8_MMA(1, 0, At, B0); PG8_MMA(1, 1, At, B1); PG8_BAR; PG8_SCHED;
	s_add_i32 s34, s52, s36
	v_lshl_add_u64 v[82:83], v[172:173], 0, s[70:71]
	s_mov_b32 m0, s34
	s_nop 0
	ds_read_b128 v[66:69], v199 offset:49152
	global_load_lds_dwordx4 v[82:83], off
	ds_read_b128 v[70:73], v199 offset:50176
	s_add_i32 m0, s34, 0x2000
	s_add_u32 s30, s30, 0x2080
	v_lshl_add_u64 v[82:83], v[174:175], 0, s[70:71]
	s_addc_u32 s31, s31, 0
	s_add_i32 s34, s53, s36
	global_load_lds_dwordx4 v[82:83], off
	ds_read_b128 v[220:223], v199 offset:51200
	v_lshl_add_u64 v[82:83], s[30:31], 0, v[0:1]
	s_mov_b32 m0, s34
	s_nop 0
	global_load_lds_dwordx4 v[82:83], off
	ds_read_b128 v[224:227], v199 offset:52224
	v_lshl_add_u64 v[82:83], s[30:31], 0, v[166:167]
	s_add_i32 m0, s34, 0x2000
	s_nop 0
	global_load_lds_dwordx4 v[82:83], off
	ds_read_b128 v[228:231], v199 offset:53248
	v_lshl_add_u64 v[82:83], v[176:177], 0, s[70:71]
	s_mov_b32 m0, s45
	s_nop 0
	global_load_lds_dwordx4 v[82:83], off
	ds_read_b128 v[232:235], v199 offset:54272
	v_lshl_add_u64 v[82:83], v[200:201], 0, s[70:71]
	s_mov_b32 m0, s46
	s_nop 0
	global_load_lds_dwordx4 v[82:83], off
	ds_read_b128 v[236:239], v199 offset:55296
	ds_read_b128 v[240:243], v199 offset:56320
	s_waitcnt vmcnt(8)
	s_waitcnt lgkmcnt(0)
	s_barrier
	s_setprio 1
	s_waitcnt lgkmcnt(0)
	v_mfma_f32_16x16x32_bf16 v[82:85], v[42:45], v[66:69], v[94:97]
	v_mfma_f32_16x16x32_bf16 v[94:97], v[46:49], v[70:73], v[82:85]
	v_mfma_f32_16x16x32_bf16 v[82:85], v[50:53], v[66:69], v[90:93]
	v_mfma_f32_16x16x32_bf16 v[78:81], v[42:45], v[220:223], v[78:81]
	v_mfma_f32_16x16x32_bf16 v[74:77], v[50:53], v[220:223], v[74:77]
	v_mfma_f32_16x16x32_bf16 v[62:65], v[42:45], v[228:231], v[62:65]
	v_mfma_f32_16x16x32_bf16 v[58:61], v[50:53], v[228:231], v[58:61]
	v_mfma_f32_16x16x32_bf16 v[14:17], v[42:45], v[236:239], v[14:17]
	v_mfma_f32_16x16x32_bf16 v[10:13], v[50:53], v[236:239], v[10:13]
	v_mfma_f32_16x16x32_bf16 v[90:93], v[54:57], v[70:73], v[82:85]
	v_mfma_f32_16x16x32_bf16 v[78:81], v[46:49], v[224:227], v[78:81]
	v_mfma_f32_16x16x32_bf16 v[74:77], v[54:57], v[224:227], v[74:77]
	v_mfma_f32_16x16x32_bf16 v[62:65], v[46:49], v[232:235], v[62:65]
	v_mfma_f32_16x16x32_bf16 v[58:61], v[54:57], v[232:235], v[58:61]
	v_mfma_f32_16x16x32_bf16 v[14:17], v[46:49], v[240:243], v[14:17]
	v_mfma_f32_16x16x32_bf16 v[10:13], v[54:57], v[240:243], v[10:13]
	s_setprio 0
	s_setprio 1
	v_mfma_f32_16x16x32_bf16 v[18:21], v[182:185], v[66:69], v[18:21]
	v_mfma_f32_16x16x32_bf16 v[86:89], v[186:189], v[70:73], v[18:21]
	v_mfma_f32_16x16x32_bf16 v[18:21], v[212:215], v[66:69], v[22:25]
	v_mfma_f32_16x16x32_bf16 v[82:85], v[216:219], v[70:73], v[18:21]
	v_mfma_f32_16x16x32_bf16 v[18:21], v[182:185], v[220:223], v[26:29]
	v_mfma_f32_16x16x32_bf16 v[70:73], v[186:189], v[224:227], v[18:21]
	v_mfma_f32_16x16x32_bf16 v[18:21], v[212:215], v[220:223], v[30:33]
	v_mfma_f32_16x16x32_bf16 v[66:69], v[216:219], v[224:227], v[18:21]
	v_mfma_f32_16x16x32_bf16 v[18:21], v[182:185], v[228:231], v[38:41]
	v_mfma_f32_16x16x32_bf16 v[38:41], v[186:189], v[232:235], v[18:21]
	v_mfma_f32_16x16x32_bf16 v[18:21], v[212:215], v[228:231], v[34:37]
	v_mfma_f32_16x16x32_bf16 v[6:9], v[182:185], v[236:239], v[6:9]
	v_mfma_f32_16x16x32_bf16 v[2:5], v[212:215], v[236:239], v[2:5]
	v_mfma_f32_16x16x32_bf16 v[34:37], v[216:219], v[232:235], v[18:21]
	v_mfma_f32_16x16x32_bf16 v[6:9], v[186:189], v[240:243], v[6:9]
	v_mfma_f32_16x16x32_bf16 v[2:5], v[216:219], v[240:243], v[2:5]
	s_setprio 0
	s_barrier
	s_add_i32 s51, s51, 2
	s_add_u32 s49, s49, 0x100
	s_addc_u32 s50, s50, 0
	s_add_u32 s28, s28, 0x100
	s_addc_u32 s29, s29, 0
	s_cmp_gt_u32 s51, 5
	s_cbranch_scc0 .LBB0_206
	s_and_b64 vcc, exec, s[12:13]
	s_cbranch_vccz .LBB0_209
	s_barrier

; #define PG8_STAGE(bufoff, gbase, voff) do { _Pragma("unroll") for (int _i = 0; _i < 2; ++_i) \
;         __builtin_amdgcn_global_load_lds((const unsigned*)((const char*)(gbase) + (voff)[_i]), (LAS unsigned*)(lds + (bufoff) + ldsw + _i * 8192), 16, 0, 0); } while (0)
; #define PG8_LDA(dst, b, h) do { _Pragma("unroll") for (int m = 0; m < 4; ++m) _Pragma("unroll") for (int k = 0; k < 2; ++k) dst[m][k] = *(const LAS bf16x8*)(lds + PG8_SA(b, h) + aoff + m * 2048 + k * 1024); } while (0)
; #define PG8_LDB(dst, b, h) do { _Pragma("unroll") for (int n = 0; n < 2; ++n) _Pragma("unroll") for (int k = 0; k < 2; ++k) dst[n][k] = *(const LAS bf16x8*)(lds + PG8_SB(b, h) + boff + n * 2048 + k * 1024); } while (0)
; #define PG8_WAIT_V(n) asm volatile("s_waitcnt vmcnt(" #n ")" ::: "memory")
; #define PG8_WAIT_L(n) asm volatile("s_waitcnt lgkmcnt(" #n ")" ::: "memory")
; #define PG8_BAR __builtin_amdgcn_s_barrier()
; #define PG8_SCHED __builtin_amdgcn_sched_barrier(0)
; template <class Epi>
; __device__ __forceinline__ void gemm_phase(LAS unsigned char* lds, const Gemm g, const StaticOrder& S, const Epi& E, const int tid) {
;     ...
;             const bool last = (t == ntt - 2);
;             const bool s1 = Epi::TWO && (t >= nt), s2 = Epi::TWO && (t + 2 >= nt);
;             const char* a1 = (s1 ? cA2 + (size_t)(t - nt + 1) * kstep : cA + (size_t)(t + 1) * kstep);
;             const char* a2 = last ? nA : (s2 ? cA2 + (size_t)(t + 2 - nt) * kstep : cA + (size_t)(t + 2) * kstep);
;             const char* b2 = last ? nB : (s2 ? cB2 + (size_t)(t + 2 - nt) * kstep : cB + (size_t)(t + 2) * kstep);
;             const char* a3 = a2 + kstep; const char* b3 = b2 + kstep;
;             if constexpr (Epi::TWO) { if (t == nt) E.mid(acc, cur, wr, wc, fr, fq); }
;             if constexpr (SP2) {
;             PG8_LDB(B0, 0, 0); PG8_LDB(B1, 0, 1); PG8_SCHED; PG8_LDA(At, 0, 0); PG8_STAGE(PG8_SA(1, 1), a1 + hstep, voffA);
;             PG8_WAIT_V(8); PG8_WAIT_L(0); PG8_BAR; PG8_MMA(0, 0, At, B0); PG8_MMA(0, 1, At, B1); PG8_BAR; PG8_SCHED;
;             PG8_LDA(At, 0, 1); PG8_STAGE(PG8_SB(0, 0), b2, voffB); PG8_STAGE(PG8_SB(0, 1), b2 + bhs, voffB); PG8_STAGE(PG8_SA(0, 0), a2, voffA);
;             PG8_WAIT_V(8); PG8_WAIT_L(0); PG8_BAR; PG8_MMA(1, 0, At, B0); PG8_MMA(1, 1, At, B1); PG8_BAR; PG8_SCHED;
.LBB0_261:
	s_add_u32 s30, s28, 0xfff80080
	s_addc_u32 s31, s29, -1
	s_add_i32 s49, 0, 0x10000
	s_cmp_eq_u32 s48, 28
	s_cselect_b32 s35, s19, s31
	s_cselect_b32 s34, s44, s30
	v_add_u32_e32 v142, s49, v149
	s_cselect_b32 s31, s17, s47
	s_cselect_b32 s30, s45, s46
	s_add_i32 s52, 0, 0x14000
	ds_read_b128 v[156:159], v142
	ds_read_b128 v[160:163], v142 offset:1024
	ds_read_b128 v[164:167], v142 offset:2048
	ds_read_b128 v[178:181], v142 offset:3072
	v_add_u32_e32 v142, s52, v149
	ds_read_b128 v[182:185], v142
	ds_read_b128 v[186:189], v142 offset:1024
	ds_read_b128 v[190:193], v142 offset:2048
	ds_read_b128 v[194:197], v142 offset:3072
	v_lshl_add_u64 v[142:143], s[28:29], 0, v[140:141]
	s_add_i32 m0, s2, 0xc000
	ds_read_b128 v[198:201], v154
	global_load_lds_dwordx4 v[142:143], off
	ds_read_b128 v[212:215], v154 offset:1024
	v_lshl_add_u64 v[142:143], s[28:29], 0, v[138:139]
	s_add_i32 m0, s2, 0xe000
	s_nop 0
	global_load_lds_dwordx4 v[142:143], off
	ds_read_b128 v[216:219], v154 offset:2048
	ds_read_b128 v[220:223], v154 offset:3072
	ds_read_b128 v[224:227], v154 offset:4096
	ds_read_b128 v[228:231], v154 offset:5120
	ds_read_b128 v[232:235], v154 offset:6144
	ds_read_b128 v[236:239], v154 offset:7168
	s_waitcnt vmcnt(8)
	s_waitcnt lgkmcnt(0)
	s_barrier
	s_setprio 1
	s_waitcnt lgkmcnt(0)
	v_mfma_f32_16x16x32_bf16 v[126:129], v[156:159], v[198:201], v[126:129]
	v_mfma_f32_16x16x32_bf16 v[122:125], v[164:167], v[198:201], v[122:125]
	v_mfma_f32_16x16x32_bf16 v[110:113], v[156:159], v[216:219], v[110:113]
	v_mfma_f32_16x16x32_bf16 v[106:109], v[164:167], v[216:219], v[106:109]
	v_mfma_f32_16x16x32_bf16 v[94:97], v[156:159], v[224:227], v[94:97]
	v_mfma_f32_16x16x32_bf16 v[90:93], v[164:167], v[224:227], v[90:93]
	v_mfma_f32_16x16x32_bf16 v[78:81], v[156:159], v[232:235], v[78:81]
	v_mfma_f32_16x16x32_bf16 v[74:77], v[164:167], v[232:235], v[74:77]
	v_mfma_f32_16x16x32_bf16 v[126:129], v[160:163], v[212:215], v[126:129]
	v_mfma_f32_16x16x32_bf16 v[122:125], v[178:181], v[212:215], v[122:125]
	v_mfma_f32_16x16x32_bf16 v[110:113], v[160:163], v[220:223], v[110:113]
	v_mfma_f32_16x16x32_bf16 v[106:109], v[178:181], v[220:223], v[106:109]
	v_mfma_f32_16x16x32_bf16 v[94:97], v[160:163], v[228:231], v[94:97]
	v_mfma_f32_16x16x32_bf16 v[90:93], v[178:181], v[228:231], v[90:93]
	v_mfma_f32_16x16x32_bf16 v[78:81], v[160:163], v[236:239], v[78:81]
	v_mfma_f32_16x16x32_bf16 v[74:77], v[178:181], v[236:239], v[74:77]
	s_setprio 0
	s_setprio 1
	v_mfma_f32_16x16x32_bf16 v[118:121], v[182:185], v[198:201], v[118:121]
	v_mfma_f32_16x16x32_bf16 v[114:117], v[190:193], v[198:201], v[114:117]
	v_mfma_f32_16x16x32_bf16 v[102:105], v[182:185], v[216:219], v[102:105]
	v_mfma_f32_16x16x32_bf16 v[98:101], v[190:193], v[216:219], v[98:101]
	v_mfma_f32_16x16x32_bf16 v[86:89], v[182:185], v[224:227], v[86:89]
	v_mfma_f32_16x16x32_bf16 v[82:85], v[190:193], v[224:227], v[82:85]
	v_mfma_f32_16x16x32_bf16 v[70:73], v[182:185], v[232:235], v[70:73]
	v_mfma_f32_16x16x32_bf16 v[66:69], v[190:193], v[232:235], v[66:69]
	v_mfma_f32_16x16x32_bf16 v[118:121], v[186:189], v[212:215], v[118:121]
	v_mfma_f32_16x16x32_bf16 v[114:117], v[194:197], v[212:215], v[114:117]
	v_mfma_f32_16x16x32_bf16 v[102:105], v[186:189], v[220:223], v[102:105]
	v_mfma_f32_16x16x32_bf16 v[98:101], v[194:197], v[220:223], v[98:101]
	v_mfma_f32_16x16x32_bf16 v[86:89], v[186:189], v[228:231], v[86:89]
	v_mfma_f32_16x16x32_bf16 v[82:85], v[194:197], v[228:231], v[82:85]
	v_mfma_f32_16x16x32_bf16 v[70:73], v[186:189], v[236:239], v[70:73]
	v_mfma_f32_16x16x32_bf16 v[66:69], v[194:197], v[236:239], v[66:69]
	s_setprio 0
	s_barrier
	s_add_i32 s49, s49, s36
	v_lshl_add_u64 v[142:143], s[30:31], 0, v[0:1]
	s_mov_b32 m0, s49
	ds_read_b128 v[198:201], v154 offset:16384
	global_load_lds_dwordx4 v[142:143], off
	ds_read_b128 v[212:215], v154 offset:17408
	s_add_i32 m0, s49, 0x2000
	s_add_u32 s50, s30, 0x8000
	v_lshl_add_u64 v[168:169], s[30:31], 0, v[134:135]
	s_addc_u32 s51, s31, 0
	s_add_i32 s49, s52, s36
	global_load_lds_dwordx4 v[168:169], off
	ds_read_b128 v[216:219], v154 offset:18432
	v_lshl_add_u64 v[172:173], s[50:51], 0, v[0:1]
	s_mov_b32 m0, s49
	v_lshl_add_u64 v[174:175], s[34:35], 0, v[132:133]
	global_load_lds_dwordx4 v[172:173], off
	ds_read_b128 v[220:223], v154 offset:19456
	v_lshl_add_u64 v[172:173], s[50:51], 0, v[134:135]
	s_add_i32 m0, s49, 0x2000
	s_nop 0
	global_load_lds_dwordx4 v[172:173], off
	ds_read_b128 v[224:227], v154 offset:20480
	v_lshl_add_u64 v[172:173], s[34:35], 0, v[130:131]
	s_mov_b32 m0, s2
	s_nop 0
	global_load_lds_dwordx4 v[172:173], off
	ds_read_b128 v[228:231], v154 offset:21504
	s_mov_b32 m0, s27
	s_nop 0
	global_load_lds_dwordx4 v[174:175], off
	ds_read_b128 v[232:235], v154 offset:22528
	ds_read_b128 v[236:239], v154 offset:23552
	s_waitcnt vmcnt(8)
	s_waitcnt lgkmcnt(0)
	s_barrier
; #define PG8_STAGE(bufoff, gbase, voff) do { _Pragma("unroll") for (int _i = 0; _i < 2; ++_i) \
;         __builtin_amdgcn_global_load_lds((const unsigned*)((const char*)(gbase) + (voff)[_i]), (LAS unsigned*)(lds + (bufoff) + ldsw + _i * 8192), 16, 0, 0); } while (0)
; #define PG8_LDA(dst, b, h) do { _Pragma("unroll") for (int m = 0; m < 4; ++m) _Pragma("unroll") for (int k = 0; k < 2; ++k) dst[m][k] = *(const LAS bf16x8*)(lds + PG8_SA(b, h) + aoff + m * 2048 + k * 1024); } while (0)
; #define PG8_LDB(dst, b, h) do { _Pragma("unroll") for (int n = 0; n < 2; ++n) _Pragma("unroll") for (int k = 0; k < 2; ++k) dst[n][k] = *(const LAS bf16x8*)(lds + PG8_SB(b, h) + boff + n * 2048 + k * 1024); } while (0)
; #define PG8_MMA(ai, bj, At, Bt) do { __builtin_amdgcn_s_setprio(1); _Pragma("unroll") for (int m = 0; m < 4; ++m) _Pragma("unroll") for (int n = 0; n < 2; ++n) _Pragma("unroll") for (int k = 0; k < 2; ++k) \
;         acc[ai][bj][m][n] = __builtin_amdgcn_mfma_f32_16x16x32_bf16(Bt[n][k], At[m][k], acc[ai][bj][m][n], 0, 0, 0); __builtin_amdgcn_s_setprio(0); } while (0)
; #define PG8_WAIT_V(n) asm volatile("s_waitcnt vmcnt(" #n ")" ::: "memory")
; #define PG8_WAIT_L(n) asm volatile("s_waitcnt lgkmcnt(" #n ")" ::: "memory")
; #define PG8_BAR __builtin_amdgcn_s_barrier()
; #define PG8_SCHED __builtin_amdgcn_sched_barrier(0)
; template <class Epi>
; __device__ __forceinline__ void gemm_phase(LAS unsigned char* lds, const Gemm g, const StaticOrder& S, const Epi& E, const int tid) {
;     ...
;             PG8_WAIT_V(8); PG8_WAIT_L(0); PG8_BAR; PG8_MMA(1, 0, At, B0); PG8_MMA(1, 1, At, B1); PG8_BAR; PG8_SCHED;
;             PG8_LDB(B0, 1, 0); PG8_LDB(B1, 1, 1); PG8_SCHED; PG8_LDA(At, 1, 0); PG8_STAGE(PG8_SA(0, 1), a2 + hstep, voffA);
;             PG8_WAIT_V(8); PG8_WAIT_L(0); PG8_BAR; PG8_MMA(0, 0, At, B0); PG8_MMA(0, 1, At, B1); PG8_BAR; PG8_SCHED;
	s_setprio 1
	s_waitcnt lgkmcnt(0)
	v_mfma_f32_16x16x32_bf16 v[62:65], v[156:159], v[198:201], v[62:65]
	v_mfma_f32_16x16x32_bf16 v[58:61], v[164:167], v[198:201], v[58:61]
	v_mfma_f32_16x16x32_bf16 v[46:49], v[156:159], v[216:219], v[46:49]
	v_mfma_f32_16x16x32_bf16 v[42:45], v[164:167], v[216:219], v[42:45]
	v_mfma_f32_16x16x32_bf16 v[30:33], v[156:159], v[224:227], v[30:33]
	v_mfma_f32_16x16x32_bf16 v[26:29], v[164:167], v[224:227], v[26:29]
	v_mfma_f32_16x16x32_bf16 v[14:17], v[156:159], v[232:235], v[14:17]
	v_mfma_f32_16x16x32_bf16 v[10:13], v[164:167], v[232:235], v[10:13]
	v_mfma_f32_16x16x32_bf16 v[62:65], v[160:163], v[212:215], v[62:65]
	v_mfma_f32_16x16x32_bf16 v[58:61], v[178:181], v[212:215], v[58:61]
	v_mfma_f32_16x16x32_bf16 v[46:49], v[160:163], v[220:223], v[46:49]
	v_mfma_f32_16x16x32_bf16 v[42:45], v[178:181], v[220:223], v[42:45]
	v_mfma_f32_16x16x32_bf16 v[30:33], v[160:163], v[228:231], v[30:33]
	v_mfma_f32_16x16x32_bf16 v[26:29], v[178:181], v[228:231], v[26:29]
	v_mfma_f32_16x16x32_bf16 v[14:17], v[160:163], v[236:239], v[14:17]
	v_mfma_f32_16x16x32_bf16 v[10:13], v[178:181], v[236:239], v[10:13]
	s_setprio 0
	s_setprio 1
	v_mfma_f32_16x16x32_bf16 v[54:57], v[182:185], v[198:201], v[54:57]
	v_mfma_f32_16x16x32_bf16 v[50:53], v[190:193], v[198:201], v[50:53]
	v_mfma_f32_16x16x32_bf16 v[38:41], v[182:185], v[216:219], v[38:41]
	v_mfma_f32_16x16x32_bf16 v[34:37], v[190:193], v[216:219], v[34:37]
	v_mfma_f32_16x16x32_bf16 v[22:25], v[182:185], v[224:227], v[22:25]
	v_mfma_f32_16x16x32_bf16 v[18:21], v[190:193], v[224:227], v[18:21]
	v_mfma_f32_16x16x32_bf16 v[6:9], v[182:185], v[232:235], v[6:9]
	v_mfma_f32_16x16x32_bf16 v[2:5], v[190:193], v[232:235], v[2:5]
	v_mfma_f32_16x16x32_bf16 v[54:57], v[186:189], v[212:215], v[54:57]
	v_mfma_f32_16x16x32_bf16 v[50:53], v[194:197], v[212:215], v[50:53]
	v_mfma_f32_16x16x32_bf16 v[38:41], v[186:189], v[220:223], v[38:41]
	v_mfma_f32_16x16x32_bf16 v[34:37], v[194:197], v[220:223], v[34:37]
	v_mfma_f32_16x16x32_bf16 v[22:25], v[186:189], v[228:231], v[22:25]
	v_mfma_f32_16x16x32_bf16 v[18:21], v[194:197], v[228:231], v[18:21]
	v_mfma_f32_16x16x32_bf16 v[6:9], v[186:189], v[236:239], v[6:9]
	v_mfma_f32_16x16x32_bf16 v[2:5], v[194:197], v[236:239], v[2:5]
	s_setprio 0
	s_barrier
	s_add_i32 s49, 0, 0x18000
	v_add_u32_e32 v155, s49, v149
	s_add_i32 s50, 0, 0x1c000
	ds_read_b128 v[156:159], v155
	ds_read_b128 v[160:163], v155 offset:1024
	ds_read_b128 v[164:167], v155 offset:2048
	ds_read_b128 v[178:181], v155 offset:3072
	v_add_u32_e32 v155, s50, v149
	ds_read_b128 v[182:185], v155
	ds_read_b128 v[186:189], v155 offset:1024
	ds_read_b128 v[190:193], v155 offset:2048
	ds_read_b128 v[194:197], v155 offset:3072
	s_add_u32 s34, s34, 0x80000
	s_addc_u32 s35, s35, 0
	s_mov_b32 m0, s37
	v_lshl_add_u64 v[176:177], s[34:35], 0, v[130:131]
	ds_read_b128 v[198:201], v154 offset:32768
	global_load_lds_dwordx4 v[176:177], off
	ds_read_b128 v[212:215], v154 offset:33792
	v_lshl_add_u64 v[176:177], s[34:35], 0, v[132:133]
	s_mov_b32 m0, s38
	s_nop 0
	global_load_lds_dwordx4 v[176:177], off
	ds_read_b128 v[216:219], v154 offset:34816
	ds_read_b128 v[220:223], v154 offset:35840
	ds_read_b128 v[224:227], v154 offset:36864
	ds_read_b128 v[228:231], v154 offset:37888
	ds_read_b128 v[232:235], v154 offset:38912
	ds_read_b128 v[236:239], v154 offset:39936
	s_waitcnt vmcnt(8)
	s_waitcnt lgkmcnt(0)
	s_barrier
	s_setprio 1
	s_waitcnt lgkmcnt(0)
	v_mfma_f32_16x16x32_bf16 v[126:129], v[156:159], v[198:201], v[126:129]
	v_mfma_f32_16x16x32_bf16 v[122:125], v[164:167], v[198:201], v[122:125]
	v_mfma_f32_16x16x32_bf16 v[110:113], v[156:159], v[216:219], v[110:113]
	v_mfma_f32_16x16x32_bf16 v[106:109], v[164:167], v[216:219], v[106:109]
	v_mfma_f32_16x16x32_bf16 v[94:97], v[156:159], v[224:227], v[94:97]
	v_mfma_f32_16x16x32_bf16 v[90:93], v[164:167], v[224:227], v[90:93]
	v_mfma_f32_16x16x32_bf16 v[78:81], v[156:159], v[232:235], v[78:81]
	v_mfma_f32_16x16x32_bf16 v[74:77], v[164:167], v[232:235], v[74:77]
	v_mfma_f32_16x16x32_bf16 v[126:129], v[160:163], v[212:215], v[126:129]
	v_mfma_f32_16x16x32_bf16 v[122:125], v[178:181], v[212:215], v[122:125]
	v_mfma_f32_16x16x32_bf16 v[110:113], v[160:163], v[220:223], v[110:113]
	v_mfma_f32_16x16x32_bf16 v[106:109], v[178:181], v[220:223], v[106:109]
	v_mfma_f32_16x16x32_bf16 v[94:97], v[160:163], v[228:231], v[94:97]
	v_mfma_f32_16x16x32_bf16 v[90:93], v[178:181], v[228:231], v[90:93]
	v_mfma_f32_16x16x32_bf16 v[78:81], v[160:163], v[236:239], v[78:81]
	v_mfma_f32_16x16x32_bf16 v[74:77], v[178:181], v[236:239], v[74:77]
	s_setprio 0
	s_setprio 1
	v_mfma_f32_16x16x32_bf16 v[118:121], v[182:185], v[198:201], v[118:121]
	v_mfma_f32_16x16x32_bf16 v[114:117], v[190:193], v[198:201], v[114:117]
	v_mfma_f32_16x16x32_bf16 v[102:105], v[182:185], v[216:219], v[102:105]
	v_mfma_f32_16x16x32_bf16 v[98:101], v[190:193], v[216:219], v[98:101]
	v_mfma_f32_16x16x32_bf16 v[86:89], v[182:185], v[224:227], v[86:89]
	v_mfma_f32_16x16x32_bf16 v[82:85], v[190:193], v[224:227], v[82:85]
	v_mfma_f32_16x16x32_bf16 v[70:73], v[182:185], v[232:235], v[70:73]
	v_mfma_f32_16x16x32_bf16 v[66:69], v[190:193], v[232:235], v[66:69]
	v_mfma_f32_16x16x32_bf16 v[118:121], v[186:189], v[212:215], v[118:121]
	v_mfma_f32_16x16x32_bf16 v[114:117], v[194:197], v[212:215], v[114:117]
	v_mfma_f32_16x16x32_bf16 v[102:105], v[186:189], v[220:223], v[102:105]
	v_mfma_f32_16x16x32_bf16 v[98:101], v[194:197], v[220:223], v[98:101]
	v_mfma_f32_16x16x32_bf16 v[86:89], v[186:189], v[228:231], v[86:89]
	v_mfma_f32_16x16x32_bf16 v[82:85], v[194:197], v[228:231], v[82:85]
	v_mfma_f32_16x16x32_bf16 v[70:73], v[186:189], v[236:239], v[70:73]
	v_mfma_f32_16x16x32_bf16 v[66:69], v[194:197], v[236:239], v[66:69]
	s_setprio 0
	s_barrier
; #define PG8_STAGE(bufoff, gbase, voff) do { _Pragma("unroll") for (int _i = 0; _i < 2; ++_i) \
;         __builtin_amdgcn_global_load_lds((const unsigned*)((const char*)(gbase) + (voff)[_i]), (LAS unsigned*)(lds + (bufoff) + ldsw + _i * 8192), 16, 0, 0); } while (0)
; #define PG8_LDA(dst, b, h) do { _Pragma("unroll") for (int m = 0; m < 4; ++m) _Pragma("unroll") for (int k = 0; k < 2; ++k) dst[m][k] = *(const LAS bf16x8*)(lds + PG8_SA(b, h) + aoff + m * 2048 + k * 1024); } while (0)
; #define PG8_MMA(ai, bj, At, Bt) do { __builtin_amdgcn_s_setprio(1); _Pragma("unroll") for (int m = 0; m < 4; ++m) _Pragma("unroll") for (int n = 0; n < 2; ++n) _Pragma("unroll") for (int k = 0; k < 2; ++k) \
;         acc[ai][bj][m][n] = __builtin_amdgcn_mfma_f32_16x16x32_bf16(Bt[n][k], At[m][k], acc[ai][bj][m][n], 0, 0, 0); __builtin_amdgcn_s_setprio(0); } while (0)
; #define PG8_WAIT_V(n) asm volatile("s_waitcnt vmcnt(" #n ")" ::: "memory")
; #define PG8_WAIT_L(n) asm volatile("s_waitcnt lgkmcnt(" #n ")" ::: "memory")
; #define PG8_BAR __builtin_amdgcn_s_barrier()
; #define PG8_SCHED __builtin_amdgcn_sched_barrier(0)
; template <class Epi>
; __device__ __forceinline__ void gemm_phase(LAS unsigned char* lds, const Gemm g, const StaticOrder& S, const Epi& E, const int tid) {
;     ...
;             PG8_LDA(At, 1, 1); PG8_STAGE(PG8_SB(1, 0), b3, voffB); PG8_STAGE(PG8_SB(1, 1), b3 + bhs, voffB); PG8_STAGE(PG8_SA(1, 0), a3, voffA);
;             PG8_WAIT_V(8); PG8_WAIT_L(0); PG8_BAR; PG8_MMA(1, 0, At, B0); PG8_MMA(1, 1, At, B1); PG8_BAR; PG8_SCHED;
;     ...
;         if (ALIGN_EPI) { if (wr == 0) PG8_BAR; }
	s_add_i32 s34, s49, s36
	v_lshl_add_u64 v[142:143], v[142:143], 0, s[70:71]
	s_mov_b32 m0, s34
	ds_read_b128 v[198:201], v154 offset:49152
	global_load_lds_dwordx4 v[142:143], off
	ds_read_b128 v[212:215], v154 offset:50176
	s_add_i32 m0, s34, 0x2000
	s_add_u32 s30, s30, 0x8080
	v_lshl_add_u64 v[142:143], v[168:169], 0, s[70:71]
	s_addc_u32 s31, s31, 0
	s_add_i32 s34, s50, s36
	global_load_lds_dwordx4 v[142:143], off
	ds_read_b128 v[216:219], v154 offset:51200
	v_lshl_add_u64 v[142:143], s[30:31], 0, v[0:1]
	s_mov_b32 m0, s34
	s_nop 0
	global_load_lds_dwordx4 v[142:143], off
	ds_read_b128 v[220:223], v154 offset:52224
	v_lshl_add_u64 v[142:143], s[30:31], 0, v[134:135]
	s_add_i32 m0, s34, 0x2000
	s_nop 0
	global_load_lds_dwordx4 v[142:143], off
	ds_read_b128 v[224:227], v154 offset:53248
	v_lshl_add_u64 v[142:143], v[172:173], 0, s[70:71]
	s_mov_b32 m0, s39
	s_nop 0
	global_load_lds_dwordx4 v[142:143], off
	ds_read_b128 v[228:231], v154 offset:54272
	v_lshl_add_u64 v[142:143], v[174:175], 0, s[70:71]
	s_mov_b32 m0, s40
	s_nop 0
	global_load_lds_dwordx4 v[142:143], off
	ds_read_b128 v[232:235], v154 offset:55296
	ds_read_b128 v[236:239], v154 offset:56320
	s_waitcnt vmcnt(8)
	s_waitcnt lgkmcnt(0)
	s_barrier
	s_setprio 1
	s_waitcnt lgkmcnt(0)
	v_mfma_f32_16x16x32_bf16 v[62:65], v[156:159], v[198:201], v[62:65]
	v_mfma_f32_16x16x32_bf16 v[58:61], v[164:167], v[198:201], v[58:61]
	v_mfma_f32_16x16x32_bf16 v[46:49], v[156:159], v[216:219], v[46:49]
	v_mfma_f32_16x16x32_bf16 v[42:45], v[164:167], v[216:219], v[42:45]
	v_mfma_f32_16x16x32_bf16 v[30:33], v[156:159], v[224:227], v[30:33]
	v_mfma_f32_16x16x32_bf16 v[26:29], v[164:167], v[224:227], v[26:29]
	v_mfma_f32_16x16x32_bf16 v[14:17], v[156:159], v[232:235], v[14:17]
	v_mfma_f32_16x16x32_bf16 v[10:13], v[164:167], v[232:235], v[10:13]
	v_mfma_f32_16x16x32_bf16 v[62:65], v[160:163], v[212:215], v[62:65]
	v_mfma_f32_16x16x32_bf16 v[58:61], v[178:181], v[212:215], v[58:61]
	v_mfma_f32_16x16x32_bf16 v[46:49], v[160:163], v[220:223], v[46:49]
	v_mfma_f32_16x16x32_bf16 v[42:45], v[178:181], v[220:223], v[42:45]
	v_mfma_f32_16x16x32_bf16 v[30:33], v[160:163], v[228:231], v[30:33]
	v_mfma_f32_16x16x32_bf16 v[26:29], v[178:181], v[228:231], v[26:29]
	v_mfma_f32_16x16x32_bf16 v[14:17], v[160:163], v[236:239], v[14:17]
	v_mfma_f32_16x16x32_bf16 v[10:13], v[178:181], v[236:239], v[10:13]
	s_setprio 0
	s_setprio 1
	v_mfma_f32_16x16x32_bf16 v[54:57], v[182:185], v[198:201], v[54:57]
	v_mfma_f32_16x16x32_bf16 v[50:53], v[190:193], v[198:201], v[50:53]
	v_mfma_f32_16x16x32_bf16 v[38:41], v[182:185], v[216:219], v[38:41]
	v_mfma_f32_16x16x32_bf16 v[34:37], v[190:193], v[216:219], v[34:37]
	v_mfma_f32_16x16x32_bf16 v[22:25], v[182:185], v[224:227], v[22:25]
	v_mfma_f32_16x16x32_bf16 v[18:21], v[190:193], v[224:227], v[18:21]
	v_mfma_f32_16x16x32_bf16 v[6:9], v[182:185], v[232:235], v[6:9]
	v_mfma_f32_16x16x32_bf16 v[2:5], v[190:193], v[232:235], v[2:5]
	v_mfma_f32_16x16x32_bf16 v[54:57], v[186:189], v[212:215], v[54:57]
	v_mfma_f32_16x16x32_bf16 v[50:53], v[194:197], v[212:215], v[50:53]
	v_mfma_f32_16x16x32_bf16 v[38:41], v[186:189], v[220:223], v[38:41]
	v_mfma_f32_16x16x32_bf16 v[34:37], v[194:197], v[220:223], v[34:37]
	v_mfma_f32_16x16x32_bf16 v[22:25], v[186:189], v[228:231], v[22:25]
	v_mfma_f32_16x16x32_bf16 v[18:21], v[194:197], v[228:231], v[18:21]
	v_mfma_f32_16x16x32_bf16 v[6:9], v[186:189], v[236:239], v[6:9]
	v_mfma_f32_16x16x32_bf16 v[2:5], v[194:197], v[236:239], v[2:5]
	s_setprio 0
	s_barrier
	s_add_i32 s48, s48, 2
	s_add_u32 s46, s46, 0x100
	s_addc_u32 s47, s47, 0
	s_add_u32 s28, s28, 0x100
	s_addc_u32 s29, s29, 0
	s_cmp_gt_u32 s48, 29
	s_cbranch_scc0 .LBB0_261
	s_and_b64 vcc, exec, s[14:15]
	s_cbranch_vccz .LBB0_264
	s_barrier

; #define PG8_STAGE(bufoff, gbase, voff) do { _Pragma("unroll") for (int _i = 0; _i < 2; ++_i) \
;         __builtin_amdgcn_global_load_lds((const unsigned*)((const char*)(gbase) + (voff)[_i]), (LAS unsigned*)(lds + (bufoff) + ldsw + _i * 8192), 16, 0, 0); } while (0)
; #define PG8_LDA(dst, b, h) do { _Pragma("unroll") for (int m = 0; m < 4; ++m) _Pragma("unroll") for (int k = 0; k < 2; ++k) dst[m][k] = *(const LAS bf16x8*)(lds + PG8_SA(b, h) + aoff + m * 2048 + k * 1024); } while (0)
; #define PG8_LDB(dst, b, h) do { _Pragma("unroll") for (int n = 0; n < 2; ++n) _Pragma("unroll") for (int k = 0; k < 2; ++k) dst[n][k] = *(const LAS bf16x8*)(lds + PG8_SB(b, h) + boff + n * 2048 + k * 1024); } while (0)
; #define PG8_WAIT_V(n) asm volatile("s_waitcnt vmcnt(" #n ")" ::: "memory")
; #define PG8_WAIT_L(n) asm volatile("s_waitcnt lgkmcnt(" #n ")" ::: "memory")
; #define PG8_BAR __builtin_amdgcn_s_barrier()
; #define PG8_SCHED __builtin_amdgcn_sched_barrier(0)
; template <class Epi>
; __device__ __forceinline__ void gemm_phase(LAS unsigned char* lds, const Gemm g, const StaticOrder& S, const Epi& E, const int tid) {
;     ...
;             const bool last = (t == ntt - 2);
;             const bool s1 = Epi::TWO && (t >= nt), s2 = Epi::TWO && (t + 2 >= nt);
;             const char* a1 = (s1 ? cA2 + (size_t)(t - nt + 1) * kstep : cA + (size_t)(t + 1) * kstep);
;             const char* a2 = last ? nA : (s2 ? cA2 + (size_t)(t + 2 - nt) * kstep : cA + (size_t)(t + 2) * kstep);
;             const char* b2 = last ? nB : (s2 ? cB2 + (size_t)(t + 2 - nt) * kstep : cB + (size_t)(t + 2) * kstep);
;             const char* a3 = a2 + kstep; const char* b3 = b2 + kstep;
;             if constexpr (Epi::TWO) { if (t == nt) E.mid(acc, cur, wr, wc, fr, fq); }
;             if constexpr (SP2) {
;             PG8_LDB(B0, 0, 0); PG8_LDB(B1, 0, 1); PG8_SCHED; PG8_LDA(At, 0, 0); PG8_STAGE(PG8_SA(1, 1), a1 + hstep, voffA);
;             PG8_WAIT_V(8); PG8_WAIT_L(0); PG8_BAR; PG8_MMA(0, 0, At, B0); PG8_MMA(0, 1, At, B1); PG8_BAR; PG8_SCHED;
;             PG8_LDA(At, 0, 1); PG8_STAGE(PG8_SB(0, 0), b2, voffB); PG8_STAGE(PG8_SB(0, 1), b2 + bhs, voffB); PG8_STAGE(PG8_SA(0, 0), a2, voffA);
;             PG8_WAIT_V(8); PG8_WAIT_L(0); PG8_BAR; PG8_MMA(1, 0, At, B0); PG8_MMA(1, 1, At, B1); PG8_BAR; PG8_SCHED;
.LBB0_314:
	s_add_u32 s40, s6, 0xfff80080
	s_addc_u32 s41, s7, -1
	s_add_i32 s56, 0, 0x10000
	s_cmp_eq_u32 s55, 28
	s_cselect_b32 s43, s27, s41
	s_cselect_b32 s42, s39, s40
	s_cselect_b32 s41, s25, s54
	s_cselect_b32 s40, s52, s53
	s_add_i32 s58, 0, 0x14000
	v_add_u32_e32 v46, s56, v212
	v_add_u32_e32 v70, s58, v212
	ds_read_b128 v[34:37], v46
	ds_read_b128 v[38:41], v46 offset:1024
	ds_read_b128 v[42:45], v46 offset:2048
	ds_read_b128 v[46:49], v46 offset:3072
	ds_read_b128 v[58:61], v70
	ds_read_b128 v[62:65], v70 offset:1024
	ds_read_b128 v[66:69], v70 offset:2048
	ds_read_b128 v[70:73], v70 offset:3072
	v_lshl_add_u64 v[172:173], s[6:7], 0, v[188:189]
	s_add_i32 m0, s44, 0xc000
	ds_read_b128 v[162:165], v220
	global_load_lds_dwordx4 v[172:173], off
	ds_read_b128 v[166:169], v220 offset:1024
	v_lshl_add_u64 v[172:173], s[6:7], 0, v[186:187]
	s_add_i32 m0, s44, 0xe000
	s_nop 0
	global_load_lds_dwordx4 v[172:173], off
	ds_read_b128 v[190:193], v220 offset:2048
	ds_read_b128 v[194:197], v220 offset:3072
	ds_read_b128 v[198:201], v220 offset:4096
	ds_read_b128 v[222:225], v220 offset:5120
	ds_read_b128 v[226:229], v220 offset:6144
	ds_read_b128 v[230:233], v220 offset:7168
	s_waitcnt vmcnt(8)
	s_waitcnt lgkmcnt(0)
	s_barrier
	s_setprio 1
	s_waitcnt lgkmcnt(0)
	v_mfma_f32_16x16x32_bf16 v[158:161], v[34:37], v[162:165], v[158:161]
	v_mfma_f32_16x16x32_bf16 v[154:157], v[42:45], v[162:165], v[154:157]
	v_mfma_f32_16x16x32_bf16 v[142:145], v[34:37], v[190:193], v[142:145]
	v_mfma_f32_16x16x32_bf16 v[138:141], v[42:45], v[190:193], v[138:141]
	v_mfma_f32_16x16x32_bf16 v[126:129], v[34:37], v[198:201], v[126:129]
	v_mfma_f32_16x16x32_bf16 v[122:125], v[42:45], v[198:201], v[122:125]
	v_mfma_f32_16x16x32_bf16 v[110:113], v[34:37], v[226:229], v[110:113]
	v_mfma_f32_16x16x32_bf16 v[106:109], v[42:45], v[226:229], v[106:109]
	v_mfma_f32_16x16x32_bf16 v[158:161], v[38:41], v[166:169], v[158:161]
	v_mfma_f32_16x16x32_bf16 v[154:157], v[46:49], v[166:169], v[154:157]
	v_mfma_f32_16x16x32_bf16 v[142:145], v[38:41], v[194:197], v[142:145]
	v_mfma_f32_16x16x32_bf16 v[138:141], v[46:49], v[194:197], v[138:141]
	v_mfma_f32_16x16x32_bf16 v[126:129], v[38:41], v[222:225], v[126:129]
	v_mfma_f32_16x16x32_bf16 v[122:125], v[46:49], v[222:225], v[122:125]
	v_mfma_f32_16x16x32_bf16 v[110:113], v[38:41], v[230:233], v[110:113]
	v_mfma_f32_16x16x32_bf16 v[106:109], v[46:49], v[230:233], v[106:109]
	s_setprio 0
	s_setprio 1
	v_mfma_f32_16x16x32_bf16 v[150:153], v[58:61], v[162:165], v[150:153]
	v_mfma_f32_16x16x32_bf16 v[146:149], v[66:69], v[162:165], v[146:149]
	v_mfma_f32_16x16x32_bf16 v[134:137], v[58:61], v[190:193], v[134:137]
	v_mfma_f32_16x16x32_bf16 v[130:133], v[66:69], v[190:193], v[130:133]
	v_mfma_f32_16x16x32_bf16 v[118:121], v[58:61], v[198:201], v[118:121]
	v_mfma_f32_16x16x32_bf16 v[114:117], v[66:69], v[198:201], v[114:117]
	v_mfma_f32_16x16x32_bf16 v[102:105], v[58:61], v[226:229], v[102:105]
	v_mfma_f32_16x16x32_bf16 v[98:101], v[66:69], v[226:229], v[98:101]
	v_mfma_f32_16x16x32_bf16 v[150:153], v[62:65], v[166:169], v[150:153]
	v_mfma_f32_16x16x32_bf16 v[146:149], v[70:73], v[166:169], v[146:149]
	v_mfma_f32_16x16x32_bf16 v[134:137], v[62:65], v[194:197], v[134:137]
	v_mfma_f32_16x16x32_bf16 v[130:133], v[70:73], v[194:197], v[130:133]
	v_mfma_f32_16x16x32_bf16 v[118:121], v[62:65], v[222:225], v[118:121]
	v_mfma_f32_16x16x32_bf16 v[114:117], v[70:73], v[222:225], v[114:117]
	v_mfma_f32_16x16x32_bf16 v[102:105], v[62:65], v[230:233], v[102:105]
	v_mfma_f32_16x16x32_bf16 v[98:101], v[70:73], v[230:233], v[98:101]
	s_setprio 0
	s_barrier
	s_add_i32 s56, s56, s33
	v_lshl_add_u64 v[172:173], s[40:41], 0, v[0:1]
	s_mov_b32 m0, s56
	ds_read_b128 v[162:165], v220 offset:16384
	global_load_lds_dwordx4 v[172:173], off
	ds_read_b128 v[166:169], v220 offset:17408
	s_add_i32 m0, s56, 0x2000
	s_add_u32 s56, s40, 0x8000
	v_lshl_add_u64 v[174:175], s[40:41], 0, v[182:183]
	s_addc_u32 s57, s41, 0
	s_add_i32 s58, s58, s33
	global_load_lds_dwordx4 v[174:175], off
	ds_read_b128 v[190:193], v220 offset:18432
	v_lshl_add_u64 v[176:177], s[56:57], 0, v[0:1]
	s_mov_b32 m0, s58
	v_lshl_add_u64 v[238:239], s[42:43], 0, v[180:181]
	global_load_lds_dwordx4 v[176:177], off
	ds_read_b128 v[194:197], v220 offset:19456
	v_lshl_add_u64 v[176:177], s[56:57], 0, v[182:183]
	s_add_i32 m0, s58, 0x2000
	s_nop 0
	global_load_lds_dwordx4 v[176:177], off
	ds_read_b128 v[198:201], v220 offset:20480
	v_lshl_add_u64 v[176:177], s[42:43], 0, v[178:179]
	s_mov_b32 m0, s44
	s_nop 0
	global_load_lds_dwordx4 v[176:177], off
	ds_read_b128 v[222:225], v220 offset:21504
	s_mov_b32 m0, s45
	s_nop 0
	global_load_lds_dwordx4 v[238:239], off
	ds_read_b128 v[226:229], v220 offset:22528
	ds_read_b128 v[230:233], v220 offset:23552
	s_waitcnt vmcnt(8)
	s_waitcnt lgkmcnt(0)
	s_barrier
; #define PG8_STAGE(bufoff, gbase, voff) do { _Pragma("unroll") for (int _i = 0; _i < 2; ++_i) \
;         __builtin_amdgcn_global_load_lds((const unsigned*)((const char*)(gbase) + (voff)[_i]), (LAS unsigned*)(lds + (bufoff) + ldsw + _i * 8192), 16, 0, 0); } while (0)
; #define PG8_LDA(dst, b, h) do { _Pragma("unroll") for (int m = 0; m < 4; ++m) _Pragma("unroll") for (int k = 0; k < 2; ++k) dst[m][k] = *(const LAS bf16x8*)(lds + PG8_SA(b, h) + aoff + m * 2048 + k * 1024); } while (0)
; #define PG8_LDB(dst, b, h) do { _Pragma("unroll") for (int n = 0; n < 2; ++n) _Pragma("unroll") for (int k = 0; k < 2; ++k) dst[n][k] = *(const LAS bf16x8*)(lds + PG8_SB(b, h) + boff + n * 2048 + k * 1024); } while (0)
; #define PG8_MMA(ai, bj, At, Bt) do { __builtin_amdgcn_s_setprio(1); _Pragma("unroll") for (int m = 0; m < 4; ++m) _Pragma("unroll") for (int n = 0; n < 2; ++n) _Pragma("unroll") for (int k = 0; k < 2; ++k) \
;         acc[ai][bj][m][n] = __builtin_amdgcn_mfma_f32_16x16x32_bf16(Bt[n][k], At[m][k], acc[ai][bj][m][n], 0, 0, 0); __builtin_amdgcn_s_setprio(0); } while (0)
; #define PG8_WAIT_V(n) asm volatile("s_waitcnt vmcnt(" #n ")" ::: "memory")
; #define PG8_WAIT_L(n) asm volatile("s_waitcnt lgkmcnt(" #n ")" ::: "memory")
; #define PG8_BAR __builtin_amdgcn_s_barrier()
; #define PG8_SCHED __builtin_amdgcn_sched_barrier(0)
; template <class Epi>
; __device__ __forceinline__ void gemm_phase(LAS unsigned char* lds, const Gemm g, const StaticOrder& S, const Epi& E, const int tid) {
;     ...
;             PG8_WAIT_V(8); PG8_WAIT_L(0); PG8_BAR; PG8_MMA(1, 0, At, B0); PG8_MMA(1, 1, At, B1); PG8_BAR; PG8_SCHED;
;             PG8_LDB(B0, 1, 0); PG8_LDB(B1, 1, 1); PG8_SCHED; PG8_LDA(At, 1, 0); PG8_STAGE(PG8_SA(0, 1), a2 + hstep, voffA);
;             PG8_WAIT_V(8); PG8_WAIT_L(0); PG8_BAR; PG8_MMA(0, 0, At, B0); PG8_MMA(0, 1, At, B1); PG8_BAR; PG8_SCHED;
	s_setprio 1
	s_waitcnt lgkmcnt(0)
	v_mfma_f32_16x16x32_bf16 v[94:97], v[34:37], v[162:165], v[94:97]
	v_mfma_f32_16x16x32_bf16 v[90:93], v[42:45], v[162:165], v[90:93]
	v_mfma_f32_16x16x32_bf16 v[78:81], v[34:37], v[190:193], v[78:81]
	v_mfma_f32_16x16x32_bf16 v[74:77], v[42:45], v[190:193], v[74:77]
	v_mfma_f32_16x16x32_bf16 v[30:33], v[34:37], v[198:201], v[30:33]
	v_mfma_f32_16x16x32_bf16 v[26:29], v[42:45], v[198:201], v[26:29]
	v_mfma_f32_16x16x32_bf16 v[14:17], v[34:37], v[226:229], v[14:17]
	v_mfma_f32_16x16x32_bf16 v[10:13], v[42:45], v[226:229], v[10:13]
	v_mfma_f32_16x16x32_bf16 v[94:97], v[38:41], v[166:169], v[94:97]
	v_mfma_f32_16x16x32_bf16 v[90:93], v[46:49], v[166:169], v[90:93]
	v_mfma_f32_16x16x32_bf16 v[78:81], v[38:41], v[194:197], v[78:81]
	v_mfma_f32_16x16x32_bf16 v[74:77], v[46:49], v[194:197], v[74:77]
	v_mfma_f32_16x16x32_bf16 v[30:33], v[38:41], v[222:225], v[30:33]
	v_mfma_f32_16x16x32_bf16 v[26:29], v[46:49], v[222:225], v[26:29]
	v_mfma_f32_16x16x32_bf16 v[14:17], v[38:41], v[230:233], v[14:17]
	v_mfma_f32_16x16x32_bf16 v[10:13], v[46:49], v[230:233], v[10:13]
	s_setprio 0
	s_setprio 1
	v_mfma_f32_16x16x32_bf16 v[22:25], v[58:61], v[198:201], v[22:25]
	v_mfma_f32_16x16x32_bf16 v[18:21], v[66:69], v[198:201], v[18:21]
	v_mfma_f32_16x16x32_bf16 v[6:9], v[58:61], v[226:229], v[6:9]
	v_mfma_f32_16x16x32_bf16 v[2:5], v[66:69], v[226:229], v[2:5]
	v_mfma_f32_16x16x32_bf16 v[34:37], v[58:61], v[162:165], v[86:89]
	v_mfma_f32_16x16x32_bf16 v[38:41], v[66:69], v[162:165], v[82:85]
	v_mfma_f32_16x16x32_bf16 v[42:45], v[58:61], v[190:193], v[54:57]
	v_mfma_f32_16x16x32_bf16 v[46:49], v[66:69], v[190:193], v[50:53]
	v_mfma_f32_16x16x32_bf16 v[22:25], v[62:65], v[222:225], v[22:25]
	v_mfma_f32_16x16x32_bf16 v[18:21], v[70:73], v[222:225], v[18:21]
	v_mfma_f32_16x16x32_bf16 v[6:9], v[62:65], v[230:233], v[6:9]
	v_mfma_f32_16x16x32_bf16 v[2:5], v[70:73], v[230:233], v[2:5]
	v_mfma_f32_16x16x32_bf16 v[34:37], v[62:65], v[166:169], v[34:37]
	v_mfma_f32_16x16x32_bf16 v[38:41], v[70:73], v[166:169], v[38:41]
	v_mfma_f32_16x16x32_bf16 v[42:45], v[62:65], v[194:197], v[42:45]
	v_mfma_f32_16x16x32_bf16 v[46:49], v[70:73], v[194:197], v[46:49]
	s_setprio 0
	s_barrier
	s_add_i32 s56, 0, 0x18000
	s_add_i32 s57, 0, 0x1c000
	v_add_u32_e32 v62, s56, v212
	v_add_u32_e32 v82, s57, v212
	ds_read_b128 v[50:53], v62
	ds_read_b128 v[54:57], v62 offset:1024
	ds_read_b128 v[58:61], v62 offset:2048
	ds_read_b128 v[62:65], v62 offset:3072
	ds_read_b128 v[66:69], v82
	ds_read_b128 v[70:73], v82 offset:1024
	ds_read_b128 v[162:165], v82 offset:2048
	ds_read_b128 v[166:169], v82 offset:3072
	s_add_u32 s42, s42, 0x80000
	s_addc_u32 s43, s43, 0
	s_mov_b32 m0, s46
	v_lshl_add_u64 v[234:235], s[42:43], 0, v[178:179]
	ds_read_b128 v[82:85], v220 offset:32768
	global_load_lds_dwordx4 v[234:235], off
	ds_read_b128 v[86:89], v220 offset:33792
	v_lshl_add_u64 v[234:235], s[42:43], 0, v[180:181]
	s_mov_b32 m0, s47
	s_nop 0
	global_load_lds_dwordx4 v[234:235], off
	ds_read_b128 v[190:193], v220 offset:34816
	ds_read_b128 v[194:197], v220 offset:35840
	ds_read_b128 v[198:201], v220 offset:36864
	ds_read_b128 v[222:225], v220 offset:37888
	ds_read_b128 v[226:229], v220 offset:38912
	ds_read_b128 v[230:233], v220 offset:39936
	s_waitcnt vmcnt(8)
	s_waitcnt lgkmcnt(0)
	s_barrier
	s_setprio 1
	s_waitcnt lgkmcnt(0)
	v_mfma_f32_16x16x32_bf16 v[158:161], v[50:53], v[82:85], v[158:161]
	v_mfma_f32_16x16x32_bf16 v[154:157], v[58:61], v[82:85], v[154:157]
	v_mfma_f32_16x16x32_bf16 v[142:145], v[50:53], v[190:193], v[142:145]
	v_mfma_f32_16x16x32_bf16 v[138:141], v[58:61], v[190:193], v[138:141]
	v_mfma_f32_16x16x32_bf16 v[126:129], v[50:53], v[198:201], v[126:129]
	v_mfma_f32_16x16x32_bf16 v[122:125], v[58:61], v[198:201], v[122:125]
	v_mfma_f32_16x16x32_bf16 v[110:113], v[50:53], v[226:229], v[110:113]
	v_mfma_f32_16x16x32_bf16 v[106:109], v[58:61], v[226:229], v[106:109]
	v_mfma_f32_16x16x32_bf16 v[158:161], v[54:57], v[86:89], v[158:161]
	v_mfma_f32_16x16x32_bf16 v[154:157], v[62:65], v[86:89], v[154:157]
	v_mfma_f32_16x16x32_bf16 v[142:145], v[54:57], v[194:197], v[142:145]
	v_mfma_f32_16x16x32_bf16 v[138:141], v[62:65], v[194:197], v[138:141]
	v_mfma_f32_16x16x32_bf16 v[126:129], v[54:57], v[222:225], v[126:129]
	v_mfma_f32_16x16x32_bf16 v[122:125], v[62:65], v[222:225], v[122:125]
	v_mfma_f32_16x16x32_bf16 v[110:113], v[54:57], v[230:233], v[110:113]
	v_mfma_f32_16x16x32_bf16 v[106:109], v[62:65], v[230:233], v[106:109]
	s_setprio 0
	s_setprio 1
	v_mfma_f32_16x16x32_bf16 v[150:153], v[66:69], v[82:85], v[150:153]
	v_mfma_f32_16x16x32_bf16 v[82:85], v[162:165], v[82:85], v[146:149]
	v_mfma_f32_16x16x32_bf16 v[146:149], v[166:169], v[86:89], v[82:85]
	v_mfma_f32_16x16x32_bf16 v[82:85], v[66:69], v[190:193], v[134:137]
	v_mfma_f32_16x16x32_bf16 v[134:137], v[70:73], v[194:197], v[82:85]
	v_mfma_f32_16x16x32_bf16 v[82:85], v[162:165], v[190:193], v[130:133]
	v_mfma_f32_16x16x32_bf16 v[130:133], v[166:169], v[194:197], v[82:85]
	v_mfma_f32_16x16x32_bf16 v[82:85], v[66:69], v[198:201], v[118:121]
	v_mfma_f32_16x16x32_bf16 v[118:121], v[70:73], v[222:225], v[82:85]
	v_mfma_f32_16x16x32_bf16 v[82:85], v[162:165], v[198:201], v[114:117]
	v_mfma_f32_16x16x32_bf16 v[114:117], v[166:169], v[222:225], v[82:85]
	v_mfma_f32_16x16x32_bf16 v[82:85], v[66:69], v[226:229], v[102:105]
	v_mfma_f32_16x16x32_bf16 v[102:105], v[70:73], v[230:233], v[82:85]
	v_mfma_f32_16x16x32_bf16 v[82:85], v[162:165], v[226:229], v[98:101]
	v_mfma_f32_16x16x32_bf16 v[150:153], v[70:73], v[86:89], v[150:153]
	v_mfma_f32_16x16x32_bf16 v[98:101], v[166:169], v[230:233], v[82:85]
	s_setprio 0
	s_barrier
; #define PG8_STAGE(bufoff, gbase, voff) do { _Pragma("unroll") for (int _i = 0; _i < 2; ++_i) \
;         __builtin_amdgcn_global_load_lds((const unsigned*)((const char*)(gbase) + (voff)[_i]), (LAS unsigned*)(lds + (bufoff) + ldsw + _i * 8192), 16, 0, 0); } while (0)
; #define PG8_LDA(dst, b, h) do { _Pragma("unroll") for (int m = 0; m < 4; ++m) _Pragma("unroll") for (int k = 0; k < 2; ++k) dst[m][k] = *(const LAS bf16x8*)(lds + PG8_SA(b, h) + aoff + m * 2048 + k * 1024); } while (0)
; #define PG8_MMA(ai, bj, At, Bt) do { __builtin_amdgcn_s_setprio(1); _Pragma("unroll") for (int m = 0; m < 4; ++m) _Pragma("unroll") for (int n = 0; n < 2; ++n) _Pragma("unroll") for (int k = 0; k < 2; ++k) \
;         acc[ai][bj][m][n] = __builtin_amdgcn_mfma_f32_16x16x32_bf16(Bt[n][k], At[m][k], acc[ai][bj][m][n], 0, 0, 0); __builtin_amdgcn_s_setprio(0); } while (0)
; #define PG8_WAIT_V(n) asm volatile("s_waitcnt vmcnt(" #n ")" ::: "memory")
; #define PG8_WAIT_L(n) asm volatile("s_waitcnt lgkmcnt(" #n ")" ::: "memory")
; #define PG8_BAR __builtin_amdgcn_s_barrier()
; #define PG8_SCHED __builtin_amdgcn_sched_barrier(0)
; template <class Epi>
; __device__ __forceinline__ void gemm_phase(LAS unsigned char* lds, const Gemm g, const StaticOrder& S, const Epi& E, const int tid) {
;     ...
;             PG8_LDA(At, 1, 1); PG8_STAGE(PG8_SB(1, 0), b3, voffB); PG8_STAGE(PG8_SB(1, 1), b3 + bhs, voffB); PG8_STAGE(PG8_SA(1, 0), a3, voffA);
;             PG8_WAIT_V(8); PG8_WAIT_L(0); PG8_BAR; PG8_MMA(1, 0, At, B0); PG8_MMA(1, 1, At, B1); PG8_BAR; PG8_SCHED;
;     ...
;         if (ALIGN_EPI) { if (wr == 0) PG8_BAR; }
	s_add_i32 s42, s56, s33
	v_lshl_add_u64 v[86:87], v[172:173], 0, s[70:71]
	s_mov_b32 m0, s42
	s_nop 0
	ds_read_b128 v[82:85], v220 offset:49152
	global_load_lds_dwordx4 v[86:87], off
	ds_read_b128 v[190:193], v220 offset:50176
	s_add_i32 m0, s42, 0x2000
	s_add_u32 s40, s40, 0x8080
	v_lshl_add_u64 v[86:87], v[174:175], 0, s[70:71]
	s_addc_u32 s41, s41, 0
	s_add_i32 s42, s57, s33
	global_load_lds_dwordx4 v[86:87], off
	ds_read_b128 v[194:197], v220 offset:51200
	v_lshl_add_u64 v[86:87], s[40:41], 0, v[0:1]
	s_mov_b32 m0, s42
	s_nop 0
	global_load_lds_dwordx4 v[86:87], off
	ds_read_b128 v[198:201], v220 offset:52224
	v_lshl_add_u64 v[86:87], s[40:41], 0, v[182:183]
	s_add_i32 m0, s42, 0x2000
	s_nop 0
	global_load_lds_dwordx4 v[86:87], off
	ds_read_b128 v[222:225], v220 offset:53248
	v_lshl_add_u64 v[86:87], v[176:177], 0, s[70:71]
	s_mov_b32 m0, s48
	s_nop 0
	global_load_lds_dwordx4 v[86:87], off
	ds_read_b128 v[226:229], v220 offset:54272
	v_lshl_add_u64 v[86:87], v[238:239], 0, s[70:71]
	s_mov_b32 m0, s49
	s_nop 0
	global_load_lds_dwordx4 v[86:87], off
	ds_read_b128 v[230:233], v220 offset:55296
	ds_read_b128 v[234:237], v220 offset:56320
	s_waitcnt vmcnt(8)
	s_waitcnt lgkmcnt(0)
	s_barrier
	s_setprio 1
	s_waitcnt lgkmcnt(0)
	v_mfma_f32_16x16x32_bf16 v[86:89], v[50:53], v[82:85], v[94:97]
	v_mfma_f32_16x16x32_bf16 v[94:97], v[54:57], v[190:193], v[86:89]
	v_mfma_f32_16x16x32_bf16 v[86:89], v[58:61], v[82:85], v[90:93]
	v_mfma_f32_16x16x32_bf16 v[78:81], v[50:53], v[194:197], v[78:81]
	v_mfma_f32_16x16x32_bf16 v[74:77], v[58:61], v[194:197], v[74:77]
	v_mfma_f32_16x16x32_bf16 v[30:33], v[50:53], v[222:225], v[30:33]
	v_mfma_f32_16x16x32_bf16 v[26:29], v[58:61], v[222:225], v[26:29]
	v_mfma_f32_16x16x32_bf16 v[14:17], v[50:53], v[230:233], v[14:17]
	v_mfma_f32_16x16x32_bf16 v[10:13], v[58:61], v[230:233], v[10:13]
	v_mfma_f32_16x16x32_bf16 v[90:93], v[62:65], v[190:193], v[86:89]
	v_mfma_f32_16x16x32_bf16 v[78:81], v[54:57], v[198:201], v[78:81]
	v_mfma_f32_16x16x32_bf16 v[74:77], v[62:65], v[198:201], v[74:77]
	v_mfma_f32_16x16x32_bf16 v[30:33], v[54:57], v[226:229], v[30:33]
	v_mfma_f32_16x16x32_bf16 v[26:29], v[62:65], v[226:229], v[26:29]
	v_mfma_f32_16x16x32_bf16 v[14:17], v[54:57], v[234:237], v[14:17]
	v_mfma_f32_16x16x32_bf16 v[10:13], v[62:65], v[234:237], v[10:13]
	s_setprio 0
	s_setprio 1
	v_mfma_f32_16x16x32_bf16 v[34:37], v[66:69], v[82:85], v[34:37]
	v_mfma_f32_16x16x32_bf16 v[86:89], v[70:73], v[190:193], v[34:37]
	v_mfma_f32_16x16x32_bf16 v[34:37], v[162:165], v[82:85], v[38:41]
	v_mfma_f32_16x16x32_bf16 v[82:85], v[166:169], v[190:193], v[34:37]
	v_mfma_f32_16x16x32_bf16 v[34:37], v[66:69], v[194:197], v[42:45]
	v_mfma_f32_16x16x32_bf16 v[54:57], v[70:73], v[198:201], v[34:37]
	v_mfma_f32_16x16x32_bf16 v[34:37], v[162:165], v[194:197], v[46:49]
	v_mfma_f32_16x16x32_bf16 v[22:25], v[66:69], v[222:225], v[22:25]
	v_mfma_f32_16x16x32_bf16 v[18:21], v[162:165], v[222:225], v[18:21]
	v_mfma_f32_16x16x32_bf16 v[6:9], v[66:69], v[230:233], v[6:9]
	v_mfma_f32_16x16x32_bf16 v[2:5], v[162:165], v[230:233], v[2:5]
	v_mfma_f32_16x16x32_bf16 v[50:53], v[166:169], v[198:201], v[34:37]
	v_mfma_f32_16x16x32_bf16 v[22:25], v[70:73], v[226:229], v[22:25]
	v_mfma_f32_16x16x32_bf16 v[18:21], v[166:169], v[226:229], v[18:21]
	v_mfma_f32_16x16x32_bf16 v[6:9], v[70:73], v[234:237], v[6:9]
	v_mfma_f32_16x16x32_bf16 v[2:5], v[166:169], v[234:237], v[2:5]
	s_setprio 0
	s_barrier
	s_add_i32 s55, s55, 2
	s_add_u32 s53, s53, 0x100
	s_addc_u32 s54, s54, 0
	s_add_u32 s6, s6, 0x100
	s_addc_u32 s7, s7, 0
	s_cmp_gt_u32 s55, 29
	s_cbranch_scc0 .LBB0_314
	s_and_b64 vcc, exec, s[22:23]
	s_cbranch_vccz .LBB0_317
	s_barrier

; #define PG8_STAGE(bufoff, gbase, voff) do { _Pragma("unroll") for (int _i = 0; _i < 2; ++_i) \
;         __builtin_amdgcn_global_load_lds((const unsigned*)((const char*)(gbase) + (voff)[_i]), (LAS unsigned*)(lds + (bufoff) + ldsw + _i * 8192), 16, 0, 0); } while (0)
; #define PG8_LDA(dst, b, h) do { _Pragma("unroll") for (int m = 0; m < 4; ++m) _Pragma("unroll") for (int k = 0; k < 2; ++k) dst[m][k] = *(const LAS bf16x8*)(lds + PG8_SA(b, h) + aoff + m * 2048 + k * 1024); } while (0)
; #define PG8_LDB(dst, b, h) do { _Pragma("unroll") for (int n = 0; n < 2; ++n) _Pragma("unroll") for (int k = 0; k < 2; ++k) dst[n][k] = *(const LAS bf16x8*)(lds + PG8_SB(b, h) + boff + n * 2048 + k * 1024); } while (0)
; #define PG8_MMA(ai, bj, At, Bt) do { __builtin_amdgcn_s_setprio(1); _Pragma("unroll") for (int m = 0; m < 4; ++m) _Pragma("unroll") for (int n = 0; n < 2; ++n) _Pragma("unroll") for (int k = 0; k < 2; ++k) \
;         acc[ai][bj][m][n] = __builtin_amdgcn_mfma_f32_16x16x32_bf16(Bt[n][k], At[m][k], acc[ai][bj][m][n], 0, 0, 0); __builtin_amdgcn_s_setprio(0); } while (0)
; #define PG8_WAIT_V(n) asm volatile("s_waitcnt vmcnt(" #n ")" ::: "memory")
; #define PG8_WAIT_L(n) asm volatile("s_waitcnt lgkmcnt(" #n ")" ::: "memory")
; #define PG8_BAR __builtin_amdgcn_s_barrier()
; #define PG8_SCHED __builtin_amdgcn_sched_barrier(0)
; template <class Epi>
; __device__ __forceinline__ void gemm_phase(LAS unsigned char* lds, const Gemm g, const StaticOrder& S, const Epi& E, const int tid) {
;     ...
;             PG8_LDB(B0, 0, 0); PG8_LDB(B1, 0, 1); PG8_SCHED; PG8_LDA(At, 0, 0); PG8_STAGE(PG8_SA(1, 1), a1 + hstep, voffA);
;             PG8_WAIT_V(8); PG8_WAIT_L(0); PG8_BAR; PG8_MMA(0, 0, At, B0); PG8_MMA(0, 1, At, B1); PG8_BAR; PG8_SCHED;
;             PG8_LDA(At, 0, 1); PG8_STAGE(PG8_SB(0, 0), b2, voffB); PG8_STAGE(PG8_SB(0, 1), b2 + bhs, voffB); PG8_STAGE(PG8_SA(0, 0), a2, voffA);
;             PG8_WAIT_V(8); PG8_WAIT_L(0); PG8_BAR; PG8_MMA(1, 0, At, B0); PG8_MMA(1, 1, At, B1); PG8_BAR; PG8_SCHED;
.LBB0_454:
	s_add_i32 s13, 0, 0x10000
	v_add_u32_e32 v0, s13, v153
	s_add_i32 s36, 0, 0x14000
	ds_read_b128 v[132:135], v0
	ds_read_b128 v[136:139], v0 offset:1024
	ds_read_b128 v[156:159], v0 offset:2048
	ds_read_b128 v[160:163], v0 offset:3072
	v_add_u32_e32 v0, s36, v153
	ds_read_b128 v[164:167], v0
	ds_read_b128 v[178:181], v0 offset:1024
	ds_read_b128 v[182:185], v0 offset:2048
	ds_read_b128 v[186:189], v0 offset:3072
	s_add_u32 s34, s34, 0x40000
	s_addc_u32 s35, s35, 0
	v_lshl_add_u64 v[2:3], s[34:35], 0, v[140:141]
	s_add_i32 m0, s43, 0xc000
	ds_read_b128 v[190:193], v155
	global_load_lds_dwordx4 v[2:3], off
	ds_read_b128 v[194:197], v155 offset:1024
	v_lshl_add_u64 v[2:3], s[34:35], 0, v[144:145]
	s_add_i32 m0, s43, 0xe000
	s_nop 0
	global_load_lds_dwordx4 v[2:3], off
	ds_read_b128 v[198:201], v155 offset:2048
	ds_read_b128 v[212:215], v155 offset:3072
	ds_read_b128 v[216:219], v155 offset:4096
	ds_read_b128 v[220:223], v155 offset:5120
	ds_read_b128 v[224:227], v155 offset:6144
	ds_read_b128 v[228:231], v155 offset:7168
	s_waitcnt vmcnt(8)
	s_waitcnt lgkmcnt(0)
	s_barrier
	s_setprio 1
	s_waitcnt lgkmcnt(0)
	v_mfma_f32_16x16x32_bf16 v[128:131], v[132:135], v[190:193], v[128:131]
	v_mfma_f32_16x16x32_bf16 v[124:127], v[156:159], v[190:193], v[124:127]
	v_mfma_f32_16x16x32_bf16 v[112:115], v[132:135], v[198:201], v[112:115]
	v_mfma_f32_16x16x32_bf16 v[108:111], v[156:159], v[198:201], v[108:111]
	v_mfma_f32_16x16x32_bf16 v[96:99], v[132:135], v[216:219], v[96:99]
	v_mfma_f32_16x16x32_bf16 v[92:95], v[156:159], v[216:219], v[92:95]
	v_mfma_f32_16x16x32_bf16 v[80:83], v[132:135], v[224:227], v[80:83]
	v_mfma_f32_16x16x32_bf16 v[76:79], v[156:159], v[224:227], v[76:79]
	v_mfma_f32_16x16x32_bf16 v[128:131], v[136:139], v[194:197], v[128:131]
	v_mfma_f32_16x16x32_bf16 v[124:127], v[160:163], v[194:197], v[124:127]
	v_mfma_f32_16x16x32_bf16 v[112:115], v[136:139], v[212:215], v[112:115]
	v_mfma_f32_16x16x32_bf16 v[108:111], v[160:163], v[212:215], v[108:111]
	v_mfma_f32_16x16x32_bf16 v[96:99], v[136:139], v[220:223], v[96:99]
	v_mfma_f32_16x16x32_bf16 v[92:95], v[160:163], v[220:223], v[92:95]
	v_mfma_f32_16x16x32_bf16 v[80:83], v[136:139], v[228:231], v[80:83]
	v_mfma_f32_16x16x32_bf16 v[76:79], v[160:163], v[228:231], v[76:79]
	s_setprio 0
	s_setprio 1
	v_mfma_f32_16x16x32_bf16 v[120:123], v[164:167], v[190:193], v[120:123]
	v_mfma_f32_16x16x32_bf16 v[116:119], v[182:185], v[190:193], v[116:119]
	v_mfma_f32_16x16x32_bf16 v[104:107], v[164:167], v[198:201], v[104:107]
	v_mfma_f32_16x16x32_bf16 v[100:103], v[182:185], v[198:201], v[100:103]
	v_mfma_f32_16x16x32_bf16 v[88:91], v[164:167], v[216:219], v[88:91]
	v_mfma_f32_16x16x32_bf16 v[84:87], v[182:185], v[216:219], v[84:87]
	v_mfma_f32_16x16x32_bf16 v[72:75], v[164:167], v[224:227], v[72:75]
	v_mfma_f32_16x16x32_bf16 v[68:71], v[182:185], v[224:227], v[68:71]
	v_mfma_f32_16x16x32_bf16 v[120:123], v[178:181], v[194:197], v[120:123]
	v_mfma_f32_16x16x32_bf16 v[116:119], v[186:189], v[194:197], v[116:119]
	v_mfma_f32_16x16x32_bf16 v[104:107], v[178:181], v[212:215], v[104:107]
	v_mfma_f32_16x16x32_bf16 v[100:103], v[186:189], v[212:215], v[100:103]
	v_mfma_f32_16x16x32_bf16 v[88:91], v[178:181], v[220:223], v[88:91]
	v_mfma_f32_16x16x32_bf16 v[84:87], v[186:189], v[220:223], v[84:87]
	v_mfma_f32_16x16x32_bf16 v[72:75], v[178:181], v[228:231], v[72:75]
	v_mfma_f32_16x16x32_bf16 v[68:71], v[186:189], v[228:231], v[68:71]
	s_setprio 0
	s_barrier
	s_add_i32 s13, s13, s42
	v_lshl_add_u64 v[168:169], s[28:29], 0, v[142:143]
	s_mov_b32 m0, s13
	ds_read_b128 v[190:193], v155 offset:16384
	global_load_lds_dwordx4 v[168:169], off
	ds_read_b128 v[194:197], v155 offset:17408
	s_add_i32 m0, s13, 0x2000
	s_add_u32 s34, s28, 0x4000
	v_lshl_add_u64 v[172:173], s[28:29], 0, v[146:147]
	s_addc_u32 s35, s29, 0
	s_add_i32 s13, s36, s42
	global_load_lds_dwordx4 v[172:173], off
	ds_read_b128 v[198:201], v155 offset:18432
	v_lshl_add_u64 v[2:3], s[34:35], 0, v[142:143]
	s_mov_b32 m0, s13
	v_lshl_add_u64 v[174:175], s[30:31], 0, v[140:141]
	global_load_lds_dwordx4 v[2:3], off
	ds_read_b128 v[212:215], v155 offset:19456
	v_lshl_add_u64 v[2:3], s[34:35], 0, v[146:147]
	s_add_i32 m0, s13, 0x2000
	v_lshl_add_u64 v[176:177], s[30:31], 0, v[144:145]
	global_load_lds_dwordx4 v[2:3], off
	ds_read_b128 v[216:219], v155 offset:20480
	s_mov_b32 m0, s43
	s_nop 0
	global_load_lds_dwordx4 v[174:175], off
	ds_read_b128 v[220:223], v155 offset:21504
	s_mov_b32 m0, s44
	s_nop 0
	global_load_lds_dwordx4 v[176:177], off
	ds_read_b128 v[224:227], v155 offset:22528
	ds_read_b128 v[228:231], v155 offset:23552
	s_waitcnt vmcnt(8)
	s_waitcnt lgkmcnt(0)
	s_barrier
; #define PG8_STAGE(bufoff, gbase, voff) do { _Pragma("unroll") for (int _i = 0; _i < 2; ++_i) \
;         __builtin_amdgcn_global_load_lds((const unsigned*)((const char*)(gbase) + (voff)[_i]), (LAS unsigned*)(lds + (bufoff) + ldsw + _i * 8192), 16, 0, 0); } while (0)
; #define PG8_LDA(dst, b, h) do { _Pragma("unroll") for (int m = 0; m < 4; ++m) _Pragma("unroll") for (int k = 0; k < 2; ++k) dst[m][k] = *(const LAS bf16x8*)(lds + PG8_SA(b, h) + aoff + m * 2048 + k * 1024); } while (0)
; #define PG8_LDB(dst, b, h) do { _Pragma("unroll") for (int n = 0; n < 2; ++n) _Pragma("unroll") for (int k = 0; k < 2; ++k) dst[n][k] = *(const LAS bf16x8*)(lds + PG8_SB(b, h) + boff + n * 2048 + k * 1024); } while (0)
; #define PG8_MMA(ai, bj, At, Bt) do { __builtin_amdgcn_s_setprio(1); _Pragma("unroll") for (int m = 0; m < 4; ++m) _Pragma("unroll") for (int n = 0; n < 2; ++n) _Pragma("unroll") for (int k = 0; k < 2; ++k) \
;         acc[ai][bj][m][n] = __builtin_amdgcn_mfma_f32_16x16x32_bf16(Bt[n][k], At[m][k], acc[ai][bj][m][n], 0, 0, 0); __builtin_amdgcn_s_setprio(0); } while (0)
; #define PG8_WAIT_V(n) asm volatile("s_waitcnt vmcnt(" #n ")" ::: "memory")
; #define PG8_WAIT_L(n) asm volatile("s_waitcnt lgkmcnt(" #n ")" ::: "memory")
; #define PG8_BAR __builtin_amdgcn_s_barrier()
; #define PG8_SCHED __builtin_amdgcn_sched_barrier(0)
; template <class Epi>
; __device__ __forceinline__ void gemm_phase(LAS unsigned char* lds, const Gemm g, const StaticOrder& S, const Epi& E, const int tid) {
;     ...
;             PG8_WAIT_V(8); PG8_WAIT_L(0); PG8_BAR; PG8_MMA(1, 0, At, B0); PG8_MMA(1, 1, At, B1); PG8_BAR; PG8_SCHED;
;             PG8_LDB(B0, 1, 0); PG8_LDB(B1, 1, 1); PG8_SCHED; PG8_LDA(At, 1, 0); PG8_STAGE(PG8_SA(0, 1), a2 + hstep, voffA);
;             PG8_WAIT_V(8); PG8_WAIT_L(0); PG8_BAR; PG8_MMA(0, 0, At, B0); PG8_MMA(0, 1, At, B1); PG8_BAR; PG8_SCHED;
	s_setprio 1
	s_waitcnt lgkmcnt(0)
	v_mfma_f32_16x16x32_bf16 v[64:67], v[132:135], v[190:193], v[64:67]
	v_mfma_f32_16x16x32_bf16 v[60:63], v[156:159], v[190:193], v[60:63]
	v_mfma_f32_16x16x32_bf16 v[48:51], v[132:135], v[198:201], v[48:51]
	v_mfma_f32_16x16x32_bf16 v[44:47], v[156:159], v[198:201], v[44:47]
	v_mfma_f32_16x16x32_bf16 v[32:35], v[132:135], v[216:219], v[32:35]
	v_mfma_f32_16x16x32_bf16 v[28:31], v[156:159], v[216:219], v[28:31]
	v_mfma_f32_16x16x32_bf16 v[16:19], v[132:135], v[224:227], v[16:19]
	v_mfma_f32_16x16x32_bf16 v[12:15], v[156:159], v[224:227], v[12:15]
	v_mfma_f32_16x16x32_bf16 v[64:67], v[136:139], v[194:197], v[64:67]
	v_mfma_f32_16x16x32_bf16 v[60:63], v[160:163], v[194:197], v[60:63]
	v_mfma_f32_16x16x32_bf16 v[48:51], v[136:139], v[212:215], v[48:51]
	v_mfma_f32_16x16x32_bf16 v[44:47], v[160:163], v[212:215], v[44:47]
	v_mfma_f32_16x16x32_bf16 v[32:35], v[136:139], v[220:223], v[32:35]
	v_mfma_f32_16x16x32_bf16 v[28:31], v[160:163], v[220:223], v[28:31]
	v_mfma_f32_16x16x32_bf16 v[16:19], v[136:139], v[228:231], v[16:19]
	v_mfma_f32_16x16x32_bf16 v[12:15], v[160:163], v[228:231], v[12:15]
	s_setprio 0
	s_setprio 1
	v_mfma_f32_16x16x32_bf16 v[56:59], v[164:167], v[190:193], v[56:59]
	v_mfma_f32_16x16x32_bf16 v[52:55], v[182:185], v[190:193], v[52:55]
	v_mfma_f32_16x16x32_bf16 v[40:43], v[164:167], v[198:201], v[40:43]
	v_mfma_f32_16x16x32_bf16 v[36:39], v[182:185], v[198:201], v[36:39]
	v_mfma_f32_16x16x32_bf16 v[24:27], v[164:167], v[216:219], v[24:27]
	v_mfma_f32_16x16x32_bf16 v[20:23], v[182:185], v[216:219], v[20:23]
	v_mfma_f32_16x16x32_bf16 v[8:11], v[164:167], v[224:227], v[8:11]
	v_mfma_f32_16x16x32_bf16 v[2:5], v[182:185], v[224:227], v[4:7]
	v_mfma_f32_16x16x32_bf16 v[56:59], v[178:181], v[194:197], v[56:59]
	v_mfma_f32_16x16x32_bf16 v[52:55], v[186:189], v[194:197], v[52:55]
	v_mfma_f32_16x16x32_bf16 v[40:43], v[178:181], v[212:215], v[40:43]
	v_mfma_f32_16x16x32_bf16 v[36:39], v[186:189], v[212:215], v[36:39]
	v_mfma_f32_16x16x32_bf16 v[24:27], v[178:181], v[220:223], v[24:27]
	v_mfma_f32_16x16x32_bf16 v[20:23], v[186:189], v[220:223], v[20:23]
	v_mfma_f32_16x16x32_bf16 v[8:11], v[178:181], v[228:231], v[8:11]
	v_mfma_f32_16x16x32_bf16 v[2:5], v[186:189], v[228:231], v[2:5]
	s_setprio 0
	s_barrier
	s_add_i32 s13, 0, 0x18000
	v_add_u32_e32 v0, s13, v153
	s_add_i32 s34, 0, 0x1c000
	ds_read_b128 v[132:135], v0
	ds_read_b128 v[136:139], v0 offset:1024
	ds_read_b128 v[156:159], v0 offset:2048
	ds_read_b128 v[160:163], v0 offset:3072
	v_add_u32_e32 v0, s34, v153
	ds_read_b128 v[164:167], v0
	ds_read_b128 v[178:181], v0 offset:1024
	ds_read_b128 v[182:185], v0 offset:2048
	ds_read_b128 v[186:189], v0 offset:3072
	s_add_u32 s30, s30, 0x40000
	s_addc_u32 s31, s31, 0
	s_mov_b32 m0, s45
	v_lshl_add_u64 v[6:7], s[30:31], 0, v[140:141]
	ds_read_b128 v[190:193], v155 offset:32768
	global_load_lds_dwordx4 v[6:7], off
	ds_read_b128 v[194:197], v155 offset:33792
	v_lshl_add_u64 v[6:7], s[30:31], 0, v[144:145]
	s_mov_b32 m0, s46
	s_nop 0
	global_load_lds_dwordx4 v[6:7], off
	ds_read_b128 v[198:201], v155 offset:34816
	ds_read_b128 v[212:215], v155 offset:35840
	ds_read_b128 v[216:219], v155 offset:36864
	ds_read_b128 v[220:223], v155 offset:37888
	ds_read_b128 v[224:227], v155 offset:38912
	ds_read_b128 v[228:231], v155 offset:39936
	s_waitcnt vmcnt(8)
	s_waitcnt lgkmcnt(0)
	s_barrier
	s_setprio 1
	s_waitcnt lgkmcnt(0)
	v_mfma_f32_16x16x32_bf16 v[128:131], v[132:135], v[190:193], v[128:131]
	v_mfma_f32_16x16x32_bf16 v[124:127], v[156:159], v[190:193], v[124:127]
	v_mfma_f32_16x16x32_bf16 v[112:115], v[132:135], v[198:201], v[112:115]
	v_mfma_f32_16x16x32_bf16 v[108:111], v[156:159], v[198:201], v[108:111]
	v_mfma_f32_16x16x32_bf16 v[96:99], v[132:135], v[216:219], v[96:99]
	v_mfma_f32_16x16x32_bf16 v[92:95], v[156:159], v[216:219], v[92:95]
	v_mfma_f32_16x16x32_bf16 v[80:83], v[132:135], v[224:227], v[80:83]
	v_mfma_f32_16x16x32_bf16 v[76:79], v[156:159], v[224:227], v[76:79]
	v_mfma_f32_16x16x32_bf16 v[128:131], v[136:139], v[194:197], v[128:131]
	v_mfma_f32_16x16x32_bf16 v[124:127], v[160:163], v[194:197], v[124:127]
	v_mfma_f32_16x16x32_bf16 v[112:115], v[136:139], v[212:215], v[112:115]
	v_mfma_f32_16x16x32_bf16 v[108:111], v[160:163], v[212:215], v[108:111]
	v_mfma_f32_16x16x32_bf16 v[96:99], v[136:139], v[220:223], v[96:99]
	v_mfma_f32_16x16x32_bf16 v[92:95], v[160:163], v[220:223], v[92:95]
	v_mfma_f32_16x16x32_bf16 v[80:83], v[136:139], v[228:231], v[80:83]
	v_mfma_f32_16x16x32_bf16 v[76:79], v[160:163], v[228:231], v[76:79]
	s_setprio 0
	s_setprio 1
	v_mfma_f32_16x16x32_bf16 v[120:123], v[164:167], v[190:193], v[120:123]
	v_mfma_f32_16x16x32_bf16 v[116:119], v[182:185], v[190:193], v[116:119]
	v_mfma_f32_16x16x32_bf16 v[104:107], v[164:167], v[198:201], v[104:107]
	v_mfma_f32_16x16x32_bf16 v[100:103], v[182:185], v[198:201], v[100:103]
	v_mfma_f32_16x16x32_bf16 v[88:91], v[164:167], v[216:219], v[88:91]
	v_mfma_f32_16x16x32_bf16 v[84:87], v[182:185], v[216:219], v[84:87]
	v_mfma_f32_16x16x32_bf16 v[72:75], v[164:167], v[224:227], v[72:75]
	v_mfma_f32_16x16x32_bf16 v[68:71], v[182:185], v[224:227], v[68:71]
	v_mfma_f32_16x16x32_bf16 v[120:123], v[178:181], v[194:197], v[120:123]
	v_mfma_f32_16x16x32_bf16 v[116:119], v[186:189], v[194:197], v[116:119]
	v_mfma_f32_16x16x32_bf16 v[104:107], v[178:181], v[212:215], v[104:107]
	v_mfma_f32_16x16x32_bf16 v[100:103], v[186:189], v[212:215], v[100:103]
	v_mfma_f32_16x16x32_bf16 v[88:91], v[178:181], v[220:223], v[88:91]
	v_mfma_f32_16x16x32_bf16 v[84:87], v[186:189], v[220:223], v[84:87]
	v_mfma_f32_16x16x32_bf16 v[72:75], v[178:181], v[228:231], v[72:75]
	v_mfma_f32_16x16x32_bf16 v[68:71], v[186:189], v[228:231], v[68:71]
	s_setprio 0
	s_barrier
; #define PG8_STAGE(bufoff, gbase, voff) do { _Pragma("unroll") for (int _i = 0; _i < 2; ++_i) \
;         __builtin_amdgcn_global_load_lds((const unsigned*)((const char*)(gbase) + (voff)[_i]), (LAS unsigned*)(lds + (bufoff) + ldsw + _i * 8192), 16, 0, 0); } while (0)
; #define PG8_LDA(dst, b, h) do { _Pragma("unroll") for (int m = 0; m < 4; ++m) _Pragma("unroll") for (int k = 0; k < 2; ++k) dst[m][k] = *(const LAS bf16x8*)(lds + PG8_SA(b, h) + aoff + m * 2048 + k * 1024); } while (0)
; #define PG8_MMA(ai, bj, At, Bt) do { __builtin_amdgcn_s_setprio(1); _Pragma("unroll") for (int m = 0; m < 4; ++m) _Pragma("unroll") for (int n = 0; n < 2; ++n) _Pragma("unroll") for (int k = 0; k < 2; ++k) \
;         acc[ai][bj][m][n] = __builtin_amdgcn_mfma_f32_16x16x32_bf16(Bt[n][k], At[m][k], acc[ai][bj][m][n], 0, 0, 0); __builtin_amdgcn_s_setprio(0); } while (0)
; #define PG8_WAIT_V(n) asm volatile("s_waitcnt vmcnt(" #n ")" ::: "memory")
; #define PG8_WAIT_L(n) asm volatile("s_waitcnt lgkmcnt(" #n ")" ::: "memory")
; #define PG8_BAR __builtin_amdgcn_s_barrier()
; #define PG8_SCHED __builtin_amdgcn_sched_barrier(0)
; template <class Epi>
; __device__ __forceinline__ void gemm_phase(LAS unsigned char* lds, const Gemm g, const StaticOrder& S, const Epi& E, const int tid) {
;     ...
;         for (int t = 0; t < ntt; t += 2) {
;     ...
;             PG8_LDA(At, 1, 1); PG8_STAGE(PG8_SB(1, 0), b3, voffB); PG8_STAGE(PG8_SB(1, 1), b3 + bhs, voffB); PG8_STAGE(PG8_SA(1, 0), a3, voffA);
;             PG8_WAIT_V(8); PG8_WAIT_L(0); PG8_BAR; PG8_MMA(1, 0, At, B0); PG8_MMA(1, 1, At, B1); PG8_BAR; PG8_SCHED;
	s_add_i32 s13, s13, s42
	v_lshl_add_u64 v[6:7], v[168:169], 0, s[70:71]
	s_mov_b32 m0, s13
	ds_read_b128 v[190:193], v155 offset:49152
	global_load_lds_dwordx4 v[6:7], off
	ds_read_b128 v[194:197], v155 offset:50176
	s_add_i32 m0, s13, 0x2000
	s_add_u32 s28, s28, 0x4080
	v_lshl_add_u64 v[6:7], v[172:173], 0, s[70:71]
	s_addc_u32 s29, s29, 0
	s_add_i32 s13, s34, s42
	global_load_lds_dwordx4 v[6:7], off
	ds_read_b128 v[198:201], v155 offset:51200
	v_lshl_add_u64 v[6:7], s[28:29], 0, v[142:143]
	s_mov_b32 m0, s13
	s_nop 0
	global_load_lds_dwordx4 v[6:7], off
	ds_read_b128 v[212:215], v155 offset:52224
	v_lshl_add_u64 v[6:7], s[28:29], 0, v[146:147]
	s_add_i32 m0, s13, 0x2000
	s_nop 0
	global_load_lds_dwordx4 v[6:7], off
	ds_read_b128 v[216:219], v155 offset:53248
	v_lshl_add_u64 v[6:7], v[174:175], 0, s[70:71]
	s_mov_b32 m0, s47
	s_nop 0
	global_load_lds_dwordx4 v[6:7], off
	ds_read_b128 v[220:223], v155 offset:54272
	v_lshl_add_u64 v[6:7], v[176:177], 0, s[70:71]
	s_mov_b32 m0, s48
	s_nop 0
	global_load_lds_dwordx4 v[6:7], off
	ds_read_b128 v[224:227], v155 offset:55296
	ds_read_b128 v[228:231], v155 offset:56320
	s_waitcnt vmcnt(8)
	s_waitcnt lgkmcnt(0)
	s_barrier
	s_setprio 1
	s_waitcnt lgkmcnt(0)
	v_mfma_f32_16x16x32_bf16 v[64:67], v[132:135], v[190:193], v[64:67]
	v_mfma_f32_16x16x32_bf16 v[60:63], v[156:159], v[190:193], v[60:63]
	v_mfma_f32_16x16x32_bf16 v[48:51], v[132:135], v[198:201], v[48:51]
	v_mfma_f32_16x16x32_bf16 v[44:47], v[156:159], v[198:201], v[44:47]
	v_mfma_f32_16x16x32_bf16 v[32:35], v[132:135], v[216:219], v[32:35]
	v_mfma_f32_16x16x32_bf16 v[28:31], v[156:159], v[216:219], v[28:31]
	v_mfma_f32_16x16x32_bf16 v[16:19], v[132:135], v[224:227], v[16:19]
	v_mfma_f32_16x16x32_bf16 v[12:15], v[156:159], v[224:227], v[12:15]
	v_mfma_f32_16x16x32_bf16 v[64:67], v[136:139], v[194:197], v[64:67]
	v_mfma_f32_16x16x32_bf16 v[60:63], v[160:163], v[194:197], v[60:63]
	v_mfma_f32_16x16x32_bf16 v[48:51], v[136:139], v[212:215], v[48:51]
	v_mfma_f32_16x16x32_bf16 v[44:47], v[160:163], v[212:215], v[44:47]
	v_mfma_f32_16x16x32_bf16 v[32:35], v[136:139], v[220:223], v[32:35]
	v_mfma_f32_16x16x32_bf16 v[28:31], v[160:163], v[220:223], v[28:31]
	v_mfma_f32_16x16x32_bf16 v[16:19], v[136:139], v[228:231], v[16:19]
	v_mfma_f32_16x16x32_bf16 v[12:15], v[160:163], v[228:231], v[12:15]
	s_setprio 0
	s_setprio 1
	v_mfma_f32_16x16x32_bf16 v[56:59], v[164:167], v[190:193], v[56:59]
	v_mfma_f32_16x16x32_bf16 v[52:55], v[182:185], v[190:193], v[52:55]
	v_mfma_f32_16x16x32_bf16 v[40:43], v[164:167], v[198:201], v[40:43]
	v_mfma_f32_16x16x32_bf16 v[36:39], v[182:185], v[198:201], v[36:39]
	v_mfma_f32_16x16x32_bf16 v[24:27], v[164:167], v[216:219], v[24:27]
	v_mfma_f32_16x16x32_bf16 v[20:23], v[182:185], v[216:219], v[20:23]
	v_mfma_f32_16x16x32_bf16 v[6:9], v[164:167], v[224:227], v[8:11]
	v_mfma_f32_16x16x32_bf16 v[2:5], v[182:185], v[224:227], v[2:5]
	v_mfma_f32_16x16x32_bf16 v[56:59], v[178:181], v[194:197], v[56:59]
	v_mfma_f32_16x16x32_bf16 v[52:55], v[186:189], v[194:197], v[52:55]
	v_mfma_f32_16x16x32_bf16 v[40:43], v[178:181], v[212:215], v[40:43]
	v_mfma_f32_16x16x32_bf16 v[36:39], v[186:189], v[212:215], v[36:39]
	v_mfma_f32_16x16x32_bf16 v[24:27], v[178:181], v[220:223], v[24:27]
	v_mfma_f32_16x16x32_bf16 v[20:23], v[186:189], v[220:223], v[20:23]
	v_mfma_f32_16x16x32_bf16 v[8:11], v[178:181], v[228:231], v[6:9]
	v_mfma_f32_16x16x32_bf16 v[4:7], v[186:189], v[228:231], v[2:5]
	s_setprio 0
	s_barrier
	s_add_i32 s2, s2, 2
	s_add_u32 s24, s24, 0x100
	s_addc_u32 s25, s25, 0
	s_add_u32 s26, s26, 0x100
	s_addc_u32 s27, s27, 0
	s_cmp_gt_u32 s11, 29
	s_cbranch_scc1 .LBB0_467

; #define PG8_STAGE(bufoff, gbase, voff) do { _Pragma("unroll") for (int _i = 0; _i < 2; ++_i) \
;         __builtin_amdgcn_global_load_lds((const unsigned*)((const char*)(gbase) + (voff)[_i]), (LAS unsigned*)(lds + (bufoff) + ldsw + _i * 8192), 16, 0, 0); } while (0)
; #define PG8_LDA(dst, b, h) do { _Pragma("unroll") for (int m = 0; m < 4; ++m) _Pragma("unroll") for (int k = 0; k < 2; ++k) dst[m][k] = *(const LAS bf16x8*)(lds + PG8_SA(b, h) + aoff + m * 2048 + k * 1024); } while (0)
; #define PG8_LDB(dst, b, h) do { _Pragma("unroll") for (int n = 0; n < 2; ++n) _Pragma("unroll") for (int k = 0; k < 2; ++k) dst[n][k] = *(const LAS bf16x8*)(lds + PG8_SB(b, h) + boff + n * 2048 + k * 1024); } while (0)
; #define PG8_WAIT_V(n) asm volatile("s_waitcnt vmcnt(" #n ")" ::: "memory")
; #define PG8_WAIT_L(n) asm volatile("s_waitcnt lgkmcnt(" #n ")" ::: "memory")
; #define PG8_BAR __builtin_amdgcn_s_barrier()
; #define PG8_SCHED __builtin_amdgcn_sched_barrier(0)
; template <class Epi>
; __device__ __forceinline__ void gemm_phase(LAS unsigned char* lds, const Gemm g, const StaticOrder& S, const Epi& E, const int tid) {
;     ...
;             const bool last = (t == ntt - 2);
;             const bool s1 = Epi::TWO && (t >= nt), s2 = Epi::TWO && (t + 2 >= nt);
;             const char* a1 = (s1 ? cA2 + (size_t)(t - nt + 1) * kstep : cA + (size_t)(t + 1) * kstep);
;             const char* a2 = last ? nA : (s2 ? cA2 + (size_t)(t + 2 - nt) * kstep : cA + (size_t)(t + 2) * kstep);
;             const char* b2 = last ? nB : (s2 ? cB2 + (size_t)(t + 2 - nt) * kstep : cB + (size_t)(t + 2) * kstep);
;             const char* a3 = a2 + kstep; const char* b3 = b2 + kstep;
;             if constexpr (Epi::TWO) { if (t == nt) E.mid(acc, cur, wr, wc, fr, fq); }
;             if constexpr (SP2) {
;             PG8_LDB(B0, 0, 0); PG8_LDB(B1, 0, 1); PG8_SCHED; PG8_LDA(At, 0, 0); PG8_STAGE(PG8_SA(1, 1), a1 + hstep, voffA);
;             PG8_WAIT_V(8); PG8_WAIT_L(0); PG8_BAR; PG8_MMA(0, 0, At, B0); PG8_MMA(0, 1, At, B1); PG8_BAR; PG8_SCHED;
;             PG8_LDA(At, 0, 1); PG8_STAGE(PG8_SB(0, 0), b2, voffB); PG8_STAGE(PG8_SB(0, 1), b2 + bhs, voffB); PG8_STAGE(PG8_SA(0, 0), a2, voffA);
;             PG8_WAIT_V(8); PG8_WAIT_L(0); PG8_BAR; PG8_MMA(1, 0, At, B0); PG8_MMA(1, 1, At, B1); PG8_BAR; PG8_SCHED;
.LBB0_546:
	s_add_u32 s28, s26, 0xfff80080
	s_addc_u32 s29, s27, -1
	s_add_i32 s44, 0, 0x10000
	s_cmp_eq_u32 s39, 28
	s_cselect_b32 s35, s19, s29
	s_cselect_b32 s34, s31, s28
	v_add_u32_e32 v0, s44, v149
	s_cselect_b32 s29, s17, s38
	s_cselect_b32 s28, s33, s37
	s_add_i32 s46, 0, 0x14000
	ds_read_b128 v[150:153], v0
	ds_read_b128 v[154:157], v0 offset:1024
	ds_read_b128 v[158:161], v0 offset:2048
	ds_read_b128 v[186:189], v0 offset:3072
	v_add_u32_e32 v0, s46, v149
	ds_read_b128 v[190:193], v0
	ds_read_b128 v[194:197], v0 offset:1024
	ds_read_b128 v[198:201], v0 offset:2048
	ds_read_b128 v[212:215], v0 offset:3072
	v_lshl_add_u64 v[162:163], s[26:27], 0, v[146:147]
	s_add_i32 m0, s57, 0xc000
	ds_read_b128 v[216:219], v184
	global_load_lds_dwordx4 v[162:163], off
	ds_read_b128 v[220:223], v184 offset:1024
	v_lshl_add_u64 v[162:163], s[26:27], 0, v[144:145]
	s_add_i32 m0, s57, 0xe000
	s_nop 0
	global_load_lds_dwordx4 v[162:163], off
	ds_read_b128 v[224:227], v184 offset:2048
	ds_read_b128 v[228:231], v184 offset:3072
	ds_read_b128 v[232:235], v184 offset:4096
	ds_read_b128 v[236:239], v184 offset:5120
	ds_read_b128 v[240:243], v184 offset:6144
	ds_read_b128 v[244:247], v184 offset:7168
	s_waitcnt vmcnt(8)
	s_waitcnt lgkmcnt(0)
	s_barrier
	s_setprio 1
	s_waitcnt lgkmcnt(0)
	v_mfma_f32_16x16x32_bf16 v[126:129], v[150:153], v[216:219], v[126:129]
	v_mfma_f32_16x16x32_bf16 v[122:125], v[158:161], v[216:219], v[122:125]
	v_mfma_f32_16x16x32_bf16 v[110:113], v[150:153], v[224:227], v[110:113]
	v_mfma_f32_16x16x32_bf16 v[106:109], v[158:161], v[224:227], v[106:109]
	v_mfma_f32_16x16x32_bf16 v[94:97], v[150:153], v[232:235], v[94:97]
	v_mfma_f32_16x16x32_bf16 v[90:93], v[158:161], v[232:235], v[90:93]
	v_mfma_f32_16x16x32_bf16 v[78:81], v[150:153], v[240:243], v[78:81]
	v_mfma_f32_16x16x32_bf16 v[74:77], v[158:161], v[240:243], v[74:77]
	v_mfma_f32_16x16x32_bf16 v[126:129], v[154:157], v[220:223], v[126:129]
	v_mfma_f32_16x16x32_bf16 v[122:125], v[186:189], v[220:223], v[122:125]
	v_mfma_f32_16x16x32_bf16 v[110:113], v[154:157], v[228:231], v[110:113]
	v_mfma_f32_16x16x32_bf16 v[106:109], v[186:189], v[228:231], v[106:109]
	v_mfma_f32_16x16x32_bf16 v[94:97], v[154:157], v[236:239], v[94:97]
	v_mfma_f32_16x16x32_bf16 v[90:93], v[186:189], v[236:239], v[90:93]
	v_mfma_f32_16x16x32_bf16 v[78:81], v[154:157], v[244:247], v[78:81]
	v_mfma_f32_16x16x32_bf16 v[74:77], v[186:189], v[244:247], v[74:77]
	s_setprio 0
	s_setprio 1
	v_mfma_f32_16x16x32_bf16 v[118:121], v[190:193], v[216:219], v[118:121]
	v_mfma_f32_16x16x32_bf16 v[114:117], v[198:201], v[216:219], v[114:117]
	v_mfma_f32_16x16x32_bf16 v[102:105], v[190:193], v[224:227], v[102:105]
	v_mfma_f32_16x16x32_bf16 v[98:101], v[198:201], v[224:227], v[98:101]
	v_mfma_f32_16x16x32_bf16 v[86:89], v[190:193], v[232:235], v[86:89]
	v_mfma_f32_16x16x32_bf16 v[82:85], v[198:201], v[232:235], v[82:85]
	v_mfma_f32_16x16x32_bf16 v[70:73], v[190:193], v[240:243], v[70:73]
	v_mfma_f32_16x16x32_bf16 v[66:69], v[198:201], v[240:243], v[66:69]
	v_mfma_f32_16x16x32_bf16 v[118:121], v[194:197], v[220:223], v[118:121]
	v_mfma_f32_16x16x32_bf16 v[114:117], v[212:215], v[220:223], v[114:117]
	v_mfma_f32_16x16x32_bf16 v[102:105], v[194:197], v[228:231], v[102:105]
	v_mfma_f32_16x16x32_bf16 v[98:101], v[212:215], v[228:231], v[98:101]
	v_mfma_f32_16x16x32_bf16 v[86:89], v[194:197], v[236:239], v[86:89]
	v_mfma_f32_16x16x32_bf16 v[82:85], v[212:215], v[236:239], v[82:85]
	v_mfma_f32_16x16x32_bf16 v[70:73], v[194:197], v[244:247], v[70:73]
	v_mfma_f32_16x16x32_bf16 v[66:69], v[212:215], v[244:247], v[66:69]
	s_setprio 0
	s_barrier
	s_add_i32 s44, s44, s56
	v_lshl_add_u64 v[162:163], s[28:29], 0, v[132:133]
	s_mov_b32 m0, s44
	ds_read_b128 v[216:219], v184 offset:16384
	global_load_lds_dwordx4 v[162:163], off
	ds_read_b128 v[220:223], v184 offset:17408
	s_add_i32 m0, s44, 0x2000
	s_add_u32 s44, s28, 0x8000
	v_lshl_add_u64 v[248:249], s[28:29], 0, v[136:137]
	s_addc_u32 s45, s29, 0
	s_add_i32 s46, s46, s56
	global_load_lds_dwordx4 v[248:249], off
	ds_read_b128 v[224:227], v184 offset:18432
	v_lshl_add_u64 v[172:173], s[44:45], 0, v[132:133]
	s_mov_b32 m0, s46
	v_lshl_add_u64 v[174:175], s[34:35], 0, v[134:135]
	global_load_lds_dwordx4 v[172:173], off
	ds_read_b128 v[228:231], v184 offset:19456
	v_lshl_add_u64 v[172:173], s[44:45], 0, v[136:137]
	s_add_i32 m0, s46, 0x2000
	s_nop 0
	global_load_lds_dwordx4 v[172:173], off
	ds_read_b128 v[232:235], v184 offset:20480
	v_lshl_add_u64 v[172:173], s[34:35], 0, v[130:131]
	s_mov_b32 m0, s57
	s_nop 0
	global_load_lds_dwordx4 v[172:173], off
	ds_read_b128 v[236:239], v184 offset:21504
	s_mov_b32 m0, s58
	s_nop 0
	global_load_lds_dwordx4 v[174:175], off
	ds_read_b128 v[240:243], v184 offset:22528
	ds_read_b128 v[244:247], v184 offset:23552
	s_waitcnt vmcnt(8)
	s_waitcnt lgkmcnt(0)
	s_barrier
; #define PG8_STAGE(bufoff, gbase, voff) do { _Pragma("unroll") for (int _i = 0; _i < 2; ++_i) \
;         __builtin_amdgcn_global_load_lds((const unsigned*)((const char*)(gbase) + (voff)[_i]), (LAS unsigned*)(lds + (bufoff) + ldsw + _i * 8192), 16, 0, 0); } while (0)
; #define PG8_LDA(dst, b, h) do { _Pragma("unroll") for (int m = 0; m < 4; ++m) _Pragma("unroll") for (int k = 0; k < 2; ++k) dst[m][k] = *(const LAS bf16x8*)(lds + PG8_SA(b, h) + aoff + m * 2048 + k * 1024); } while (0)
; #define PG8_LDB(dst, b, h) do { _Pragma("unroll") for (int n = 0; n < 2; ++n) _Pragma("unroll") for (int k = 0; k < 2; ++k) dst[n][k] = *(const LAS bf16x8*)(lds + PG8_SB(b, h) + boff + n * 2048 + k * 1024); } while (0)
; #define PG8_MMA(ai, bj, At, Bt) do { __builtin_amdgcn_s_setprio(1); _Pragma("unroll") for (int m = 0; m < 4; ++m) _Pragma("unroll") for (int n = 0; n < 2; ++n) _Pragma("unroll") for (int k = 0; k < 2; ++k) \
;         acc[ai][bj][m][n] = __builtin_amdgcn_mfma_f32_16x16x32_bf16(Bt[n][k], At[m][k], acc[ai][bj][m][n], 0, 0, 0); __builtin_amdgcn_s_setprio(0); } while (0)
; #define PG8_WAIT_V(n) asm volatile("s_waitcnt vmcnt(" #n ")" ::: "memory")
; #define PG8_WAIT_L(n) asm volatile("s_waitcnt lgkmcnt(" #n ")" ::: "memory")
; #define PG8_BAR __builtin_amdgcn_s_barrier()
; #define PG8_SCHED __builtin_amdgcn_sched_barrier(0)
; template <class Epi>
; __device__ __forceinline__ void gemm_phase(LAS unsigned char* lds, const Gemm g, const StaticOrder& S, const Epi& E, const int tid) {
;     ...
;             PG8_WAIT_V(8); PG8_WAIT_L(0); PG8_BAR; PG8_MMA(1, 0, At, B0); PG8_MMA(1, 1, At, B1); PG8_BAR; PG8_SCHED;
;             PG8_LDB(B0, 1, 0); PG8_LDB(B1, 1, 1); PG8_SCHED; PG8_LDA(At, 1, 0); PG8_STAGE(PG8_SA(0, 1), a2 + hstep, voffA);
;             PG8_WAIT_V(8); PG8_WAIT_L(0); PG8_BAR; PG8_MMA(0, 0, At, B0); PG8_MMA(0, 1, At, B1); PG8_BAR; PG8_SCHED;
	s_setprio 1
	s_waitcnt lgkmcnt(0)
	v_mfma_f32_16x16x32_bf16 v[62:65], v[150:153], v[216:219], v[62:65]
	v_mfma_f32_16x16x32_bf16 v[58:61], v[158:161], v[216:219], v[58:61]
	v_mfma_f32_16x16x32_bf16 v[46:49], v[150:153], v[224:227], v[46:49]
	v_mfma_f32_16x16x32_bf16 v[42:45], v[158:161], v[224:227], v[42:45]
	v_mfma_f32_16x16x32_bf16 v[30:33], v[150:153], v[232:235], v[30:33]
	v_mfma_f32_16x16x32_bf16 v[26:29], v[158:161], v[232:235], v[26:29]
	v_mfma_f32_16x16x32_bf16 v[14:17], v[150:153], v[240:243], v[14:17]
	v_mfma_f32_16x16x32_bf16 v[10:13], v[158:161], v[240:243], v[10:13]
	v_mfma_f32_16x16x32_bf16 v[62:65], v[154:157], v[220:223], v[62:65]
	v_mfma_f32_16x16x32_bf16 v[58:61], v[186:189], v[220:223], v[58:61]
	v_mfma_f32_16x16x32_bf16 v[46:49], v[154:157], v[228:231], v[46:49]
	v_mfma_f32_16x16x32_bf16 v[42:45], v[186:189], v[228:231], v[42:45]
	v_mfma_f32_16x16x32_bf16 v[30:33], v[154:157], v[236:239], v[30:33]
	v_mfma_f32_16x16x32_bf16 v[26:29], v[186:189], v[236:239], v[26:29]
	v_mfma_f32_16x16x32_bf16 v[14:17], v[154:157], v[244:247], v[14:17]
	v_mfma_f32_16x16x32_bf16 v[10:13], v[186:189], v[244:247], v[10:13]
	s_setprio 0
	s_setprio 1
	v_mfma_f32_16x16x32_bf16 v[54:57], v[190:193], v[216:219], v[54:57]
	v_mfma_f32_16x16x32_bf16 v[50:53], v[198:201], v[216:219], v[50:53]
	v_mfma_f32_16x16x32_bf16 v[38:41], v[190:193], v[224:227], v[38:41]
	v_mfma_f32_16x16x32_bf16 v[34:37], v[198:201], v[224:227], v[34:37]
	v_mfma_f32_16x16x32_bf16 v[22:25], v[190:193], v[232:235], v[22:25]
	v_mfma_f32_16x16x32_bf16 v[18:21], v[198:201], v[232:235], v[18:21]
	v_mfma_f32_16x16x32_bf16 v[6:9], v[190:193], v[240:243], v[6:9]
	v_mfma_f32_16x16x32_bf16 v[2:5], v[198:201], v[240:243], v[2:5]
	v_mfma_f32_16x16x32_bf16 v[54:57], v[194:197], v[220:223], v[54:57]
	v_mfma_f32_16x16x32_bf16 v[50:53], v[212:215], v[220:223], v[50:53]
	v_mfma_f32_16x16x32_bf16 v[38:41], v[194:197], v[228:231], v[38:41]
	v_mfma_f32_16x16x32_bf16 v[34:37], v[212:215], v[228:231], v[34:37]
	v_mfma_f32_16x16x32_bf16 v[22:25], v[194:197], v[236:239], v[22:25]
	v_mfma_f32_16x16x32_bf16 v[18:21], v[212:215], v[236:239], v[18:21]
	v_mfma_f32_16x16x32_bf16 v[6:9], v[194:197], v[244:247], v[6:9]
	v_mfma_f32_16x16x32_bf16 v[2:5], v[212:215], v[244:247], v[2:5]
	s_setprio 0
	s_barrier
	s_add_i32 s44, 0, 0x18000
	v_add_u32_e32 v0, s44, v149
	s_add_i32 s45, 0, 0x1c000
	ds_read_b128 v[150:153], v0
	ds_read_b128 v[154:157], v0 offset:1024
	ds_read_b128 v[158:161], v0 offset:2048
	ds_read_b128 v[186:189], v0 offset:3072
	v_add_u32_e32 v0, s45, v149
	ds_read_b128 v[190:193], v0
	ds_read_b128 v[194:197], v0 offset:1024
	ds_read_b128 v[198:201], v0 offset:2048
	ds_read_b128 v[212:215], v0 offset:3072
	s_add_u32 s34, s34, 0x80000
	s_addc_u32 s35, s35, 0
	s_mov_b32 m0, s59
	v_lshl_add_u64 v[176:177], s[34:35], 0, v[130:131]
	ds_read_b128 v[216:219], v184 offset:32768
	global_load_lds_dwordx4 v[176:177], off
	ds_read_b128 v[220:223], v184 offset:33792
	v_lshl_add_u64 v[176:177], s[34:35], 0, v[134:135]
	s_mov_b32 m0, s60
	s_nop 0
	global_load_lds_dwordx4 v[176:177], off
	ds_read_b128 v[224:227], v184 offset:34816
	ds_read_b128 v[228:231], v184 offset:35840
	ds_read_b128 v[232:235], v184 offset:36864
	ds_read_b128 v[236:239], v184 offset:37888
	ds_read_b128 v[240:243], v184 offset:38912
	ds_read_b128 v[244:247], v184 offset:39936
	s_waitcnt vmcnt(8)
	s_waitcnt lgkmcnt(0)
	s_barrier
	s_setprio 1
	s_waitcnt lgkmcnt(0)
	v_mfma_f32_16x16x32_bf16 v[126:129], v[150:153], v[216:219], v[126:129]
	v_mfma_f32_16x16x32_bf16 v[122:125], v[158:161], v[216:219], v[122:125]
	v_mfma_f32_16x16x32_bf16 v[110:113], v[150:153], v[224:227], v[110:113]
	v_mfma_f32_16x16x32_bf16 v[106:109], v[158:161], v[224:227], v[106:109]
	v_mfma_f32_16x16x32_bf16 v[94:97], v[150:153], v[232:235], v[94:97]
	v_mfma_f32_16x16x32_bf16 v[90:93], v[158:161], v[232:235], v[90:93]
	v_mfma_f32_16x16x32_bf16 v[78:81], v[150:153], v[240:243], v[78:81]
	v_mfma_f32_16x16x32_bf16 v[74:77], v[158:161], v[240:243], v[74:77]
	v_mfma_f32_16x16x32_bf16 v[126:129], v[154:157], v[220:223], v[126:129]
	v_mfma_f32_16x16x32_bf16 v[122:125], v[186:189], v[220:223], v[122:125]
	v_mfma_f32_16x16x32_bf16 v[110:113], v[154:157], v[228:231], v[110:113]
	v_mfma_f32_16x16x32_bf16 v[106:109], v[186:189], v[228:231], v[106:109]
	v_mfma_f32_16x16x32_bf16 v[94:97], v[154:157], v[236:239], v[94:97]
	v_mfma_f32_16x16x32_bf16 v[90:93], v[186:189], v[236:239], v[90:93]
	v_mfma_f32_16x16x32_bf16 v[78:81], v[154:157], v[244:247], v[78:81]
	v_mfma_f32_16x16x32_bf16 v[74:77], v[186:189], v[244:247], v[74:77]
	s_setprio 0
	s_setprio 1
	v_mfma_f32_16x16x32_bf16 v[118:121], v[190:193], v[216:219], v[118:121]
	v_mfma_f32_16x16x32_bf16 v[114:117], v[198:201], v[216:219], v[114:117]
	v_mfma_f32_16x16x32_bf16 v[102:105], v[190:193], v[224:227], v[102:105]
	v_mfma_f32_16x16x32_bf16 v[98:101], v[198:201], v[224:227], v[98:101]
	v_mfma_f32_16x16x32_bf16 v[86:89], v[190:193], v[232:235], v[86:89]
	v_mfma_f32_16x16x32_bf16 v[82:85], v[198:201], v[232:235], v[82:85]
	v_mfma_f32_16x16x32_bf16 v[70:73], v[190:193], v[240:243], v[70:73]
	v_mfma_f32_16x16x32_bf16 v[66:69], v[198:201], v[240:243], v[66:69]
	v_mfma_f32_16x16x32_bf16 v[118:121], v[194:197], v[220:223], v[118:121]
	v_mfma_f32_16x16x32_bf16 v[114:117], v[212:215], v[220:223], v[114:117]
	v_mfma_f32_16x16x32_bf16 v[102:105], v[194:197], v[228:231], v[102:105]
	v_mfma_f32_16x16x32_bf16 v[98:101], v[212:215], v[228:231], v[98:101]
	v_mfma_f32_16x16x32_bf16 v[86:89], v[194:197], v[236:239], v[86:89]
	v_mfma_f32_16x16x32_bf16 v[82:85], v[212:215], v[236:239], v[82:85]
	v_mfma_f32_16x16x32_bf16 v[70:73], v[194:197], v[244:247], v[70:73]
	v_mfma_f32_16x16x32_bf16 v[66:69], v[212:215], v[244:247], v[66:69]
	s_setprio 0
	s_barrier
; #define PG8_STAGE(bufoff, gbase, voff) do { _Pragma("unroll") for (int _i = 0; _i < 2; ++_i) \
;         __builtin_amdgcn_global_load_lds((const unsigned*)((const char*)(gbase) + (voff)[_i]), (LAS unsigned*)(lds + (bufoff) + ldsw + _i * 8192), 16, 0, 0); } while (0)
; #define PG8_LDA(dst, b, h) do { _Pragma("unroll") for (int m = 0; m < 4; ++m) _Pragma("unroll") for (int k = 0; k < 2; ++k) dst[m][k] = *(const LAS bf16x8*)(lds + PG8_SA(b, h) + aoff + m * 2048 + k * 1024); } while (0)
; #define PG8_MMA(ai, bj, At, Bt) do { __builtin_amdgcn_s_setprio(1); _Pragma("unroll") for (int m = 0; m < 4; ++m) _Pragma("unroll") for (int n = 0; n < 2; ++n) _Pragma("unroll") for (int k = 0; k < 2; ++k) \
;         acc[ai][bj][m][n] = __builtin_amdgcn_mfma_f32_16x16x32_bf16(Bt[n][k], At[m][k], acc[ai][bj][m][n], 0, 0, 0); __builtin_amdgcn_s_setprio(0); } while (0)
; #define PG8_WAIT_V(n) asm volatile("s_waitcnt vmcnt(" #n ")" ::: "memory")
; #define PG8_WAIT_L(n) asm volatile("s_waitcnt lgkmcnt(" #n ")" ::: "memory")
; #define PG8_BAR __builtin_amdgcn_s_barrier()
; #define PG8_SCHED __builtin_amdgcn_sched_barrier(0)
; template <class Epi>
; __device__ __forceinline__ void gemm_phase(LAS unsigned char* lds, const Gemm g, const StaticOrder& S, const Epi& E, const int tid) {
;     ...
;             PG8_LDA(At, 1, 1); PG8_STAGE(PG8_SB(1, 0), b3, voffB); PG8_STAGE(PG8_SB(1, 1), b3 + bhs, voffB); PG8_STAGE(PG8_SA(1, 0), a3, voffA);
;             PG8_WAIT_V(8); PG8_WAIT_L(0); PG8_BAR; PG8_MMA(1, 0, At, B0); PG8_MMA(1, 1, At, B1); PG8_BAR; PG8_SCHED;
;     ...
;         if (ALIGN_EPI) { if (wr == 0) PG8_BAR; }
	s_add_i32 s34, s44, s56
	v_lshl_add_u64 v[162:163], v[162:163], 0, s[70:71]
	s_mov_b32 m0, s34
	ds_read_b128 v[216:219], v184 offset:49152
	global_load_lds_dwordx4 v[162:163], off
	ds_read_b128 v[220:223], v184 offset:50176
	s_add_i32 m0, s34, 0x2000
	s_add_u32 s28, s28, 0x8080
	v_lshl_add_u64 v[162:163], v[248:249], 0, s[70:71]
	s_addc_u32 s29, s29, 0
	s_add_i32 s34, s45, s56
	global_load_lds_dwordx4 v[162:163], off
	ds_read_b128 v[224:227], v184 offset:51200
	v_lshl_add_u64 v[162:163], s[28:29], 0, v[132:133]
	s_mov_b32 m0, s34
	s_nop 0
	global_load_lds_dwordx4 v[162:163], off
	ds_read_b128 v[228:231], v184 offset:52224
	v_lshl_add_u64 v[162:163], s[28:29], 0, v[136:137]
	s_add_i32 m0, s34, 0x2000
	s_nop 0
	global_load_lds_dwordx4 v[162:163], off
	ds_read_b128 v[232:235], v184 offset:53248
	v_lshl_add_u64 v[162:163], v[172:173], 0, s[70:71]
	s_mov_b32 m0, s61
	s_nop 0
	global_load_lds_dwordx4 v[162:163], off
	ds_read_b128 v[236:239], v184 offset:54272
	v_lshl_add_u64 v[162:163], v[174:175], 0, s[70:71]
	s_mov_b32 m0, s62
	s_nop 0
	global_load_lds_dwordx4 v[162:163], off
	ds_read_b128 v[240:243], v184 offset:55296
	ds_read_b128 v[244:247], v184 offset:56320
	s_waitcnt vmcnt(8)
	s_waitcnt lgkmcnt(0)
	s_barrier
	s_setprio 1
	s_waitcnt lgkmcnt(0)
	v_mfma_f32_16x16x32_bf16 v[62:65], v[150:153], v[216:219], v[62:65]
	v_mfma_f32_16x16x32_bf16 v[58:61], v[158:161], v[216:219], v[58:61]
	v_mfma_f32_16x16x32_bf16 v[46:49], v[150:153], v[224:227], v[46:49]
	v_mfma_f32_16x16x32_bf16 v[42:45], v[158:161], v[224:227], v[42:45]
	v_mfma_f32_16x16x32_bf16 v[30:33], v[150:153], v[232:235], v[30:33]
	v_mfma_f32_16x16x32_bf16 v[26:29], v[158:161], v[232:235], v[26:29]
	v_mfma_f32_16x16x32_bf16 v[14:17], v[150:153], v[240:243], v[14:17]
	v_mfma_f32_16x16x32_bf16 v[10:13], v[158:161], v[240:243], v[10:13]
	v_mfma_f32_16x16x32_bf16 v[62:65], v[154:157], v[220:223], v[62:65]
	v_mfma_f32_16x16x32_bf16 v[58:61], v[186:189], v[220:223], v[58:61]
	v_mfma_f32_16x16x32_bf16 v[46:49], v[154:157], v[228:231], v[46:49]
	v_mfma_f32_16x16x32_bf16 v[42:45], v[186:189], v[228:231], v[42:45]
	v_mfma_f32_16x16x32_bf16 v[30:33], v[154:157], v[236:239], v[30:33]
	v_mfma_f32_16x16x32_bf16 v[26:29], v[186:189], v[236:239], v[26:29]
	v_mfma_f32_16x16x32_bf16 v[14:17], v[154:157], v[244:247], v[14:17]
	v_mfma_f32_16x16x32_bf16 v[10:13], v[186:189], v[244:247], v[10:13]
	s_setprio 0
	s_setprio 1
	v_mfma_f32_16x16x32_bf16 v[54:57], v[190:193], v[216:219], v[54:57]
	v_mfma_f32_16x16x32_bf16 v[50:53], v[198:201], v[216:219], v[50:53]
	v_mfma_f32_16x16x32_bf16 v[38:41], v[190:193], v[224:227], v[38:41]
	v_mfma_f32_16x16x32_bf16 v[34:37], v[198:201], v[224:227], v[34:37]
	v_mfma_f32_16x16x32_bf16 v[22:25], v[190:193], v[232:235], v[22:25]
	v_mfma_f32_16x16x32_bf16 v[18:21], v[198:201], v[232:235], v[18:21]
	v_mfma_f32_16x16x32_bf16 v[6:9], v[190:193], v[240:243], v[6:9]
	v_mfma_f32_16x16x32_bf16 v[2:5], v[198:201], v[240:243], v[2:5]
	v_mfma_f32_16x16x32_bf16 v[54:57], v[194:197], v[220:223], v[54:57]
	v_mfma_f32_16x16x32_bf16 v[50:53], v[212:215], v[220:223], v[50:53]
	v_mfma_f32_16x16x32_bf16 v[38:41], v[194:197], v[228:231], v[38:41]
	v_mfma_f32_16x16x32_bf16 v[34:37], v[212:215], v[228:231], v[34:37]
	v_mfma_f32_16x16x32_bf16 v[22:25], v[194:197], v[236:239], v[22:25]
	v_mfma_f32_16x16x32_bf16 v[18:21], v[212:215], v[236:239], v[18:21]
	v_mfma_f32_16x16x32_bf16 v[6:9], v[194:197], v[244:247], v[6:9]
	v_mfma_f32_16x16x32_bf16 v[2:5], v[212:215], v[244:247], v[2:5]
	s_setprio 0
	s_barrier
	s_add_i32 s39, s39, 2
	s_add_u32 s37, s37, 0x100
	s_addc_u32 s38, s38, 0
	s_add_u32 s26, s26, 0x100
	s_addc_u32 s27, s27, 0
	s_cmp_gt_u32 s39, 29
	s_cbranch_scc0 .LBB0_546
	s_and_b64 vcc, exec, s[14:15]
	s_cbranch_vccz .LBB0_549
	s_barrier

; #define PG8_STAGE(bufoff, gbase, voff) do { _Pragma("unroll") for (int _i = 0; _i < 2; ++_i) \
;         __builtin_amdgcn_global_load_lds((const unsigned*)((const char*)(gbase) + (voff)[_i]), (LAS unsigned*)(lds + (bufoff) + ldsw + _i * 8192), 16, 0, 0); } while (0)
; #define PG8_LDA(dst, b, h) do { _Pragma("unroll") for (int m = 0; m < 4; ++m) _Pragma("unroll") for (int k = 0; k < 2; ++k) dst[m][k] = *(const LAS bf16x8*)(lds + PG8_SA(b, h) + aoff + m * 2048 + k * 1024); } while (0)
; #define PG8_LDB(dst, b, h) do { _Pragma("unroll") for (int n = 0; n < 2; ++n) _Pragma("unroll") for (int k = 0; k < 2; ++k) dst[n][k] = *(const LAS bf16x8*)(lds + PG8_SB(b, h) + boff + n * 2048 + k * 1024); } while (0)
; #define PG8_WAIT_V(n) asm volatile("s_waitcnt vmcnt(" #n ")" ::: "memory")
; #define PG8_WAIT_L(n) asm volatile("s_waitcnt lgkmcnt(" #n ")" ::: "memory")
; #define PG8_BAR __builtin_amdgcn_s_barrier()
; #define PG8_SCHED __builtin_amdgcn_sched_barrier(0)
; template <class Epi>
; __device__ __forceinline__ void gemm_phase(LAS unsigned char* lds, const Gemm g, const StaticOrder& S, const Epi& E, const int tid) {
;     ...
;             const bool last = (t == ntt - 2);
;             const bool s1 = Epi::TWO && (t >= nt), s2 = Epi::TWO && (t + 2 >= nt);
;             const char* a1 = (s1 ? cA2 + (size_t)(t - nt + 1) * kstep : cA + (size_t)(t + 1) * kstep);
;             const char* a2 = last ? nA : (s2 ? cA2 + (size_t)(t + 2 - nt) * kstep : cA + (size_t)(t + 2) * kstep);
;             const char* b2 = last ? nB : (s2 ? cB2 + (size_t)(t + 2 - nt) * kstep : cB + (size_t)(t + 2) * kstep);
;             const char* a3 = a2 + kstep; const char* b3 = b2 + kstep;
;             if constexpr (Epi::TWO) { if (t == nt) E.mid(acc, cur, wr, wc, fr, fq); }
;             if constexpr (SP2) {
;             PG8_LDB(B0, 0, 0); PG8_LDB(B1, 0, 1); PG8_SCHED; PG8_LDA(At, 0, 0); PG8_STAGE(PG8_SA(1, 1), a1 + hstep, voffA);
;             PG8_WAIT_V(8); PG8_WAIT_L(0); PG8_BAR; PG8_MMA(0, 0, At, B0); PG8_MMA(0, 1, At, B1); PG8_BAR; PG8_SCHED;
;             PG8_LDA(At, 0, 1); PG8_STAGE(PG8_SB(0, 0), b2, voffB); PG8_STAGE(PG8_SB(0, 1), b2 + bhs, voffB); PG8_STAGE(PG8_SA(0, 0), a2, voffA);
;             PG8_WAIT_V(8); PG8_WAIT_L(0); PG8_BAR; PG8_MMA(1, 0, At, B0); PG8_MMA(1, 1, At, B1); PG8_BAR; PG8_SCHED;
.LBB0_844:
	s_add_u32 s28, s26, 0xfff80080
	s_addc_u32 s29, s27, -1
	s_add_i32 s48, 0, 0x10000
	s_cmp_eq_u32 s47, 28
	s_cselect_b32 s31, s15, s29
	s_cselect_b32 s30, s43, s28
	v_add_u32_e32 v145, s48, v142
	s_cselect_b32 s29, s13, s46
	s_cselect_b32 s28, s44, s45
	s_add_i32 s50, 0, 0x14000
	ds_read_b128 v[146:149], v145
	ds_read_b128 v[150:153], v145 offset:1024
	ds_read_b128 v[154:157], v145 offset:2048
	ds_read_b128 v[158:161], v145 offset:3072
	v_add_u32_e32 v145, s50, v142
	ds_read_b128 v[162:165], v145
	ds_read_b128 v[166:169], v145 offset:1024
	ds_read_b128 v[178:181], v145 offset:2048
	ds_read_b128 v[182:185], v145 offset:3072
	v_lshl_add_u64 v[172:173], s[26:27], 0, v[138:139]
	s_add_i32 m0, s23, 0xc000
	ds_read_b128 v[186:189], v144
	global_load_lds_dwordx4 v[172:173], off
	ds_read_b128 v[190:193], v144 offset:1024
	v_lshl_add_u64 v[172:173], s[26:27], 0, v[136:137]
	s_add_i32 m0, s23, 0xe000
	s_nop 0
	global_load_lds_dwordx4 v[172:173], off
	ds_read_b128 v[194:197], v144 offset:2048
	ds_read_b128 v[198:201], v144 offset:3072
	ds_read_b128 v[212:215], v144 offset:4096
	ds_read_b128 v[216:219], v144 offset:5120
	ds_read_b128 v[220:223], v144 offset:6144
	ds_read_b128 v[224:227], v144 offset:7168
	s_waitcnt vmcnt(8)
	s_waitcnt lgkmcnt(0)
	s_barrier
	s_setprio 1
	s_waitcnt lgkmcnt(0)
	v_mfma_f32_16x16x32_bf16 v[126:129], v[146:149], v[186:189], v[126:129]
	v_mfma_f32_16x16x32_bf16 v[122:125], v[154:157], v[186:189], v[122:125]
	v_mfma_f32_16x16x32_bf16 v[118:121], v[146:149], v[194:197], v[118:121]
	v_mfma_f32_16x16x32_bf16 v[110:113], v[154:157], v[194:197], v[110:113]
	v_mfma_f32_16x16x32_bf16 v[102:105], v[146:149], v[212:215], v[102:105]
	v_mfma_f32_16x16x32_bf16 v[94:97], v[154:157], v[212:215], v[94:97]
	v_mfma_f32_16x16x32_bf16 v[86:89], v[146:149], v[220:223], v[86:89]
	v_mfma_f32_16x16x32_bf16 v[78:81], v[154:157], v[220:223], v[78:81]
	v_mfma_f32_16x16x32_bf16 v[126:129], v[150:153], v[190:193], v[126:129]
	v_mfma_f32_16x16x32_bf16 v[122:125], v[158:161], v[190:193], v[122:125]
	v_mfma_f32_16x16x32_bf16 v[118:121], v[150:153], v[198:201], v[118:121]
	v_mfma_f32_16x16x32_bf16 v[110:113], v[158:161], v[198:201], v[110:113]
	v_mfma_f32_16x16x32_bf16 v[102:105], v[150:153], v[216:219], v[102:105]
	v_mfma_f32_16x16x32_bf16 v[94:97], v[158:161], v[216:219], v[94:97]
	v_mfma_f32_16x16x32_bf16 v[86:89], v[150:153], v[224:227], v[86:89]
	v_mfma_f32_16x16x32_bf16 v[78:81], v[158:161], v[224:227], v[78:81]
	s_setprio 0
	s_setprio 1
	v_mfma_f32_16x16x32_bf16 v[114:117], v[162:165], v[186:189], v[114:117]
	v_mfma_f32_16x16x32_bf16 v[106:109], v[178:181], v[186:189], v[106:109]
	v_mfma_f32_16x16x32_bf16 v[98:101], v[162:165], v[194:197], v[98:101]
	v_mfma_f32_16x16x32_bf16 v[90:93], v[178:181], v[194:197], v[90:93]
	v_mfma_f32_16x16x32_bf16 v[82:85], v[162:165], v[212:215], v[82:85]
	v_mfma_f32_16x16x32_bf16 v[74:77], v[178:181], v[212:215], v[74:77]
	v_mfma_f32_16x16x32_bf16 v[70:73], v[162:165], v[220:223], v[70:73]
	v_mfma_f32_16x16x32_bf16 v[66:69], v[178:181], v[220:223], v[66:69]
	v_mfma_f32_16x16x32_bf16 v[114:117], v[166:169], v[190:193], v[114:117]
	v_mfma_f32_16x16x32_bf16 v[106:109], v[182:185], v[190:193], v[106:109]
	v_mfma_f32_16x16x32_bf16 v[98:101], v[166:169], v[198:201], v[98:101]
	v_mfma_f32_16x16x32_bf16 v[90:93], v[182:185], v[198:201], v[90:93]
	v_mfma_f32_16x16x32_bf16 v[82:85], v[166:169], v[216:219], v[82:85]
	v_mfma_f32_16x16x32_bf16 v[74:77], v[182:185], v[216:219], v[74:77]
	v_mfma_f32_16x16x32_bf16 v[70:73], v[166:169], v[224:227], v[70:73]
	v_mfma_f32_16x16x32_bf16 v[66:69], v[182:185], v[224:227], v[66:69]
	s_setprio 0
	s_barrier
	s_add_i32 s48, s48, s37
	v_lshl_add_u64 v[172:173], s[28:29], 0, v[0:1]
	s_mov_b32 m0, s48
	ds_read_b128 v[186:189], v144 offset:16384
	global_load_lds_dwordx4 v[172:173], off
	ds_read_b128 v[190:193], v144 offset:17408
	s_add_i32 m0, s48, 0x2000
	s_add_u32 s48, s28, 0x8000
	v_lshl_add_u64 v[174:175], s[28:29], 0, v[134:135]
	s_addc_u32 s49, s29, 0
	s_add_i32 s50, s50, s37
	global_load_lds_dwordx4 v[174:175], off
	ds_read_b128 v[194:197], v144 offset:18432
	v_lshl_add_u64 v[176:177], s[48:49], 0, v[0:1]
	s_mov_b32 m0, s50
	v_lshl_add_u64 v[228:229], s[30:31], 0, v[132:133]
	global_load_lds_dwordx4 v[176:177], off
	ds_read_b128 v[198:201], v144 offset:19456
	v_lshl_add_u64 v[176:177], s[48:49], 0, v[134:135]
	s_add_i32 m0, s50, 0x2000
	s_nop 0
	global_load_lds_dwordx4 v[176:177], off
	ds_read_b128 v[212:215], v144 offset:20480
	v_lshl_add_u64 v[176:177], s[30:31], 0, v[130:131]
	s_mov_b32 m0, s23
	s_nop 0
	global_load_lds_dwordx4 v[176:177], off
	ds_read_b128 v[216:219], v144 offset:21504
	s_mov_b32 m0, s25
	s_nop 0
	global_load_lds_dwordx4 v[228:229], off
	ds_read_b128 v[220:223], v144 offset:22528
	ds_read_b128 v[224:227], v144 offset:23552
	s_waitcnt vmcnt(8)
	s_waitcnt lgkmcnt(0)
	s_barrier
; #define PG8_STAGE(bufoff, gbase, voff) do { _Pragma("unroll") for (int _i = 0; _i < 2; ++_i) \
;         __builtin_amdgcn_global_load_lds((const unsigned*)((const char*)(gbase) + (voff)[_i]), (LAS unsigned*)(lds + (bufoff) + ldsw + _i * 8192), 16, 0, 0); } while (0)
; #define PG8_LDA(dst, b, h) do { _Pragma("unroll") for (int m = 0; m < 4; ++m) _Pragma("unroll") for (int k = 0; k < 2; ++k) dst[m][k] = *(const LAS bf16x8*)(lds + PG8_SA(b, h) + aoff + m * 2048 + k * 1024); } while (0)
; #define PG8_LDB(dst, b, h) do { _Pragma("unroll") for (int n = 0; n < 2; ++n) _Pragma("unroll") for (int k = 0; k < 2; ++k) dst[n][k] = *(const LAS bf16x8*)(lds + PG8_SB(b, h) + boff + n * 2048 + k * 1024); } while (0)
; #define PG8_MMA(ai, bj, At, Bt) do { __builtin_amdgcn_s_setprio(1); _Pragma("unroll") for (int m = 0; m < 4; ++m) _Pragma("unroll") for (int n = 0; n < 2; ++n) _Pragma("unroll") for (int k = 0; k < 2; ++k) \
;         acc[ai][bj][m][n] = __builtin_amdgcn_mfma_f32_16x16x32_bf16(Bt[n][k], At[m][k], acc[ai][bj][m][n], 0, 0, 0); __builtin_amdgcn_s_setprio(0); } while (0)
; #define PG8_WAIT_V(n) asm volatile("s_waitcnt vmcnt(" #n ")" ::: "memory")
; #define PG8_WAIT_L(n) asm volatile("s_waitcnt lgkmcnt(" #n ")" ::: "memory")
; #define PG8_BAR __builtin_amdgcn_s_barrier()
; #define PG8_SCHED __builtin_amdgcn_sched_barrier(0)
; template <class Epi>
; __device__ __forceinline__ void gemm_phase(LAS unsigned char* lds, const Gemm g, const StaticOrder& S, const Epi& E, const int tid) {
;     ...
;             PG8_WAIT_V(8); PG8_WAIT_L(0); PG8_BAR; PG8_MMA(1, 0, At, B0); PG8_MMA(1, 1, At, B1); PG8_BAR; PG8_SCHED;
;             PG8_LDB(B0, 1, 0); PG8_LDB(B1, 1, 1); PG8_SCHED; PG8_LDA(At, 1, 0); PG8_STAGE(PG8_SA(0, 1), a2 + hstep, voffA);
;             PG8_WAIT_V(8); PG8_WAIT_L(0); PG8_BAR; PG8_MMA(0, 0, At, B0); PG8_MMA(0, 1, At, B1); PG8_BAR; PG8_SCHED;
	s_setprio 1
	s_waitcnt lgkmcnt(0)
	v_mfma_f32_16x16x32_bf16 v[62:65], v[146:149], v[186:189], v[62:65]
	v_mfma_f32_16x16x32_bf16 v[58:61], v[154:157], v[186:189], v[58:61]
	v_mfma_f32_16x16x32_bf16 v[54:57], v[146:149], v[194:197], v[54:57]
	v_mfma_f32_16x16x32_bf16 v[46:49], v[154:157], v[194:197], v[46:49]
	v_mfma_f32_16x16x32_bf16 v[38:41], v[146:149], v[212:215], v[38:41]
	v_mfma_f32_16x16x32_bf16 v[30:33], v[154:157], v[212:215], v[30:33]
	v_mfma_f32_16x16x32_bf16 v[22:25], v[146:149], v[220:223], v[22:25]
	v_mfma_f32_16x16x32_bf16 v[14:17], v[154:157], v[220:223], v[14:17]
	v_mfma_f32_16x16x32_bf16 v[62:65], v[150:153], v[190:193], v[62:65]
	v_mfma_f32_16x16x32_bf16 v[58:61], v[158:161], v[190:193], v[58:61]
	v_mfma_f32_16x16x32_bf16 v[54:57], v[150:153], v[198:201], v[54:57]
	v_mfma_f32_16x16x32_bf16 v[46:49], v[158:161], v[198:201], v[46:49]
	v_mfma_f32_16x16x32_bf16 v[38:41], v[150:153], v[216:219], v[38:41]
	v_mfma_f32_16x16x32_bf16 v[30:33], v[158:161], v[216:219], v[30:33]
	v_mfma_f32_16x16x32_bf16 v[22:25], v[150:153], v[224:227], v[22:25]
	v_mfma_f32_16x16x32_bf16 v[14:17], v[158:161], v[224:227], v[14:17]
	s_setprio 0
	s_setprio 1
	v_mfma_f32_16x16x32_bf16 v[50:53], v[162:165], v[186:189], v[50:53]
	v_mfma_f32_16x16x32_bf16 v[42:45], v[178:181], v[186:189], v[42:45]
	v_mfma_f32_16x16x32_bf16 v[34:37], v[162:165], v[194:197], v[34:37]
	v_mfma_f32_16x16x32_bf16 v[26:29], v[178:181], v[194:197], v[26:29]
	v_mfma_f32_16x16x32_bf16 v[18:21], v[162:165], v[212:215], v[18:21]
	v_mfma_f32_16x16x32_bf16 v[10:13], v[178:181], v[212:215], v[10:13]
	v_mfma_f32_16x16x32_bf16 v[6:9], v[162:165], v[220:223], v[6:9]
	v_mfma_f32_16x16x32_bf16 v[2:5], v[178:181], v[220:223], v[2:5]
	v_mfma_f32_16x16x32_bf16 v[50:53], v[166:169], v[190:193], v[50:53]
	v_mfma_f32_16x16x32_bf16 v[42:45], v[182:185], v[190:193], v[42:45]
	v_mfma_f32_16x16x32_bf16 v[34:37], v[166:169], v[198:201], v[34:37]
	v_mfma_f32_16x16x32_bf16 v[26:29], v[182:185], v[198:201], v[26:29]
	v_mfma_f32_16x16x32_bf16 v[18:21], v[166:169], v[216:219], v[18:21]
	v_mfma_f32_16x16x32_bf16 v[10:13], v[182:185], v[216:219], v[10:13]
	v_mfma_f32_16x16x32_bf16 v[6:9], v[166:169], v[224:227], v[6:9]
	v_mfma_f32_16x16x32_bf16 v[2:5], v[182:185], v[224:227], v[2:5]
	s_setprio 0
	s_barrier
	s_add_i32 s48, 0, 0x18000
	v_add_u32_e32 v145, s48, v142
	s_add_i32 s49, 0, 0x1c000
	ds_read_b128 v[146:149], v145
	ds_read_b128 v[150:153], v145 offset:1024
	ds_read_b128 v[154:157], v145 offset:2048
	ds_read_b128 v[158:161], v145 offset:3072
	v_add_u32_e32 v145, s49, v142
	ds_read_b128 v[162:165], v145
	ds_read_b128 v[166:169], v145 offset:1024
	ds_read_b128 v[178:181], v145 offset:2048
	ds_read_b128 v[182:185], v145 offset:3072
	s_add_u32 s30, s30, 0x80000
	s_addc_u32 s31, s31, 0
	s_mov_b32 m0, s38
	v_lshl_add_u64 v[230:231], s[30:31], 0, v[130:131]
	ds_read_b128 v[186:189], v144 offset:32768
	global_load_lds_dwordx4 v[230:231], off
	ds_read_b128 v[190:193], v144 offset:33792
	v_lshl_add_u64 v[230:231], s[30:31], 0, v[132:133]
	s_mov_b32 m0, s39
	s_nop 0
	global_load_lds_dwordx4 v[230:231], off
	ds_read_b128 v[194:197], v144 offset:34816
	ds_read_b128 v[198:201], v144 offset:35840
	ds_read_b128 v[212:215], v144 offset:36864
	ds_read_b128 v[216:219], v144 offset:37888
	ds_read_b128 v[220:223], v144 offset:38912
	ds_read_b128 v[224:227], v144 offset:39936
	s_waitcnt vmcnt(8)
	s_waitcnt lgkmcnt(0)
	s_barrier
	s_setprio 1
	s_waitcnt lgkmcnt(0)
	v_mfma_f32_16x16x32_bf16 v[126:129], v[146:149], v[186:189], v[126:129]
	v_mfma_f32_16x16x32_bf16 v[122:125], v[154:157], v[186:189], v[122:125]
	v_mfma_f32_16x16x32_bf16 v[118:121], v[146:149], v[194:197], v[118:121]
	v_mfma_f32_16x16x32_bf16 v[110:113], v[154:157], v[194:197], v[110:113]
	v_mfma_f32_16x16x32_bf16 v[102:105], v[146:149], v[212:215], v[102:105]
	v_mfma_f32_16x16x32_bf16 v[94:97], v[154:157], v[212:215], v[94:97]
	v_mfma_f32_16x16x32_bf16 v[86:89], v[146:149], v[220:223], v[86:89]
	v_mfma_f32_16x16x32_bf16 v[78:81], v[154:157], v[220:223], v[78:81]
	v_mfma_f32_16x16x32_bf16 v[126:129], v[150:153], v[190:193], v[126:129]
	v_mfma_f32_16x16x32_bf16 v[122:125], v[158:161], v[190:193], v[122:125]
	v_mfma_f32_16x16x32_bf16 v[118:121], v[150:153], v[198:201], v[118:121]
	v_mfma_f32_16x16x32_bf16 v[110:113], v[158:161], v[198:201], v[110:113]
	v_mfma_f32_16x16x32_bf16 v[102:105], v[150:153], v[216:219], v[102:105]
	v_mfma_f32_16x16x32_bf16 v[94:97], v[158:161], v[216:219], v[94:97]
	v_mfma_f32_16x16x32_bf16 v[86:89], v[150:153], v[224:227], v[86:89]
	v_mfma_f32_16x16x32_bf16 v[78:81], v[158:161], v[224:227], v[78:81]
	s_setprio 0
	s_setprio 1
	v_mfma_f32_16x16x32_bf16 v[114:117], v[162:165], v[186:189], v[114:117]
	v_mfma_f32_16x16x32_bf16 v[106:109], v[178:181], v[186:189], v[106:109]
	v_mfma_f32_16x16x32_bf16 v[98:101], v[162:165], v[194:197], v[98:101]
	v_mfma_f32_16x16x32_bf16 v[90:93], v[178:181], v[194:197], v[90:93]
	v_mfma_f32_16x16x32_bf16 v[82:85], v[162:165], v[212:215], v[82:85]
	v_mfma_f32_16x16x32_bf16 v[74:77], v[178:181], v[212:215], v[74:77]
	v_mfma_f32_16x16x32_bf16 v[70:73], v[162:165], v[220:223], v[70:73]
	v_mfma_f32_16x16x32_bf16 v[66:69], v[178:181], v[220:223], v[66:69]
	v_mfma_f32_16x16x32_bf16 v[114:117], v[166:169], v[190:193], v[114:117]
	v_mfma_f32_16x16x32_bf16 v[106:109], v[182:185], v[190:193], v[106:109]
	v_mfma_f32_16x16x32_bf16 v[98:101], v[166:169], v[198:201], v[98:101]
	v_mfma_f32_16x16x32_bf16 v[90:93], v[182:185], v[198:201], v[90:93]
	v_mfma_f32_16x16x32_bf16 v[82:85], v[166:169], v[216:219], v[82:85]
	v_mfma_f32_16x16x32_bf16 v[74:77], v[182:185], v[216:219], v[74:77]
	v_mfma_f32_16x16x32_bf16 v[70:73], v[166:169], v[224:227], v[70:73]
	v_mfma_f32_16x16x32_bf16 v[66:69], v[182:185], v[224:227], v[66:69]
	s_setprio 0
	s_barrier
; #define PG8_STAGE(bufoff, gbase, voff) do { _Pragma("unroll") for (int _i = 0; _i < 2; ++_i) \
;         __builtin_amdgcn_global_load_lds((const unsigned*)((const char*)(gbase) + (voff)[_i]), (LAS unsigned*)(lds + (bufoff) + ldsw + _i * 8192), 16, 0, 0); } while (0)
; #define PG8_LDA(dst, b, h) do { _Pragma("unroll") for (int m = 0; m < 4; ++m) _Pragma("unroll") for (int k = 0; k < 2; ++k) dst[m][k] = *(const LAS bf16x8*)(lds + PG8_SA(b, h) + aoff + m * 2048 + k * 1024); } while (0)
; #define PG8_MMA(ai, bj, At, Bt) do { __builtin_amdgcn_s_setprio(1); _Pragma("unroll") for (int m = 0; m < 4; ++m) _Pragma("unroll") for (int n = 0; n < 2; ++n) _Pragma("unroll") for (int k = 0; k < 2; ++k) \
;         acc[ai][bj][m][n] = __builtin_amdgcn_mfma_f32_16x16x32_bf16(Bt[n][k], At[m][k], acc[ai][bj][m][n], 0, 0, 0); __builtin_amdgcn_s_setprio(0); } while (0)
; #define PG8_WAIT_V(n) asm volatile("s_waitcnt vmcnt(" #n ")" ::: "memory")
; #define PG8_WAIT_L(n) asm volatile("s_waitcnt lgkmcnt(" #n ")" ::: "memory")
; #define PG8_BAR __builtin_amdgcn_s_barrier()
; #define PG8_SCHED __builtin_amdgcn_sched_barrier(0)
; template <class Epi>
; __device__ __forceinline__ void gemm_phase(LAS unsigned char* lds, const Gemm g, const StaticOrder& S, const Epi& E, const int tid) {
;     ...
;             PG8_LDA(At, 1, 1); PG8_STAGE(PG8_SB(1, 0), b3, voffB); PG8_STAGE(PG8_SB(1, 1), b3 + bhs, voffB); PG8_STAGE(PG8_SA(1, 0), a3, voffA);
;             PG8_WAIT_V(8); PG8_WAIT_L(0); PG8_BAR; PG8_MMA(1, 0, At, B0); PG8_MMA(1, 1, At, B1); PG8_BAR; PG8_SCHED;
;     ...
;         if (ALIGN_EPI) { if (wr == 0) PG8_BAR; }
	s_add_i32 s30, s48, s37
	v_lshl_add_u64 v[172:173], v[172:173], 0, s[70:71]
	s_mov_b32 m0, s30
	ds_read_b128 v[186:189], v144 offset:49152
	global_load_lds_dwordx4 v[172:173], off
	ds_read_b128 v[190:193], v144 offset:50176
	s_add_i32 m0, s30, 0x2000
	s_add_u32 s28, s28, 0x8080
	v_lshl_add_u64 v[172:173], v[174:175], 0, s[70:71]
	s_addc_u32 s29, s29, 0
	s_add_i32 s30, s49, s37
	global_load_lds_dwordx4 v[172:173], off
	ds_read_b128 v[194:197], v144 offset:51200
	v_lshl_add_u64 v[172:173], s[28:29], 0, v[0:1]
	s_mov_b32 m0, s30
	s_nop 0
	global_load_lds_dwordx4 v[172:173], off
	ds_read_b128 v[198:201], v144 offset:52224
	v_lshl_add_u64 v[172:173], s[28:29], 0, v[134:135]
	s_add_i32 m0, s30, 0x2000
	s_nop 0
	global_load_lds_dwordx4 v[172:173], off
	ds_read_b128 v[212:215], v144 offset:53248
	v_lshl_add_u64 v[172:173], v[176:177], 0, s[70:71]
	s_mov_b32 m0, s40
	s_nop 0
	global_load_lds_dwordx4 v[172:173], off
	ds_read_b128 v[216:219], v144 offset:54272
	v_lshl_add_u64 v[172:173], v[228:229], 0, s[70:71]
	s_mov_b32 m0, s41
	s_nop 0
	global_load_lds_dwordx4 v[172:173], off
	ds_read_b128 v[220:223], v144 offset:55296
	ds_read_b128 v[224:227], v144 offset:56320
	s_waitcnt vmcnt(8)
	s_waitcnt lgkmcnt(0)
	s_barrier
	s_setprio 1
	s_waitcnt lgkmcnt(0)
	v_mfma_f32_16x16x32_bf16 v[62:65], v[146:149], v[186:189], v[62:65]
	v_mfma_f32_16x16x32_bf16 v[58:61], v[154:157], v[186:189], v[58:61]
	v_mfma_f32_16x16x32_bf16 v[54:57], v[146:149], v[194:197], v[54:57]
	v_mfma_f32_16x16x32_bf16 v[46:49], v[154:157], v[194:197], v[46:49]
	v_mfma_f32_16x16x32_bf16 v[38:41], v[146:149], v[212:215], v[38:41]
	v_mfma_f32_16x16x32_bf16 v[30:33], v[154:157], v[212:215], v[30:33]
	v_mfma_f32_16x16x32_bf16 v[22:25], v[146:149], v[220:223], v[22:25]
	v_mfma_f32_16x16x32_bf16 v[14:17], v[154:157], v[220:223], v[14:17]
	v_mfma_f32_16x16x32_bf16 v[62:65], v[150:153], v[190:193], v[62:65]
	v_mfma_f32_16x16x32_bf16 v[58:61], v[158:161], v[190:193], v[58:61]
	v_mfma_f32_16x16x32_bf16 v[54:57], v[150:153], v[198:201], v[54:57]
	v_mfma_f32_16x16x32_bf16 v[46:49], v[158:161], v[198:201], v[46:49]
	v_mfma_f32_16x16x32_bf16 v[38:41], v[150:153], v[216:219], v[38:41]
	v_mfma_f32_16x16x32_bf16 v[30:33], v[158:161], v[216:219], v[30:33]
	v_mfma_f32_16x16x32_bf16 v[22:25], v[150:153], v[224:227], v[22:25]
	v_mfma_f32_16x16x32_bf16 v[14:17], v[158:161], v[224:227], v[14:17]
	s_setprio 0
	s_setprio 1
	v_mfma_f32_16x16x32_bf16 v[50:53], v[162:165], v[186:189], v[50:53]
	v_mfma_f32_16x16x32_bf16 v[42:45], v[178:181], v[186:189], v[42:45]
	v_mfma_f32_16x16x32_bf16 v[34:37], v[162:165], v[194:197], v[34:37]
	v_mfma_f32_16x16x32_bf16 v[26:29], v[178:181], v[194:197], v[26:29]
	v_mfma_f32_16x16x32_bf16 v[18:21], v[162:165], v[212:215], v[18:21]
	v_mfma_f32_16x16x32_bf16 v[10:13], v[178:181], v[212:215], v[10:13]
	v_mfma_f32_16x16x32_bf16 v[6:9], v[162:165], v[220:223], v[6:9]
	v_mfma_f32_16x16x32_bf16 v[2:5], v[178:181], v[220:223], v[2:5]
	v_mfma_f32_16x16x32_bf16 v[50:53], v[166:169], v[190:193], v[50:53]
	v_mfma_f32_16x16x32_bf16 v[42:45], v[182:185], v[190:193], v[42:45]
	v_mfma_f32_16x16x32_bf16 v[34:37], v[166:169], v[198:201], v[34:37]
	v_mfma_f32_16x16x32_bf16 v[26:29], v[182:185], v[198:201], v[26:29]
	v_mfma_f32_16x16x32_bf16 v[18:21], v[166:169], v[216:219], v[18:21]
	v_mfma_f32_16x16x32_bf16 v[10:13], v[182:185], v[216:219], v[10:13]
	v_mfma_f32_16x16x32_bf16 v[6:9], v[166:169], v[224:227], v[6:9]
	v_mfma_f32_16x16x32_bf16 v[2:5], v[182:185], v[224:227], v[2:5]
	s_setprio 0
	s_barrier
	s_add_i32 s47, s47, 2
	s_add_u32 s45, s45, 0x100
	s_addc_u32 s46, s46, 0
	s_add_u32 s26, s26, 0x100
	s_addc_u32 s27, s27, 0
	s_cmp_gt_u32 s47, 29
	s_cbranch_scc0 .LBB0_844
	s_and_b64 vcc, exec, s[10:11]
	s_cbranch_vccz .LBB0_847
	s_barrier

; #define PG8_STAGE(bufoff, gbase, voff) do { _Pragma("unroll") for (int _i = 0; _i < 2; ++_i) \
;         __builtin_amdgcn_global_load_lds((const unsigned*)((const char*)(gbase) + (voff)[_i]), (LAS unsigned*)(lds + (bufoff) + ldsw + _i * 8192), 16, 0, 0); } while (0)
; #define PG8_LDA(dst, b, h) do { _Pragma("unroll") for (int m = 0; m < 4; ++m) _Pragma("unroll") for (int k = 0; k < 2; ++k) dst[m][k] = *(const LAS bf16x8*)(lds + PG8_SA(b, h) + aoff + m * 2048 + k * 1024); } while (0)
; #define PG8_LDB(dst, b, h) do { _Pragma("unroll") for (int n = 0; n < 2; ++n) _Pragma("unroll") for (int k = 0; k < 2; ++k) dst[n][k] = *(const LAS bf16x8*)(lds + PG8_SB(b, h) + boff + n * 2048 + k * 1024); } while (0)
; #define PG8_WAIT_V(n) asm volatile("s_waitcnt vmcnt(" #n ")" ::: "memory")
; #define PG8_WAIT_L(n) asm volatile("s_waitcnt lgkmcnt(" #n ")" ::: "memory")
; #define PG8_BAR __builtin_amdgcn_s_barrier()
; #define PG8_SCHED __builtin_amdgcn_sched_barrier(0)
; template <class Epi>
; __device__ __forceinline__ void gemm_phase(LAS unsigned char* lds, const Gemm g, const StaticOrder& S, const Epi& E, const int tid) {
;     ...
;             const bool last = (t == ntt - 2);
;             const bool s1 = Epi::TWO && (t >= nt), s2 = Epi::TWO && (t + 2 >= nt);
;             const char* a1 = (s1 ? cA2 + (size_t)(t - nt + 1) * kstep : cA + (size_t)(t + 1) * kstep);
;             const char* a2 = last ? nA : (s2 ? cA2 + (size_t)(t + 2 - nt) * kstep : cA + (size_t)(t + 2) * kstep);
;             const char* b2 = last ? nB : (s2 ? cB2 + (size_t)(t + 2 - nt) * kstep : cB + (size_t)(t + 2) * kstep);
;             const char* a3 = a2 + kstep; const char* b3 = b2 + kstep;
;             if constexpr (Epi::TWO) { if (t == nt) E.mid(acc, cur, wr, wc, fr, fq); }
;             if constexpr (SP2) {
;             PG8_LDB(B0, 0, 0); PG8_LDB(B1, 0, 1); PG8_SCHED; PG8_LDA(At, 0, 0); PG8_STAGE(PG8_SA(1, 1), a1 + hstep, voffA);
;             PG8_WAIT_V(8); PG8_WAIT_L(0); PG8_BAR; PG8_MMA(0, 0, At, B0); PG8_MMA(0, 1, At, B1); PG8_BAR; PG8_SCHED;
;             PG8_LDA(At, 0, 1); PG8_STAGE(PG8_SB(0, 0), b2, voffB); PG8_STAGE(PG8_SB(0, 1), b2 + bhs, voffB); PG8_STAGE(PG8_SA(0, 0), a2, voffA);
;             PG8_WAIT_V(8); PG8_WAIT_L(0); PG8_BAR; PG8_MMA(1, 0, At, B0); PG8_MMA(1, 1, At, B1); PG8_BAR; PG8_SCHED;
.LBB0_861:
	s_add_u32 s30, s28, 0xfff80080
	s_addc_u32 s31, s29, -1
	s_add_i32 s51, 0, 0x10000
	s_cmp_eq_u32 s50, 28
	s_cselect_b32 s35, s17, s31
	s_cselect_b32 s34, s46, s30
	v_add_u32_e32 v145, s51, v142
	s_cselect_b32 s31, s15, s49
	s_cselect_b32 s30, s47, s48
	s_add_i32 s54, 0, 0x14000
	ds_read_b128 v[146:149], v145
	ds_read_b128 v[150:153], v145 offset:1024
	ds_read_b128 v[154:157], v145 offset:2048
	ds_read_b128 v[158:161], v145 offset:3072
	v_add_u32_e32 v145, s54, v142
	ds_read_b128 v[162:165], v145
	ds_read_b128 v[166:169], v145 offset:1024
	ds_read_b128 v[178:181], v145 offset:2048
	ds_read_b128 v[182:185], v145 offset:3072
	v_lshl_add_u64 v[172:173], s[28:29], 0, v[138:139]
	s_add_i32 m0, s25, 0xc000
	ds_read_b128 v[186:189], v144
	global_load_lds_dwordx4 v[172:173], off
	ds_read_b128 v[190:193], v144 offset:1024
	v_lshl_add_u64 v[172:173], s[28:29], 0, v[136:137]
	s_add_i32 m0, s25, 0xe000
	s_nop 0
	global_load_lds_dwordx4 v[172:173], off
	ds_read_b128 v[194:197], v144 offset:2048
	ds_read_b128 v[198:201], v144 offset:3072
	ds_read_b128 v[212:215], v144 offset:4096
	ds_read_b128 v[216:219], v144 offset:5120
	ds_read_b128 v[220:223], v144 offset:6144
	ds_read_b128 v[224:227], v144 offset:7168
	s_waitcnt vmcnt(8)
	s_waitcnt lgkmcnt(0)
	s_barrier
	s_setprio 1
	s_waitcnt lgkmcnt(0)
	v_mfma_f32_16x16x32_bf16 v[126:129], v[146:149], v[186:189], v[126:129]
	v_mfma_f32_16x16x32_bf16 v[122:125], v[154:157], v[186:189], v[122:125]
	v_mfma_f32_16x16x32_bf16 v[118:121], v[146:149], v[194:197], v[118:121]
	v_mfma_f32_16x16x32_bf16 v[110:113], v[154:157], v[194:197], v[110:113]
	v_mfma_f32_16x16x32_bf16 v[102:105], v[146:149], v[212:215], v[102:105]
	v_mfma_f32_16x16x32_bf16 v[94:97], v[154:157], v[212:215], v[94:97]
	v_mfma_f32_16x16x32_bf16 v[86:89], v[146:149], v[220:223], v[86:89]
	v_mfma_f32_16x16x32_bf16 v[78:81], v[154:157], v[220:223], v[78:81]
	v_mfma_f32_16x16x32_bf16 v[126:129], v[150:153], v[190:193], v[126:129]
	v_mfma_f32_16x16x32_bf16 v[122:125], v[158:161], v[190:193], v[122:125]
	v_mfma_f32_16x16x32_bf16 v[118:121], v[150:153], v[198:201], v[118:121]
	v_mfma_f32_16x16x32_bf16 v[110:113], v[158:161], v[198:201], v[110:113]
	v_mfma_f32_16x16x32_bf16 v[102:105], v[150:153], v[216:219], v[102:105]
	v_mfma_f32_16x16x32_bf16 v[94:97], v[158:161], v[216:219], v[94:97]
	v_mfma_f32_16x16x32_bf16 v[86:89], v[150:153], v[224:227], v[86:89]
	v_mfma_f32_16x16x32_bf16 v[78:81], v[158:161], v[224:227], v[78:81]
	s_setprio 0
	s_setprio 1
	v_mfma_f32_16x16x32_bf16 v[114:117], v[162:165], v[186:189], v[114:117]
	v_mfma_f32_16x16x32_bf16 v[106:109], v[178:181], v[186:189], v[106:109]
	v_mfma_f32_16x16x32_bf16 v[98:101], v[162:165], v[194:197], v[98:101]
	v_mfma_f32_16x16x32_bf16 v[90:93], v[178:181], v[194:197], v[90:93]
	v_mfma_f32_16x16x32_bf16 v[82:85], v[162:165], v[212:215], v[82:85]
	v_mfma_f32_16x16x32_bf16 v[74:77], v[178:181], v[212:215], v[74:77]
	v_mfma_f32_16x16x32_bf16 v[70:73], v[162:165], v[220:223], v[70:73]
	v_mfma_f32_16x16x32_bf16 v[66:69], v[178:181], v[220:223], v[66:69]
	v_mfma_f32_16x16x32_bf16 v[114:117], v[166:169], v[190:193], v[114:117]
	v_mfma_f32_16x16x32_bf16 v[106:109], v[182:185], v[190:193], v[106:109]
	v_mfma_f32_16x16x32_bf16 v[98:101], v[166:169], v[198:201], v[98:101]
	v_mfma_f32_16x16x32_bf16 v[90:93], v[182:185], v[198:201], v[90:93]
	v_mfma_f32_16x16x32_bf16 v[82:85], v[166:169], v[216:219], v[82:85]
	v_mfma_f32_16x16x32_bf16 v[74:77], v[182:185], v[216:219], v[74:77]
	v_mfma_f32_16x16x32_bf16 v[70:73], v[166:169], v[224:227], v[70:73]
	v_mfma_f32_16x16x32_bf16 v[66:69], v[182:185], v[224:227], v[66:69]
	s_setprio 0
	s_barrier
	s_add_i32 s51, s51, s40
	v_lshl_add_u64 v[172:173], s[30:31], 0, v[0:1]
	s_mov_b32 m0, s51
	ds_read_b128 v[186:189], v144 offset:16384
	global_load_lds_dwordx4 v[172:173], off
	ds_read_b128 v[190:193], v144 offset:17408
	s_add_i32 m0, s51, 0x2000
	s_add_u32 s52, s30, 0x8000
	v_lshl_add_u64 v[174:175], s[30:31], 0, v[134:135]
	s_addc_u32 s53, s31, 0
	s_add_i32 s51, s54, s40
	global_load_lds_dwordx4 v[174:175], off
	ds_read_b128 v[194:197], v144 offset:18432
	v_lshl_add_u64 v[176:177], s[52:53], 0, v[0:1]
	s_mov_b32 m0, s51
	v_lshl_add_u64 v[228:229], s[34:35], 0, v[132:133]
	global_load_lds_dwordx4 v[176:177], off
	ds_read_b128 v[198:201], v144 offset:19456
	v_lshl_add_u64 v[176:177], s[52:53], 0, v[134:135]
	s_add_i32 m0, s51, 0x2000
	s_nop 0
	global_load_lds_dwordx4 v[176:177], off
	ds_read_b128 v[212:215], v144 offset:20480
	v_lshl_add_u64 v[176:177], s[34:35], 0, v[130:131]
	s_mov_b32 m0, s25
	s_nop 0
	global_load_lds_dwordx4 v[176:177], off
	ds_read_b128 v[216:219], v144 offset:21504
	s_mov_b32 m0, s27
	s_nop 0
	global_load_lds_dwordx4 v[228:229], off
	ds_read_b128 v[220:223], v144 offset:22528
	ds_read_b128 v[224:227], v144 offset:23552
	s_waitcnt vmcnt(8)
	s_waitcnt lgkmcnt(0)
	s_barrier
; #define PG8_STAGE(bufoff, gbase, voff) do { _Pragma("unroll") for (int _i = 0; _i < 2; ++_i) \
;         __builtin_amdgcn_global_load_lds((const unsigned*)((const char*)(gbase) + (voff)[_i]), (LAS unsigned*)(lds + (bufoff) + ldsw + _i * 8192), 16, 0, 0); } while (0)
; #define PG8_LDA(dst, b, h) do { _Pragma("unroll") for (int m = 0; m < 4; ++m) _Pragma("unroll") for (int k = 0; k < 2; ++k) dst[m][k] = *(const LAS bf16x8*)(lds + PG8_SA(b, h) + aoff + m * 2048 + k * 1024); } while (0)
; #define PG8_LDB(dst, b, h) do { _Pragma("unroll") for (int n = 0; n < 2; ++n) _Pragma("unroll") for (int k = 0; k < 2; ++k) dst[n][k] = *(const LAS bf16x8*)(lds + PG8_SB(b, h) + boff + n * 2048 + k * 1024); } while (0)
; #define PG8_MMA(ai, bj, At, Bt) do { __builtin_amdgcn_s_setprio(1); _Pragma("unroll") for (int m = 0; m < 4; ++m) _Pragma("unroll") for (int n = 0; n < 2; ++n) _Pragma("unroll") for (int k = 0; k < 2; ++k) \
;         acc[ai][bj][m][n] = __builtin_amdgcn_mfma_f32_16x16x32_bf16(Bt[n][k], At[m][k], acc[ai][bj][m][n], 0, 0, 0); __builtin_amdgcn_s_setprio(0); } while (0)
; #define PG8_WAIT_V(n) asm volatile("s_waitcnt vmcnt(" #n ")" ::: "memory")
; #define PG8_WAIT_L(n) asm volatile("s_waitcnt lgkmcnt(" #n ")" ::: "memory")
; #define PG8_BAR __builtin_amdgcn_s_barrier()
; #define PG8_SCHED __builtin_amdgcn_sched_barrier(0)
; template <class Epi>
; __device__ __forceinline__ void gemm_phase(LAS unsigned char* lds, const Gemm g, const StaticOrder& S, const Epi& E, const int tid) {
;     ...
;             PG8_WAIT_V(8); PG8_WAIT_L(0); PG8_BAR; PG8_MMA(1, 0, At, B0); PG8_MMA(1, 1, At, B1); PG8_BAR; PG8_SCHED;
;             PG8_LDB(B0, 1, 0); PG8_LDB(B1, 1, 1); PG8_SCHED; PG8_LDA(At, 1, 0); PG8_STAGE(PG8_SA(0, 1), a2 + hstep, voffA);
;             PG8_WAIT_V(8); PG8_WAIT_L(0); PG8_BAR; PG8_MMA(0, 0, At, B0); PG8_MMA(0, 1, At, B1); PG8_BAR; PG8_SCHED;
	s_setprio 1
	s_waitcnt lgkmcnt(0)
	v_mfma_f32_16x16x32_bf16 v[62:65], v[146:149], v[186:189], v[62:65]
	v_mfma_f32_16x16x32_bf16 v[58:61], v[154:157], v[186:189], v[58:61]
	v_mfma_f32_16x16x32_bf16 v[54:57], v[146:149], v[194:197], v[54:57]
	v_mfma_f32_16x16x32_bf16 v[46:49], v[154:157], v[194:197], v[46:49]
	v_mfma_f32_16x16x32_bf16 v[38:41], v[146:149], v[212:215], v[38:41]
	v_mfma_f32_16x16x32_bf16 v[30:33], v[154:157], v[212:215], v[30:33]
	v_mfma_f32_16x16x32_bf16 v[22:25], v[146:149], v[220:223], v[22:25]
	v_mfma_f32_16x16x32_bf16 v[14:17], v[154:157], v[220:223], v[14:17]
	v_mfma_f32_16x16x32_bf16 v[62:65], v[150:153], v[190:193], v[62:65]
	v_mfma_f32_16x16x32_bf16 v[58:61], v[158:161], v[190:193], v[58:61]
	v_mfma_f32_16x16x32_bf16 v[54:57], v[150:153], v[198:201], v[54:57]
	v_mfma_f32_16x16x32_bf16 v[46:49], v[158:161], v[198:201], v[46:49]
	v_mfma_f32_16x16x32_bf16 v[38:41], v[150:153], v[216:219], v[38:41]
	v_mfma_f32_16x16x32_bf16 v[30:33], v[158:161], v[216:219], v[30:33]
	v_mfma_f32_16x16x32_bf16 v[22:25], v[150:153], v[224:227], v[22:25]
	v_mfma_f32_16x16x32_bf16 v[14:17], v[158:161], v[224:227], v[14:17]
	s_setprio 0
	s_setprio 1
	v_mfma_f32_16x16x32_bf16 v[50:53], v[162:165], v[186:189], v[50:53]
	v_mfma_f32_16x16x32_bf16 v[42:45], v[178:181], v[186:189], v[42:45]
	v_mfma_f32_16x16x32_bf16 v[34:37], v[162:165], v[194:197], v[34:37]
	v_mfma_f32_16x16x32_bf16 v[26:29], v[178:181], v[194:197], v[26:29]
	v_mfma_f32_16x16x32_bf16 v[18:21], v[162:165], v[212:215], v[18:21]
	v_mfma_f32_16x16x32_bf16 v[10:13], v[178:181], v[212:215], v[10:13]
	v_mfma_f32_16x16x32_bf16 v[6:9], v[162:165], v[220:223], v[6:9]
	v_mfma_f32_16x16x32_bf16 v[2:5], v[178:181], v[220:223], v[2:5]
	v_mfma_f32_16x16x32_bf16 v[50:53], v[166:169], v[190:193], v[50:53]
	v_mfma_f32_16x16x32_bf16 v[42:45], v[182:185], v[190:193], v[42:45]
	v_mfma_f32_16x16x32_bf16 v[34:37], v[166:169], v[198:201], v[34:37]
	v_mfma_f32_16x16x32_bf16 v[26:29], v[182:185], v[198:201], v[26:29]
	v_mfma_f32_16x16x32_bf16 v[18:21], v[166:169], v[216:219], v[18:21]
	v_mfma_f32_16x16x32_bf16 v[10:13], v[182:185], v[216:219], v[10:13]
	v_mfma_f32_16x16x32_bf16 v[6:9], v[166:169], v[224:227], v[6:9]
	v_mfma_f32_16x16x32_bf16 v[2:5], v[182:185], v[224:227], v[2:5]
	s_setprio 0
	s_barrier
	s_add_i32 s51, 0, 0x18000
	v_add_u32_e32 v145, s51, v142
	s_add_i32 s52, 0, 0x1c000
	ds_read_b128 v[146:149], v145
	ds_read_b128 v[150:153], v145 offset:1024
	ds_read_b128 v[154:157], v145 offset:2048
	ds_read_b128 v[158:161], v145 offset:3072
	v_add_u32_e32 v145, s52, v142
	ds_read_b128 v[162:165], v145
	ds_read_b128 v[166:169], v145 offset:1024
	ds_read_b128 v[178:181], v145 offset:2048
	ds_read_b128 v[182:185], v145 offset:3072
	s_add_u32 s34, s34, 0x80000
	s_addc_u32 s35, s35, 0
	s_mov_b32 m0, s41
	v_lshl_add_u64 v[230:231], s[34:35], 0, v[130:131]
	ds_read_b128 v[186:189], v144 offset:32768
	global_load_lds_dwordx4 v[230:231], off
	ds_read_b128 v[190:193], v144 offset:33792
	v_lshl_add_u64 v[230:231], s[34:35], 0, v[132:133]
	s_mov_b32 m0, s42
	s_nop 0
	global_load_lds_dwordx4 v[230:231], off
	ds_read_b128 v[194:197], v144 offset:34816
	ds_read_b128 v[198:201], v144 offset:35840
	ds_read_b128 v[212:215], v144 offset:36864
	ds_read_b128 v[216:219], v144 offset:37888
	ds_read_b128 v[220:223], v144 offset:38912
	ds_read_b128 v[224:227], v144 offset:39936
	s_waitcnt vmcnt(8)
	s_waitcnt lgkmcnt(0)
	s_barrier
	s_setprio 1
	s_waitcnt lgkmcnt(0)
	v_mfma_f32_16x16x32_bf16 v[126:129], v[146:149], v[186:189], v[126:129]
	v_mfma_f32_16x16x32_bf16 v[122:125], v[154:157], v[186:189], v[122:125]
	v_mfma_f32_16x16x32_bf16 v[118:121], v[146:149], v[194:197], v[118:121]
	v_mfma_f32_16x16x32_bf16 v[110:113], v[154:157], v[194:197], v[110:113]
	v_mfma_f32_16x16x32_bf16 v[102:105], v[146:149], v[212:215], v[102:105]
	v_mfma_f32_16x16x32_bf16 v[94:97], v[154:157], v[212:215], v[94:97]
	v_mfma_f32_16x16x32_bf16 v[86:89], v[146:149], v[220:223], v[86:89]
	v_mfma_f32_16x16x32_bf16 v[78:81], v[154:157], v[220:223], v[78:81]
	v_mfma_f32_16x16x32_bf16 v[126:129], v[150:153], v[190:193], v[126:129]
	v_mfma_f32_16x16x32_bf16 v[122:125], v[158:161], v[190:193], v[122:125]
	v_mfma_f32_16x16x32_bf16 v[118:121], v[150:153], v[198:201], v[118:121]
	v_mfma_f32_16x16x32_bf16 v[110:113], v[158:161], v[198:201], v[110:113]
	v_mfma_f32_16x16x32_bf16 v[102:105], v[150:153], v[216:219], v[102:105]
	v_mfma_f32_16x16x32_bf16 v[94:97], v[158:161], v[216:219], v[94:97]
	v_mfma_f32_16x16x32_bf16 v[86:89], v[150:153], v[224:227], v[86:89]
	v_mfma_f32_16x16x32_bf16 v[78:81], v[158:161], v[224:227], v[78:81]
	s_setprio 0
	s_setprio 1
	v_mfma_f32_16x16x32_bf16 v[114:117], v[162:165], v[186:189], v[114:117]
	v_mfma_f32_16x16x32_bf16 v[106:109], v[178:181], v[186:189], v[106:109]
	v_mfma_f32_16x16x32_bf16 v[98:101], v[162:165], v[194:197], v[98:101]
	v_mfma_f32_16x16x32_bf16 v[90:93], v[178:181], v[194:197], v[90:93]
	v_mfma_f32_16x16x32_bf16 v[82:85], v[162:165], v[212:215], v[82:85]
	v_mfma_f32_16x16x32_bf16 v[74:77], v[178:181], v[212:215], v[74:77]
	v_mfma_f32_16x16x32_bf16 v[70:73], v[162:165], v[220:223], v[70:73]
	v_mfma_f32_16x16x32_bf16 v[66:69], v[178:181], v[220:223], v[66:69]
	v_mfma_f32_16x16x32_bf16 v[114:117], v[166:169], v[190:193], v[114:117]
	v_mfma_f32_16x16x32_bf16 v[106:109], v[182:185], v[190:193], v[106:109]
	v_mfma_f32_16x16x32_bf16 v[98:101], v[166:169], v[198:201], v[98:101]
	v_mfma_f32_16x16x32_bf16 v[90:93], v[182:185], v[198:201], v[90:93]
	v_mfma_f32_16x16x32_bf16 v[82:85], v[166:169], v[216:219], v[82:85]
	v_mfma_f32_16x16x32_bf16 v[74:77], v[182:185], v[216:219], v[74:77]
	v_mfma_f32_16x16x32_bf16 v[70:73], v[166:169], v[224:227], v[70:73]
	v_mfma_f32_16x16x32_bf16 v[66:69], v[182:185], v[224:227], v[66:69]
	s_setprio 0
	s_barrier
; #define PG8_STAGE(bufoff, gbase, voff) do { _Pragma("unroll") for (int _i = 0; _i < 2; ++_i) \
;         __builtin_amdgcn_global_load_lds((const unsigned*)((const char*)(gbase) + (voff)[_i]), (LAS unsigned*)(lds + (bufoff) + ldsw + _i * 8192), 16, 0, 0); } while (0)
; #define PG8_LDA(dst, b, h) do { _Pragma("unroll") for (int m = 0; m < 4; ++m) _Pragma("unroll") for (int k = 0; k < 2; ++k) dst[m][k] = *(const LAS bf16x8*)(lds + PG8_SA(b, h) + aoff + m * 2048 + k * 1024); } while (0)
; #define PG8_MMA(ai, bj, At, Bt) do { __builtin_amdgcn_s_setprio(1); _Pragma("unroll") for (int m = 0; m < 4; ++m) _Pragma("unroll") for (int n = 0; n < 2; ++n) _Pragma("unroll") for (int k = 0; k < 2; ++k) \
;         acc[ai][bj][m][n] = __builtin_amdgcn_mfma_f32_16x16x32_bf16(Bt[n][k], At[m][k], acc[ai][bj][m][n], 0, 0, 0); __builtin_amdgcn_s_setprio(0); } while (0)
; #define PG8_WAIT_V(n) asm volatile("s_waitcnt vmcnt(" #n ")" ::: "memory")
; #define PG8_WAIT_L(n) asm volatile("s_waitcnt lgkmcnt(" #n ")" ::: "memory")
; #define PG8_BAR __builtin_amdgcn_s_barrier()
; #define PG8_SCHED __builtin_amdgcn_sched_barrier(0)
; template <class Epi>
; __device__ __forceinline__ void gemm_phase(LAS unsigned char* lds, const Gemm g, const StaticOrder& S, const Epi& E, const int tid) {
;     ...
;             PG8_LDA(At, 1, 1); PG8_STAGE(PG8_SB(1, 0), b3, voffB); PG8_STAGE(PG8_SB(1, 1), b3 + bhs, voffB); PG8_STAGE(PG8_SA(1, 0), a3, voffA);
;             PG8_WAIT_V(8); PG8_WAIT_L(0); PG8_BAR; PG8_MMA(1, 0, At, B0); PG8_MMA(1, 1, At, B1); PG8_BAR; PG8_SCHED;
;     ...
;         if (ALIGN_EPI) { if (wr == 0) PG8_BAR; }
	s_add_i32 s34, s51, s40
	v_lshl_add_u64 v[172:173], v[172:173], 0, s[70:71]
	s_mov_b32 m0, s34
	ds_read_b128 v[186:189], v144 offset:49152
	global_load_lds_dwordx4 v[172:173], off
	ds_read_b128 v[190:193], v144 offset:50176
	s_add_i32 m0, s34, 0x2000
	s_add_u32 s30, s30, 0x8080
	v_lshl_add_u64 v[172:173], v[174:175], 0, s[70:71]
	s_addc_u32 s31, s31, 0
	s_add_i32 s34, s52, s40
	global_load_lds_dwordx4 v[172:173], off
	ds_read_b128 v[194:197], v144 offset:51200
	v_lshl_add_u64 v[172:173], s[30:31], 0, v[0:1]
	s_mov_b32 m0, s34
	s_nop 0
	global_load_lds_dwordx4 v[172:173], off
	ds_read_b128 v[198:201], v144 offset:52224
	v_lshl_add_u64 v[172:173], s[30:31], 0, v[134:135]
	s_add_i32 m0, s34, 0x2000
	s_nop 0
	global_load_lds_dwordx4 v[172:173], off
	ds_read_b128 v[212:215], v144 offset:53248
	v_lshl_add_u64 v[172:173], v[176:177], 0, s[70:71]
	s_mov_b32 m0, s43
	s_nop 0
	global_load_lds_dwordx4 v[172:173], off
	ds_read_b128 v[216:219], v144 offset:54272
	v_lshl_add_u64 v[172:173], v[228:229], 0, s[70:71]
	s_mov_b32 m0, s44
	s_nop 0
	global_load_lds_dwordx4 v[172:173], off
	ds_read_b128 v[220:223], v144 offset:55296
	ds_read_b128 v[224:227], v144 offset:56320
	s_waitcnt vmcnt(8)
	s_waitcnt lgkmcnt(0)
	s_barrier
	s_setprio 1
	s_waitcnt lgkmcnt(0)
	v_mfma_f32_16x16x32_bf16 v[62:65], v[146:149], v[186:189], v[62:65]
	v_mfma_f32_16x16x32_bf16 v[58:61], v[154:157], v[186:189], v[58:61]
	v_mfma_f32_16x16x32_bf16 v[54:57], v[146:149], v[194:197], v[54:57]
	v_mfma_f32_16x16x32_bf16 v[46:49], v[154:157], v[194:197], v[46:49]
	v_mfma_f32_16x16x32_bf16 v[38:41], v[146:149], v[212:215], v[38:41]
	v_mfma_f32_16x16x32_bf16 v[30:33], v[154:157], v[212:215], v[30:33]
	v_mfma_f32_16x16x32_bf16 v[22:25], v[146:149], v[220:223], v[22:25]
	v_mfma_f32_16x16x32_bf16 v[14:17], v[154:157], v[220:223], v[14:17]
	v_mfma_f32_16x16x32_bf16 v[62:65], v[150:153], v[190:193], v[62:65]
	v_mfma_f32_16x16x32_bf16 v[58:61], v[158:161], v[190:193], v[58:61]
	v_mfma_f32_16x16x32_bf16 v[54:57], v[150:153], v[198:201], v[54:57]
	v_mfma_f32_16x16x32_bf16 v[46:49], v[158:161], v[198:201], v[46:49]
	v_mfma_f32_16x16x32_bf16 v[38:41], v[150:153], v[216:219], v[38:41]
	v_mfma_f32_16x16x32_bf16 v[30:33], v[158:161], v[216:219], v[30:33]
	v_mfma_f32_16x16x32_bf16 v[22:25], v[150:153], v[224:227], v[22:25]
	v_mfma_f32_16x16x32_bf16 v[14:17], v[158:161], v[224:227], v[14:17]
	s_setprio 0
	s_setprio 1
	v_mfma_f32_16x16x32_bf16 v[50:53], v[162:165], v[186:189], v[50:53]
	v_mfma_f32_16x16x32_bf16 v[42:45], v[178:181], v[186:189], v[42:45]
	v_mfma_f32_16x16x32_bf16 v[34:37], v[162:165], v[194:197], v[34:37]
	v_mfma_f32_16x16x32_bf16 v[26:29], v[178:181], v[194:197], v[26:29]
	v_mfma_f32_16x16x32_bf16 v[18:21], v[162:165], v[212:215], v[18:21]
	v_mfma_f32_16x16x32_bf16 v[10:13], v[178:181], v[212:215], v[10:13]
	v_mfma_f32_16x16x32_bf16 v[6:9], v[162:165], v[220:223], v[6:9]
	v_mfma_f32_16x16x32_bf16 v[2:5], v[178:181], v[220:223], v[2:5]
	v_mfma_f32_16x16x32_bf16 v[50:53], v[166:169], v[190:193], v[50:53]
	v_mfma_f32_16x16x32_bf16 v[42:45], v[182:185], v[190:193], v[42:45]
	v_mfma_f32_16x16x32_bf16 v[34:37], v[166:169], v[198:201], v[34:37]
	v_mfma_f32_16x16x32_bf16 v[26:29], v[182:185], v[198:201], v[26:29]
	v_mfma_f32_16x16x32_bf16 v[18:21], v[166:169], v[216:219], v[18:21]
	v_mfma_f32_16x16x32_bf16 v[10:13], v[182:185], v[216:219], v[10:13]
	v_mfma_f32_16x16x32_bf16 v[6:9], v[166:169], v[224:227], v[6:9]
	v_mfma_f32_16x16x32_bf16 v[2:5], v[182:185], v[224:227], v[2:5]
	s_setprio 0
	s_barrier
	s_add_i32 s50, s50, 2
	s_add_u32 s48, s48, 0x100
	s_addc_u32 s49, s49, 0
	s_add_u32 s28, s28, 0x100
	s_addc_u32 s29, s29, 0
	s_cmp_gt_u32 s50, 29
	s_cbranch_scc0 .LBB0_861
	s_and_b64 vcc, exec, s[12:13]
	s_cbranch_vccz .LBB0_864
	s_barrier
